# stack on the tail-split base: scalar-base LDS-DMA form, projection prologue warm-up, packed-f32 SwiGLU epilogue (layer 1), mid-block priority flips removed
# baseline (speedup 1.0000x reference)
.LBB0_289:
	ds_read_b128 v[170:173], v167
	ds_read_b128 v[174:177], v167 offset:1024
	ds_read_b128 v[178:181], v167 offset:2048
	ds_read_b128 v[182:185], v167 offset:3072
	ds_read_b128 v[186:189], v168
	ds_read_b128 v[190:193], v168 offset:1024
	ds_read_b128 v[194:197], v168 offset:2048
	ds_read_b128 v[198:201], v168 offset:3072
	s_add_u32 s26, s24, 0xfffc0080
	s_addc_u32 s27, s25, -1
	s_cmp_eq_u32 s54, 12
	s_cselect_b32 s29, s13, s27
	s_cselect_b32 s28, s50, s26
	s_cselect_b32 s27, s15, s53
	s_cselect_b32 s26, s51, s52
	s_add_i32 m0, s21, 0xc000
	ds_read_b128 v[210:213], v169
	ds_read_b128 v[214:217], v169 offset:1024
	ds_read_b128 v[218:221], v169 offset:2048
	ds_read_b128 v[222:225], v169 offset:3072
	ds_read_b128 v[226:229], v169 offset:4096
	ds_read_b128 v[230:233], v169 offset:5120
	ds_read_b128 v[234:237], v169 offset:6144
	ds_read_b128 v[238:241], v169 offset:7168
	global_load_lds_dwordx4 v158, s[24:25]
	s_add_i32 m0, s21, 0xe000
	s_nop 0
	global_load_lds_dwordx4 v156, s[24:25]
	s_waitcnt vmcnt(8)
	s_waitcnt lgkmcnt(0)
	s_barrier
	s_setprio 1
	s_waitcnt lgkmcnt(0)
	v_mfma_f32_16x16x32_bf16 v[124:127], v[170:173], v[210:213], v[124:127]
	v_mfma_f32_16x16x32_bf16 v[116:119], v[178:181], v[210:213], v[116:119]
	v_mfma_f32_16x16x32_bf16 v[108:111], v[170:173], v[218:221], v[108:111]
	v_mfma_f32_16x16x32_bf16 v[100:103], v[178:181], v[218:221], v[100:103]
	v_mfma_f32_16x16x32_bf16 v[92:95], v[170:173], v[226:229], v[92:95]
	v_mfma_f32_16x16x32_bf16 v[84:87], v[178:181], v[226:229], v[84:87]
	v_mfma_f32_16x16x32_bf16 v[76:79], v[170:173], v[234:237], v[76:79]
	v_mfma_f32_16x16x32_bf16 v[68:71], v[178:181], v[234:237], v[68:71]
	v_mfma_f32_16x16x32_bf16 v[124:127], v[174:177], v[214:217], v[124:127]
	v_mfma_f32_16x16x32_bf16 v[116:119], v[182:185], v[214:217], v[116:119]
	v_mfma_f32_16x16x32_bf16 v[108:111], v[174:177], v[222:225], v[108:111]
	v_mfma_f32_16x16x32_bf16 v[100:103], v[182:185], v[222:225], v[100:103]
	v_mfma_f32_16x16x32_bf16 v[92:95], v[174:177], v[230:233], v[92:95]
	v_mfma_f32_16x16x32_bf16 v[84:87], v[182:185], v[230:233], v[84:87]
	v_mfma_f32_16x16x32_bf16 v[76:79], v[174:177], v[238:241], v[76:79]
	v_mfma_f32_16x16x32_bf16 v[68:71], v[182:185], v[238:241], v[68:71]
	v_mfma_f32_16x16x32_bf16 v[120:123], v[186:189], v[210:213], v[120:123]
	v_mfma_f32_16x16x32_bf16 v[112:115], v[194:197], v[210:213], v[112:115]
	v_mfma_f32_16x16x32_bf16 v[104:107], v[186:189], v[218:221], v[104:107]
	v_mfma_f32_16x16x32_bf16 v[96:99], v[194:197], v[218:221], v[96:99]
	v_mfma_f32_16x16x32_bf16 v[88:91], v[186:189], v[226:229], v[88:91]
	v_mfma_f32_16x16x32_bf16 v[80:83], v[194:197], v[226:229], v[80:83]
	v_mfma_f32_16x16x32_bf16 v[72:75], v[186:189], v[234:237], v[72:75]
	v_mfma_f32_16x16x32_bf16 v[64:67], v[194:197], v[234:237], v[64:67]
	v_mfma_f32_16x16x32_bf16 v[120:123], v[190:193], v[214:217], v[120:123]
	v_mfma_f32_16x16x32_bf16 v[112:115], v[198:201], v[214:217], v[112:115]
	v_mfma_f32_16x16x32_bf16 v[104:107], v[190:193], v[222:225], v[104:107]
	v_mfma_f32_16x16x32_bf16 v[96:99], v[198:201], v[222:225], v[96:99]
	v_mfma_f32_16x16x32_bf16 v[88:91], v[190:193], v[230:233], v[88:91]
	v_mfma_f32_16x16x32_bf16 v[80:83], v[198:201], v[230:233], v[80:83]
	v_mfma_f32_16x16x32_bf16 v[72:75], v[190:193], v[238:241], v[72:75]
	v_mfma_f32_16x16x32_bf16 v[64:67], v[198:201], v[238:241], v[64:67]
	s_setprio 0
	s_barrier
	s_add_i32 s55, s48, s38
	s_mov_b32 m0, s55
	ds_read_b128 v[210:213], v169 offset:16384
	ds_read_b128 v[214:217], v169 offset:17408
	ds_read_b128 v[218:221], v169 offset:18432
	ds_read_b128 v[222:225], v169 offset:19456
	ds_read_b128 v[226:229], v169 offset:20480
	ds_read_b128 v[230:233], v169 offset:21504
	ds_read_b128 v[234:237], v169 offset:22528
	ds_read_b128 v[238:241], v169 offset:23552
	global_load_lds_dwordx4 v134, s[26:27]
	s_add_i32 m0, s55, 0x2000
	s_add_u32 s56, s26, 0x4000
	s_addc_u32 s57, s27, 0
	s_add_i32 s55, s49, s38
	global_load_lds_dwordx4 v130, s[26:27]
	s_mov_b32 m0, s55
	v_lshl_add_u64 v[242:243], s[28:29], 0, v[132:133]
	global_load_lds_dwordx4 v134, s[56:57]
	s_add_i32 m0, s55, 0x2000
	s_nop 0
	global_load_lds_dwordx4 v130, s[56:57]
	v_lshl_add_u64 v[164:165], s[28:29], 0, v[136:137]
	s_mov_b32 m0, s21
	s_nop 0
	global_load_lds_dwordx4 v[164:165], off
	s_mov_b32 m0, s23
	s_nop 0
	global_load_lds_dwordx4 v[242:243], off
	s_waitcnt vmcnt(8)
	s_waitcnt lgkmcnt(0)
	s_barrier
	s_setprio 1
	s_waitcnt lgkmcnt(0)
	v_mfma_f32_16x16x32_bf16 v[60:63], v[170:173], v[210:213], v[60:63]
	v_mfma_f32_16x16x32_bf16 v[52:55], v[178:181], v[210:213], v[52:55]
	v_mfma_f32_16x16x32_bf16 v[44:47], v[170:173], v[218:221], v[44:47]
	v_mfma_f32_16x16x32_bf16 v[36:39], v[178:181], v[218:221], v[36:39]
	v_mfma_f32_16x16x32_bf16 v[28:31], v[170:173], v[226:229], v[28:31]
	v_mfma_f32_16x16x32_bf16 v[20:23], v[178:181], v[226:229], v[20:23]
	v_mfma_f32_16x16x32_bf16 v[12:15], v[170:173], v[234:237], v[12:15]
	v_mfma_f32_16x16x32_bf16 v[4:7], v[178:181], v[234:237], v[4:7]
	v_mfma_f32_16x16x32_bf16 v[60:63], v[174:177], v[214:217], v[60:63]
	v_mfma_f32_16x16x32_bf16 v[52:55], v[182:185], v[214:217], v[52:55]
	v_mfma_f32_16x16x32_bf16 v[44:47], v[174:177], v[222:225], v[44:47]
	v_mfma_f32_16x16x32_bf16 v[36:39], v[182:185], v[222:225], v[36:39]
	v_mfma_f32_16x16x32_bf16 v[28:31], v[174:177], v[230:233], v[28:31]
	v_mfma_f32_16x16x32_bf16 v[20:23], v[182:185], v[230:233], v[20:23]
	v_mfma_f32_16x16x32_bf16 v[12:15], v[174:177], v[238:241], v[12:15]
	v_mfma_f32_16x16x32_bf16 v[4:7], v[182:185], v[238:241], v[4:7]
	v_mfma_f32_16x16x32_bf16 v[56:59], v[186:189], v[210:213], v[56:59]
	v_mfma_f32_16x16x32_bf16 v[48:51], v[194:197], v[210:213], v[48:51]
	v_mfma_f32_16x16x32_bf16 v[40:43], v[186:189], v[218:221], v[40:43]
	v_mfma_f32_16x16x32_bf16 v[32:35], v[194:197], v[218:221], v[32:35]
	v_mfma_f32_16x16x32_bf16 v[24:27], v[186:189], v[226:229], v[24:27]
	v_mfma_f32_16x16x32_bf16 v[16:19], v[194:197], v[226:229], v[16:19]
	v_mfma_f32_16x16x32_bf16 v[8:11], v[186:189], v[234:237], v[8:11]
	v_mfma_f32_16x16x32_bf16 v[0:3], v[194:197], v[234:237], v[0:3]
	v_mfma_f32_16x16x32_bf16 v[56:59], v[190:193], v[214:217], v[56:59]
	v_mfma_f32_16x16x32_bf16 v[48:51], v[198:201], v[214:217], v[48:51]
	v_mfma_f32_16x16x32_bf16 v[40:43], v[190:193], v[222:225], v[40:43]
	v_mfma_f32_16x16x32_bf16 v[32:35], v[198:201], v[222:225], v[32:35]
	v_mfma_f32_16x16x32_bf16 v[24:27], v[190:193], v[230:233], v[24:27]
	v_mfma_f32_16x16x32_bf16 v[16:19], v[198:201], v[230:233], v[16:19]
	v_mfma_f32_16x16x32_bf16 v[8:11], v[190:193], v[238:241], v[8:11]
	v_mfma_f32_16x16x32_bf16 v[0:3], v[198:201], v[238:241], v[0:3]
	s_setprio 0
	s_barrier
	s_add_i32 s55, 0, 0x18000
	s_add_i32 s56, 0, 0x1c000
	v_add_u32_e32 v182, s55, v129
	v_add_u32_e32 v198, s56, v129
	ds_read_b128 v[170:173], v182
	ds_read_b128 v[174:177], v182 offset:1024
	ds_read_b128 v[178:181], v182 offset:2048
	ds_read_b128 v[182:185], v182 offset:3072
	ds_read_b128 v[186:189], v198
	ds_read_b128 v[190:193], v198 offset:1024
	ds_read_b128 v[194:197], v198 offset:2048
	ds_read_b128 v[198:201], v198 offset:3072
	s_add_u32 s28, s28, 0x40000
	s_addc_u32 s29, s29, 0
	s_mov_b32 m0, s41
	ds_read_b128 v[210:213], v169 offset:32768
	ds_read_b128 v[214:217], v169 offset:33792
	ds_read_b128 v[218:221], v169 offset:34816
	ds_read_b128 v[222:225], v169 offset:35840
	ds_read_b128 v[226:229], v169 offset:36864
	ds_read_b128 v[230:233], v169 offset:37888
	ds_read_b128 v[234:237], v169 offset:38912
	ds_read_b128 v[238:241], v169 offset:39936
	global_load_lds_dwordx4 v136, s[28:29]
	s_mov_b32 m0, s42
	s_nop 0
	global_load_lds_dwordx4 v132, s[28:29]
	s_waitcnt vmcnt(8)
	s_waitcnt lgkmcnt(0)
	s_barrier
	s_setprio 1
	s_waitcnt lgkmcnt(0)
	v_mfma_f32_16x16x32_bf16 v[124:127], v[170:173], v[210:213], v[124:127]
	v_mfma_f32_16x16x32_bf16 v[116:119], v[178:181], v[210:213], v[116:119]
	v_mfma_f32_16x16x32_bf16 v[108:111], v[170:173], v[218:221], v[108:111]
	v_mfma_f32_16x16x32_bf16 v[100:103], v[178:181], v[218:221], v[100:103]
	v_mfma_f32_16x16x32_bf16 v[92:95], v[170:173], v[226:229], v[92:95]
	v_mfma_f32_16x16x32_bf16 v[84:87], v[178:181], v[226:229], v[84:87]
	v_mfma_f32_16x16x32_bf16 v[76:79], v[170:173], v[234:237], v[76:79]
	v_mfma_f32_16x16x32_bf16 v[68:71], v[178:181], v[234:237], v[68:71]
	v_mfma_f32_16x16x32_bf16 v[124:127], v[174:177], v[214:217], v[124:127]
	v_mfma_f32_16x16x32_bf16 v[116:119], v[182:185], v[214:217], v[116:119]
	v_mfma_f32_16x16x32_bf16 v[108:111], v[174:177], v[222:225], v[108:111]
	v_mfma_f32_16x16x32_bf16 v[100:103], v[182:185], v[222:225], v[100:103]
	v_mfma_f32_16x16x32_bf16 v[92:95], v[174:177], v[230:233], v[92:95]
	v_mfma_f32_16x16x32_bf16 v[84:87], v[182:185], v[230:233], v[84:87]
	v_mfma_f32_16x16x32_bf16 v[76:79], v[174:177], v[238:241], v[76:79]
	v_mfma_f32_16x16x32_bf16 v[68:71], v[182:185], v[238:241], v[68:71]
	v_mfma_f32_16x16x32_bf16 v[120:123], v[186:189], v[210:213], v[120:123]
	v_mfma_f32_16x16x32_bf16 v[112:115], v[194:197], v[210:213], v[112:115]
	v_mfma_f32_16x16x32_bf16 v[104:107], v[186:189], v[218:221], v[104:107]
	v_mfma_f32_16x16x32_bf16 v[96:99], v[194:197], v[218:221], v[96:99]
	v_mfma_f32_16x16x32_bf16 v[88:91], v[186:189], v[226:229], v[88:91]
	v_mfma_f32_16x16x32_bf16 v[80:83], v[194:197], v[226:229], v[80:83]
	v_mfma_f32_16x16x32_bf16 v[72:75], v[186:189], v[234:237], v[72:75]
	v_mfma_f32_16x16x32_bf16 v[64:67], v[194:197], v[234:237], v[64:67]
	v_mfma_f32_16x16x32_bf16 v[120:123], v[190:193], v[214:217], v[120:123]
	v_mfma_f32_16x16x32_bf16 v[112:115], v[198:201], v[214:217], v[112:115]
	v_mfma_f32_16x16x32_bf16 v[104:107], v[190:193], v[222:225], v[104:107]
	v_mfma_f32_16x16x32_bf16 v[96:99], v[198:201], v[222:225], v[96:99]
	v_mfma_f32_16x16x32_bf16 v[88:91], v[190:193], v[230:233], v[88:91]
	v_mfma_f32_16x16x32_bf16 v[80:83], v[198:201], v[230:233], v[80:83]
	v_mfma_f32_16x16x32_bf16 v[72:75], v[190:193], v[238:241], v[72:75]
	v_mfma_f32_16x16x32_bf16 v[64:67], v[198:201], v[238:241], v[64:67]
	s_setprio 0
	s_barrier
	s_add_u32 s28, s26, 0x8000
	s_addc_u32 s29, s27, 0
	s_add_i32 s55, s55, s38
	s_mov_b32 m0, s55
	ds_read_b128 v[210:213], v169 offset:49152
	ds_read_b128 v[214:217], v169 offset:50176
	ds_read_b128 v[218:221], v169 offset:51200
	ds_read_b128 v[222:225], v169 offset:52224
	ds_read_b128 v[226:229], v169 offset:53248
	ds_read_b128 v[230:233], v169 offset:54272
	ds_read_b128 v[234:237], v169 offset:55296
	ds_read_b128 v[238:241], v169 offset:56320
	global_load_lds_dwordx4 v134, s[28:29]
	s_add_i32 m0, s55, 0x2000
	s_add_u32 s26, s26, 0xc000
	v_lshl_add_u64 v[244:245], s[28:29], 0, v[130:131]
	s_addc_u32 s27, s27, 0
	s_add_i32 s28, s56, s38
	global_load_lds_dwordx4 v[244:245], off
	s_mov_b32 m0, s28
	v_lshl_add_u64 v[164:165], v[164:165], 0, s[8:9]
	global_load_lds_dwordx4 v134, s[26:27]
	s_add_i32 m0, s28, 0x2000
	s_nop 0
	global_load_lds_dwordx4 v130, s[26:27]
	s_mov_b32 m0, s45
	s_nop 0
	global_load_lds_dwordx4 v[164:165], off
	v_lshl_add_u64 v[164:165], v[242:243], 0, s[8:9]
	s_mov_b32 m0, s46
	s_nop 0
	global_load_lds_dwordx4 v[164:165], off
	s_waitcnt vmcnt(8)
	s_waitcnt lgkmcnt(0)
	s_barrier
	s_setprio 1
	s_waitcnt lgkmcnt(0)
	v_mfma_f32_16x16x32_bf16 v[60:63], v[170:173], v[210:213], v[60:63]
	v_mfma_f32_16x16x32_bf16 v[52:55], v[178:181], v[210:213], v[52:55]
	v_mfma_f32_16x16x32_bf16 v[44:47], v[170:173], v[218:221], v[44:47]
	v_mfma_f32_16x16x32_bf16 v[36:39], v[178:181], v[218:221], v[36:39]
	v_mfma_f32_16x16x32_bf16 v[28:31], v[170:173], v[226:229], v[28:31]
	v_mfma_f32_16x16x32_bf16 v[20:23], v[178:181], v[226:229], v[20:23]
	v_mfma_f32_16x16x32_bf16 v[12:15], v[170:173], v[234:237], v[12:15]
	v_mfma_f32_16x16x32_bf16 v[4:7], v[178:181], v[234:237], v[4:7]
	v_mfma_f32_16x16x32_bf16 v[60:63], v[174:177], v[214:217], v[60:63]
	v_mfma_f32_16x16x32_bf16 v[52:55], v[182:185], v[214:217], v[52:55]
	v_mfma_f32_16x16x32_bf16 v[44:47], v[174:177], v[222:225], v[44:47]
	v_mfma_f32_16x16x32_bf16 v[36:39], v[182:185], v[222:225], v[36:39]
	v_mfma_f32_16x16x32_bf16 v[28:31], v[174:177], v[230:233], v[28:31]
	v_mfma_f32_16x16x32_bf16 v[20:23], v[182:185], v[230:233], v[20:23]
	v_mfma_f32_16x16x32_bf16 v[12:15], v[174:177], v[238:241], v[12:15]
	v_mfma_f32_16x16x32_bf16 v[4:7], v[182:185], v[238:241], v[4:7]
	v_mfma_f32_16x16x32_bf16 v[56:59], v[186:189], v[210:213], v[56:59]
	v_mfma_f32_16x16x32_bf16 v[48:51], v[194:197], v[210:213], v[48:51]
	v_mfma_f32_16x16x32_bf16 v[40:43], v[186:189], v[218:221], v[40:43]
	v_mfma_f32_16x16x32_bf16 v[32:35], v[194:197], v[218:221], v[32:35]
	v_mfma_f32_16x16x32_bf16 v[24:27], v[186:189], v[226:229], v[24:27]
	v_mfma_f32_16x16x32_bf16 v[16:19], v[194:197], v[226:229], v[16:19]
	v_mfma_f32_16x16x32_bf16 v[8:11], v[186:189], v[234:237], v[8:11]
	v_mfma_f32_16x16x32_bf16 v[0:3], v[194:197], v[234:237], v[0:3]
	v_mfma_f32_16x16x32_bf16 v[56:59], v[190:193], v[214:217], v[56:59]
	v_mfma_f32_16x16x32_bf16 v[48:51], v[198:201], v[214:217], v[48:51]
	v_mfma_f32_16x16x32_bf16 v[40:43], v[190:193], v[222:225], v[40:43]
	v_mfma_f32_16x16x32_bf16 v[32:35], v[198:201], v[222:225], v[32:35]
	v_mfma_f32_16x16x32_bf16 v[24:27], v[190:193], v[230:233], v[24:27]
	v_mfma_f32_16x16x32_bf16 v[16:19], v[198:201], v[230:233], v[16:19]
	v_mfma_f32_16x16x32_bf16 v[8:11], v[190:193], v[238:241], v[8:11]
	v_mfma_f32_16x16x32_bf16 v[0:3], v[198:201], v[238:241], v[0:3]
	s_setprio 0
	s_barrier
	s_add_i32 s54, s54, 2
	s_add_u32 s52, s52, 0x10000
	s_addc_u32 s53, s53, 0
	s_add_u32 s24, s24, 0x100
	s_addc_u32 s25, s25, 0
	s_cmp_gt_u32 s54, 13
	s_cbranch_scc0 .LBB0_289
	s_and_b64 vcc, exec, s[10:11]
	s_cbranch_vccz .LBB0_292
	s_barrier

.LBB0_408:
	v_add_u32_e32 v168, s71, v182
	v_add_u32_e32 v204, s72, v182
	ds_read_b128 v[156:159], v168
	ds_read_b128 v[160:163], v168 offset:1024
	ds_read_b128 v[164:167], v168 offset:2048
	ds_read_b128 v[168:171], v168 offset:3072
	ds_read_b128 v[172:175], v204
	ds_read_b128 v[176:179], v204 offset:1024
	ds_read_b128 v[212:215], v204 offset:2048
	ds_read_b128 v[216:219], v204 offset:3072
	s_add_u32 s40, s38, 0x4000
	s_addc_u32 s41, s39, 0
	s_cmp_eq_u32 s49, 40
	s_cselect_b32 s44, s0, s40
	s_cselect_b32 s45, s1, s41
	s_cselect_b32 s42, s36, s47
	s_cselect_b32 s43, s37, s48
	s_add_u32 s40, s44, 0x8000
	s_addc_u32 s41, s45, 0
	s_add_i32 m0, s58, 0xc000
	ds_read_b128 v[220:223], v199
	ds_read_b128 v[224:227], v199 offset:1024
	ds_read_b128 v[228:231], v199 offset:2048
	ds_read_b128 v[232:235], v199 offset:3072
	ds_read_b128 v[236:239], v199 offset:4096
	ds_read_b128 v[240:243], v199 offset:5120
	ds_read_b128 v[244:247], v199 offset:6144
	ds_read_b128 v[248:251], v199 offset:7168
	global_load_lds_dwordx4 v150, s[38:39]
	s_add_i32 m0, s58, 0xe000
	s_nop 0
	global_load_lds_dwordx4 v148, s[38:39]
	s_waitcnt vmcnt(8)
	s_waitcnt lgkmcnt(0)
	s_barrier
	s_setprio 1
	s_waitcnt lgkmcnt(0)
	v_mfma_f32_16x16x32_bf16 v[124:127], v[156:159], v[220:223], v[124:127]
	v_mfma_f32_16x16x32_bf16 v[120:123], v[164:167], v[220:223], v[120:123]
	v_mfma_f32_16x16x32_bf16 v[116:119], v[156:159], v[228:231], v[116:119]
	v_mfma_f32_16x16x32_bf16 v[108:111], v[164:167], v[228:231], v[108:111]
	v_mfma_f32_16x16x32_bf16 v[92:95], v[156:159], v[236:239], v[92:95]
	v_mfma_f32_16x16x32_bf16 v[88:91], v[164:167], v[236:239], v[88:91]
	v_mfma_f32_16x16x32_bf16 v[84:87], v[156:159], v[244:247], v[84:87]
	v_mfma_f32_16x16x32_bf16 v[76:79], v[164:167], v[244:247], v[76:79]
	v_mfma_f32_16x16x32_bf16 v[124:127], v[160:163], v[224:227], v[124:127]
	v_mfma_f32_16x16x32_bf16 v[120:123], v[168:171], v[224:227], v[120:123]
	v_mfma_f32_16x16x32_bf16 v[116:119], v[160:163], v[232:235], v[116:119]
	v_mfma_f32_16x16x32_bf16 v[108:111], v[168:171], v[232:235], v[108:111]
	v_mfma_f32_16x16x32_bf16 v[92:95], v[160:163], v[240:243], v[92:95]
	v_mfma_f32_16x16x32_bf16 v[88:91], v[168:171], v[240:243], v[88:91]
	v_mfma_f32_16x16x32_bf16 v[84:87], v[160:163], v[248:251], v[84:87]
	v_mfma_f32_16x16x32_bf16 v[76:79], v[168:171], v[248:251], v[76:79]
	v_mfma_f32_16x16x32_bf16 v[112:115], v[172:175], v[220:223], v[112:115]
	v_mfma_f32_16x16x32_bf16 v[104:107], v[212:215], v[220:223], v[104:107]
	v_mfma_f32_16x16x32_bf16 v[100:103], v[172:175], v[228:231], v[100:103]
	v_mfma_f32_16x16x32_bf16 v[96:99], v[212:215], v[228:231], v[96:99]
	v_mfma_f32_16x16x32_bf16 v[80:83], v[172:175], v[236:239], v[80:83]
	v_mfma_f32_16x16x32_bf16 v[72:75], v[212:215], v[236:239], v[72:75]
	v_mfma_f32_16x16x32_bf16 v[68:71], v[172:175], v[244:247], v[68:71]
	v_mfma_f32_16x16x32_bf16 v[64:67], v[212:215], v[244:247], v[64:67]
	v_mfma_f32_16x16x32_bf16 v[112:115], v[176:179], v[224:227], v[112:115]
	v_mfma_f32_16x16x32_bf16 v[104:107], v[216:219], v[224:227], v[104:107]
	v_mfma_f32_16x16x32_bf16 v[100:103], v[176:179], v[232:235], v[100:103]
	v_mfma_f32_16x16x32_bf16 v[96:99], v[216:219], v[232:235], v[96:99]
	v_mfma_f32_16x16x32_bf16 v[80:83], v[176:179], v[240:243], v[80:83]
	v_mfma_f32_16x16x32_bf16 v[72:75], v[216:219], v[240:243], v[72:75]
	v_mfma_f32_16x16x32_bf16 v[68:71], v[176:179], v[248:251], v[68:71]
	v_mfma_f32_16x16x32_bf16 v[64:67], v[216:219], v[248:251], v[64:67]
	s_setprio 0
	s_barrier
	s_add_i32 s50, s71, s57
	s_mov_b32 m0, s50
	ds_read_b128 v[220:223], v199 offset:16384
	ds_read_b128 v[224:227], v199 offset:17408
	ds_read_b128 v[228:231], v199 offset:18432
	ds_read_b128 v[232:235], v199 offset:19456
	ds_read_b128 v[236:239], v199 offset:20480
	ds_read_b128 v[240:243], v199 offset:21504
	ds_read_b128 v[244:247], v199 offset:22528
	ds_read_b128 v[248:251], v199 offset:23552
	global_load_lds_dwordx4 v128, s[42:43]
	s_add_i32 m0, s50, 0x2000
	s_add_u32 s50, s42, 0x4000
	s_addc_u32 s51, s43, 0
	s_add_i32 s52, s72, s57
	global_load_lds_dwordx4 v130, s[42:43]
	s_mov_b32 m0, s52
	s_nop 0
	global_load_lds_dwordx4 v128, s[50:51]
	s_add_i32 m0, s52, 0x2000
	s_nop 0
	global_load_lds_dwordx4 v130, s[50:51]
	s_mov_b32 m0, s58
	s_nop 0
	global_load_lds_dwordx4 v128, s[44:45]
	s_mov_b32 m0, s59
	s_nop 0
	global_load_lds_dwordx4 v130, s[44:45]
	s_waitcnt vmcnt(8)
	s_waitcnt lgkmcnt(0)
	s_barrier
	s_setprio 1
	s_waitcnt lgkmcnt(0)
	v_mfma_f32_16x16x32_bf16 v[60:63], v[156:159], v[220:223], v[60:63]
	v_mfma_f32_16x16x32_bf16 v[56:59], v[164:167], v[220:223], v[56:59]
	v_mfma_f32_16x16x32_bf16 v[52:55], v[156:159], v[228:231], v[52:55]
	v_mfma_f32_16x16x32_bf16 v[44:47], v[164:167], v[228:231], v[44:47]
	v_mfma_f32_16x16x32_bf16 v[32:35], v[156:159], v[236:239], v[32:35]
	v_mfma_f32_16x16x32_bf16 v[24:27], v[164:167], v[236:239], v[24:27]
	v_mfma_f32_16x16x32_bf16 v[20:23], v[156:159], v[244:247], v[20:23]
	v_mfma_f32_16x16x32_bf16 v[12:15], v[164:167], v[244:247], v[12:15]
	v_mfma_f32_16x16x32_bf16 v[60:63], v[160:163], v[224:227], v[60:63]
	v_mfma_f32_16x16x32_bf16 v[56:59], v[168:171], v[224:227], v[56:59]
	v_mfma_f32_16x16x32_bf16 v[52:55], v[160:163], v[232:235], v[52:55]
	v_mfma_f32_16x16x32_bf16 v[44:47], v[168:171], v[232:235], v[44:47]
	v_mfma_f32_16x16x32_bf16 v[32:35], v[160:163], v[240:243], v[32:35]
	v_mfma_f32_16x16x32_bf16 v[24:27], v[168:171], v[240:243], v[24:27]
	v_mfma_f32_16x16x32_bf16 v[20:23], v[160:163], v[248:251], v[20:23]
	v_mfma_f32_16x16x32_bf16 v[12:15], v[168:171], v[248:251], v[12:15]
	v_mfma_f32_16x16x32_bf16 v[48:51], v[172:175], v[220:223], v[48:51]
	v_mfma_f32_16x16x32_bf16 v[40:43], v[212:215], v[220:223], v[40:43]
	v_mfma_f32_16x16x32_bf16 v[36:39], v[172:175], v[228:231], v[36:39]
	v_mfma_f32_16x16x32_bf16 v[28:31], v[212:215], v[228:231], v[28:31]
	v_mfma_f32_16x16x32_bf16 v[16:19], v[172:175], v[236:239], v[16:19]
	v_mfma_f32_16x16x32_bf16 v[8:11], v[212:215], v[236:239], v[8:11]
	v_mfma_f32_16x16x32_bf16 v[4:7], v[172:175], v[244:247], v[4:7]
	v_mfma_f32_16x16x32_bf16 v[0:3], v[212:215], v[244:247], v[0:3]
	v_mfma_f32_16x16x32_bf16 v[48:51], v[176:179], v[224:227], v[48:51]
	v_mfma_f32_16x16x32_bf16 v[40:43], v[216:219], v[224:227], v[40:43]
	v_mfma_f32_16x16x32_bf16 v[36:39], v[176:179], v[232:235], v[36:39]
	v_mfma_f32_16x16x32_bf16 v[28:31], v[216:219], v[232:235], v[28:31]
	v_mfma_f32_16x16x32_bf16 v[16:19], v[176:179], v[240:243], v[16:19]
	v_mfma_f32_16x16x32_bf16 v[8:11], v[216:219], v[240:243], v[8:11]
	v_mfma_f32_16x16x32_bf16 v[4:7], v[176:179], v[248:251], v[4:7]
	v_mfma_f32_16x16x32_bf16 v[0:3], v[216:219], v[248:251], v[0:3]
	s_setprio 0
	s_barrier
	s_add_i32 s50, 0, 0x18000
	s_add_i32 s51, 0, 0x1c000
	v_add_u32_e32 v168, s50, v182
	v_add_u32_e32 v204, s51, v182
	ds_read_b128 v[156:159], v168
	ds_read_b128 v[160:163], v168 offset:1024
	ds_read_b128 v[164:167], v168 offset:2048
	ds_read_b128 v[168:171], v168 offset:3072
	ds_read_b128 v[172:175], v204
	ds_read_b128 v[176:179], v204 offset:1024
	ds_read_b128 v[212:215], v204 offset:2048
	ds_read_b128 v[216:219], v204 offset:3072
	s_add_u32 s44, s44, 0x4000
	s_addc_u32 s45, s45, 0
	s_mov_b32 m0, s60
	ds_read_b128 v[220:223], v199 offset:32768
	ds_read_b128 v[224:227], v199 offset:33792
	ds_read_b128 v[228:231], v199 offset:34816
	ds_read_b128 v[232:235], v199 offset:35840
	ds_read_b128 v[236:239], v199 offset:36864
	ds_read_b128 v[240:243], v199 offset:37888
	ds_read_b128 v[244:247], v199 offset:38912
	ds_read_b128 v[248:251], v199 offset:39936
	global_load_lds_dwordx4 v128, s[44:45]
	s_mov_b32 m0, s61
	s_nop 0
	global_load_lds_dwordx4 v130, s[44:45]
	s_waitcnt vmcnt(8)
	s_waitcnt lgkmcnt(0)
	s_barrier
	s_setprio 1
	s_waitcnt lgkmcnt(0)
	v_mfma_f32_16x16x32_bf16 v[124:127], v[156:159], v[220:223], v[124:127]
	v_mfma_f32_16x16x32_bf16 v[120:123], v[164:167], v[220:223], v[120:123]
	v_mfma_f32_16x16x32_bf16 v[116:119], v[156:159], v[228:231], v[116:119]
	v_mfma_f32_16x16x32_bf16 v[108:111], v[164:167], v[228:231], v[108:111]
	v_mfma_f32_16x16x32_bf16 v[92:95], v[156:159], v[236:239], v[92:95]
	v_mfma_f32_16x16x32_bf16 v[88:91], v[164:167], v[236:239], v[88:91]
	v_mfma_f32_16x16x32_bf16 v[84:87], v[156:159], v[244:247], v[84:87]
	v_mfma_f32_16x16x32_bf16 v[76:79], v[164:167], v[244:247], v[76:79]
	v_mfma_f32_16x16x32_bf16 v[124:127], v[160:163], v[224:227], v[124:127]
	v_mfma_f32_16x16x32_bf16 v[120:123], v[168:171], v[224:227], v[120:123]
	v_mfma_f32_16x16x32_bf16 v[116:119], v[160:163], v[232:235], v[116:119]
	v_mfma_f32_16x16x32_bf16 v[108:111], v[168:171], v[232:235], v[108:111]
	v_mfma_f32_16x16x32_bf16 v[92:95], v[160:163], v[240:243], v[92:95]
	v_mfma_f32_16x16x32_bf16 v[88:91], v[168:171], v[240:243], v[88:91]
	v_mfma_f32_16x16x32_bf16 v[84:87], v[160:163], v[248:251], v[84:87]
	v_mfma_f32_16x16x32_bf16 v[76:79], v[168:171], v[248:251], v[76:79]
	v_mfma_f32_16x16x32_bf16 v[112:115], v[172:175], v[220:223], v[112:115]
	v_mfma_f32_16x16x32_bf16 v[104:107], v[212:215], v[220:223], v[104:107]
	v_mfma_f32_16x16x32_bf16 v[100:103], v[172:175], v[228:231], v[100:103]
	v_mfma_f32_16x16x32_bf16 v[96:99], v[212:215], v[228:231], v[96:99]
	v_mfma_f32_16x16x32_bf16 v[80:83], v[172:175], v[236:239], v[80:83]
	v_mfma_f32_16x16x32_bf16 v[72:75], v[212:215], v[236:239], v[72:75]
	v_mfma_f32_16x16x32_bf16 v[68:71], v[172:175], v[244:247], v[68:71]
	v_mfma_f32_16x16x32_bf16 v[64:67], v[212:215], v[244:247], v[64:67]
	v_mfma_f32_16x16x32_bf16 v[112:115], v[176:179], v[224:227], v[112:115]
	v_mfma_f32_16x16x32_bf16 v[104:107], v[216:219], v[224:227], v[104:107]
	v_mfma_f32_16x16x32_bf16 v[100:103], v[176:179], v[232:235], v[100:103]
	v_mfma_f32_16x16x32_bf16 v[96:99], v[216:219], v[232:235], v[96:99]
	v_mfma_f32_16x16x32_bf16 v[80:83], v[176:179], v[240:243], v[80:83]
	v_mfma_f32_16x16x32_bf16 v[72:75], v[216:219], v[240:243], v[72:75]
	v_mfma_f32_16x16x32_bf16 v[68:71], v[176:179], v[248:251], v[68:71]
	v_mfma_f32_16x16x32_bf16 v[64:67], v[216:219], v[248:251], v[64:67]
	s_setprio 0
	s_barrier
	s_add_u32 s44, s42, 0x8000
	s_addc_u32 s45, s43, 0
	s_add_i32 s50, s50, s57
	s_mov_b32 m0, s50
	ds_read_b128 v[220:223], v199 offset:49152
	ds_read_b128 v[224:227], v199 offset:50176
	ds_read_b128 v[228:231], v199 offset:51200
	ds_read_b128 v[232:235], v199 offset:52224
	ds_read_b128 v[236:239], v199 offset:53248
	ds_read_b128 v[240:243], v199 offset:54272
	ds_read_b128 v[244:247], v199 offset:55296
	ds_read_b128 v[248:251], v199 offset:56320
	global_load_lds_dwordx4 v128, s[44:45]
	s_add_i32 m0, s50, 0x2000
	s_add_u32 s42, s42, 0xc000
	v_lshl_add_u64 v[252:253], s[44:45], 0, v[130:131]
	s_addc_u32 s43, s43, 0
	s_add_i32 s44, s51, s57
	global_load_lds_dwordx4 v[252:253], off
	s_mov_b32 m0, s44
	s_nop 0
	global_load_lds_dwordx4 v128, s[42:43]
	s_add_i32 m0, s44, 0x2000
	s_nop 0
	global_load_lds_dwordx4 v130, s[42:43]
	s_mov_b32 m0, s67
	s_nop 0
	global_load_lds_dwordx4 v128, s[40:41]
	s_mov_b32 m0, s68
	s_nop 0
	global_load_lds_dwordx4 v130, s[40:41]
	s_waitcnt vmcnt(8)
	s_waitcnt lgkmcnt(0)
	s_barrier
	s_setprio 1
	s_waitcnt lgkmcnt(0)
	v_mfma_f32_16x16x32_bf16 v[60:63], v[156:159], v[220:223], v[60:63]
	v_mfma_f32_16x16x32_bf16 v[56:59], v[164:167], v[220:223], v[56:59]
	v_mfma_f32_16x16x32_bf16 v[52:55], v[156:159], v[228:231], v[52:55]
	v_mfma_f32_16x16x32_bf16 v[44:47], v[164:167], v[228:231], v[44:47]
	v_mfma_f32_16x16x32_bf16 v[32:35], v[156:159], v[236:239], v[32:35]
	v_mfma_f32_16x16x32_bf16 v[24:27], v[164:167], v[236:239], v[24:27]
	v_mfma_f32_16x16x32_bf16 v[20:23], v[156:159], v[244:247], v[20:23]
	v_mfma_f32_16x16x32_bf16 v[12:15], v[164:167], v[244:247], v[12:15]
	v_mfma_f32_16x16x32_bf16 v[60:63], v[160:163], v[224:227], v[60:63]
	v_mfma_f32_16x16x32_bf16 v[56:59], v[168:171], v[224:227], v[56:59]
	v_mfma_f32_16x16x32_bf16 v[52:55], v[160:163], v[232:235], v[52:55]
	v_mfma_f32_16x16x32_bf16 v[44:47], v[168:171], v[232:235], v[44:47]
	v_mfma_f32_16x16x32_bf16 v[32:35], v[160:163], v[240:243], v[32:35]
	v_mfma_f32_16x16x32_bf16 v[24:27], v[168:171], v[240:243], v[24:27]
	v_mfma_f32_16x16x32_bf16 v[20:23], v[160:163], v[248:251], v[20:23]
	v_mfma_f32_16x16x32_bf16 v[12:15], v[168:171], v[248:251], v[12:15]
	v_mfma_f32_16x16x32_bf16 v[48:51], v[172:175], v[220:223], v[48:51]
	v_mfma_f32_16x16x32_bf16 v[40:43], v[212:215], v[220:223], v[40:43]
	v_mfma_f32_16x16x32_bf16 v[36:39], v[172:175], v[228:231], v[36:39]
	v_mfma_f32_16x16x32_bf16 v[28:31], v[212:215], v[228:231], v[28:31]
	v_mfma_f32_16x16x32_bf16 v[16:19], v[172:175], v[236:239], v[16:19]
	v_mfma_f32_16x16x32_bf16 v[8:11], v[212:215], v[236:239], v[8:11]
	v_mfma_f32_16x16x32_bf16 v[4:7], v[172:175], v[244:247], v[4:7]
	v_mfma_f32_16x16x32_bf16 v[0:3], v[212:215], v[244:247], v[0:3]
	v_mfma_f32_16x16x32_bf16 v[48:51], v[176:179], v[224:227], v[48:51]
	v_mfma_f32_16x16x32_bf16 v[40:43], v[216:219], v[224:227], v[40:43]
	v_mfma_f32_16x16x32_bf16 v[36:39], v[176:179], v[232:235], v[36:39]
	v_mfma_f32_16x16x32_bf16 v[28:31], v[216:219], v[232:235], v[28:31]
	v_mfma_f32_16x16x32_bf16 v[16:19], v[176:179], v[240:243], v[16:19]
	v_mfma_f32_16x16x32_bf16 v[8:11], v[216:219], v[240:243], v[8:11]
	v_mfma_f32_16x16x32_bf16 v[4:7], v[176:179], v[248:251], v[4:7]
	v_mfma_f32_16x16x32_bf16 v[0:3], v[216:219], v[248:251], v[0:3]
	s_setprio 0
	s_barrier
	s_add_i32 s49, s49, 2
	s_add_u32 s47, s47, 0x10000
	s_addc_u32 s48, s48, 0
	s_add_u32 s38, s38, 0x10000
	s_addc_u32 s39, s39, 0
	s_cmp_gt_u32 s49, 41
	s_cbranch_scc0 .LBB0_408
	s_and_b64 vcc, exec, s[14:15]
	s_cbranch_vccz .LBB0_411
	s_barrier

.LBB0_492:
	ds_read_b128 v[128:131], v212
	ds_read_b128 v[132:135], v212 offset:1024
	ds_read_b128 v[136:139], v212 offset:2048
	ds_read_b128 v[140:143], v212 offset:3072
	ds_read_b128 v[144:147], v213
	ds_read_b128 v[148:151], v213 offset:1024
	ds_read_b128 v[152:155], v213 offset:2048
	ds_read_b128 v[156:159], v213 offset:3072
	s_add_u32 s34, s30, 0xfffc0080
	s_addc_u32 s35, s31, -1
	s_cmp_eq_u32 s39, 12
	s_cselect_b32 s37, s1, s35
	s_cselect_b32 s36, s7, s34
	s_cselect_b32 s35, s10, s38
	s_cselect_b32 s34, s23, s25
	s_add_i32 m0, s47, 0xc000
	ds_read_b128 v[160:163], v214
	ds_read_b128 v[164:167], v214 offset:1024
	ds_read_b128 v[196:199], v214 offset:2048
	ds_read_b128 v[216:219], v214 offset:3072
	ds_read_b128 v[220:223], v214 offset:4096
	ds_read_b128 v[224:227], v214 offset:5120
	ds_read_b128 v[228:231], v214 offset:6144
	ds_read_b128 v[232:235], v214 offset:7168
	global_load_lds_dwordx4 v190, s[30:31]
	s_add_i32 m0, s47, 0xe000
	s_nop 0
	global_load_lds_dwordx4 v188, s[30:31]
	s_waitcnt vmcnt(8)
	s_waitcnt lgkmcnt(0)
	s_barrier
	s_setprio 1
	s_waitcnt lgkmcnt(0)
	v_mfma_f32_16x16x32_bf16 v[124:127], v[128:131], v[160:163], v[124:127]
	v_mfma_f32_16x16x32_bf16 v[120:123], v[136:139], v[160:163], v[120:123]
	v_mfma_f32_16x16x32_bf16 v[116:119], v[128:131], v[196:199], v[116:119]
	v_mfma_f32_16x16x32_bf16 v[112:115], v[136:139], v[196:199], v[112:115]
	v_mfma_f32_16x16x32_bf16 v[108:111], v[128:131], v[220:223], v[108:111]
	v_mfma_f32_16x16x32_bf16 v[104:107], v[136:139], v[220:223], v[104:107]
	v_mfma_f32_16x16x32_bf16 v[100:103], v[128:131], v[228:231], v[100:103]
	v_mfma_f32_16x16x32_bf16 v[96:99], v[136:139], v[228:231], v[96:99]
	v_mfma_f32_16x16x32_bf16 v[124:127], v[132:135], v[164:167], v[124:127]
	v_mfma_f32_16x16x32_bf16 v[120:123], v[140:143], v[164:167], v[120:123]
	v_mfma_f32_16x16x32_bf16 v[116:119], v[132:135], v[216:219], v[116:119]
	v_mfma_f32_16x16x32_bf16 v[112:115], v[140:143], v[216:219], v[112:115]
	v_mfma_f32_16x16x32_bf16 v[108:111], v[132:135], v[224:227], v[108:111]
	v_mfma_f32_16x16x32_bf16 v[104:107], v[140:143], v[224:227], v[104:107]
	v_mfma_f32_16x16x32_bf16 v[100:103], v[132:135], v[232:235], v[100:103]
	v_mfma_f32_16x16x32_bf16 v[96:99], v[140:143], v[232:235], v[96:99]
	v_mfma_f32_16x16x32_bf16 v[60:63], v[144:147], v[160:163], v[60:63]
	v_mfma_f32_16x16x32_bf16 v[56:59], v[152:155], v[160:163], v[56:59]
	v_mfma_f32_16x16x32_bf16 v[52:55], v[144:147], v[196:199], v[52:55]
	v_mfma_f32_16x16x32_bf16 v[48:51], v[152:155], v[196:199], v[48:51]
	v_mfma_f32_16x16x32_bf16 v[44:47], v[144:147], v[220:223], v[44:47]
	v_mfma_f32_16x16x32_bf16 v[40:43], v[152:155], v[220:223], v[40:43]
	v_mfma_f32_16x16x32_bf16 v[36:39], v[144:147], v[228:231], v[36:39]
	v_mfma_f32_16x16x32_bf16 v[32:35], v[152:155], v[228:231], v[32:35]
	v_mfma_f32_16x16x32_bf16 v[60:63], v[148:151], v[164:167], v[60:63]
	v_mfma_f32_16x16x32_bf16 v[56:59], v[156:159], v[164:167], v[56:59]
	v_mfma_f32_16x16x32_bf16 v[52:55], v[148:151], v[216:219], v[52:55]
	v_mfma_f32_16x16x32_bf16 v[48:51], v[156:159], v[216:219], v[48:51]
	v_mfma_f32_16x16x32_bf16 v[44:47], v[148:151], v[224:227], v[44:47]
	v_mfma_f32_16x16x32_bf16 v[40:43], v[156:159], v[224:227], v[40:43]
	v_mfma_f32_16x16x32_bf16 v[36:39], v[148:151], v[232:235], v[36:39]
	v_mfma_f32_16x16x32_bf16 v[32:35], v[156:159], v[232:235], v[32:35]
	s_setprio 0
	s_barrier
	s_add_i32 s66, s61, s46
	s_mov_b32 m0, s66
	ds_read_b128 v[160:163], v214 offset:16384
	ds_read_b128 v[164:167], v214 offset:17408
	ds_read_b128 v[196:199], v214 offset:18432
	ds_read_b128 v[216:219], v214 offset:19456
	ds_read_b128 v[220:223], v214 offset:20480
	ds_read_b128 v[224:227], v214 offset:21504
	ds_read_b128 v[228:231], v214 offset:22528
	ds_read_b128 v[232:235], v214 offset:23552
	global_load_lds_dwordx4 v172, s[34:35]
	s_add_i32 m0, s66, 0x2000
	s_add_u32 s66, s34, 0x4000
	s_addc_u32 s67, s35, 0
	s_add_i32 s68, s62, s46
	global_load_lds_dwordx4 v176, s[34:35]
	s_mov_b32 m0, s68
	v_lshl_add_u64 v[236:237], s[36:37], 0, v[174:175]
	global_load_lds_dwordx4 v172, s[66:67]
	s_add_i32 m0, s68, 0x2000
	s_nop 0
	global_load_lds_dwordx4 v176, s[66:67]
	v_lshl_add_u64 v[200:201], s[36:37], 0, v[170:171]
	s_mov_b32 m0, s47
	s_nop 0
	global_load_lds_dwordx4 v[200:201], off
	s_mov_b32 m0, s48
	s_nop 0
	global_load_lds_dwordx4 v[236:237], off
	s_waitcnt vmcnt(8)
	s_waitcnt lgkmcnt(0)
	s_barrier
	s_setprio 1
	s_waitcnt lgkmcnt(0)
	v_mfma_f32_16x16x32_bf16 v[92:95], v[128:131], v[160:163], v[92:95]
	v_mfma_f32_16x16x32_bf16 v[88:91], v[136:139], v[160:163], v[88:91]
	v_mfma_f32_16x16x32_bf16 v[84:87], v[128:131], v[196:199], v[84:87]
	v_mfma_f32_16x16x32_bf16 v[80:83], v[136:139], v[196:199], v[80:83]
	v_mfma_f32_16x16x32_bf16 v[76:79], v[128:131], v[220:223], v[76:79]
	v_mfma_f32_16x16x32_bf16 v[72:75], v[136:139], v[220:223], v[72:75]
	v_mfma_f32_16x16x32_bf16 v[68:71], v[128:131], v[228:231], v[68:71]
	v_mfma_f32_16x16x32_bf16 v[64:67], v[136:139], v[228:231], v[64:67]
	v_mfma_f32_16x16x32_bf16 v[92:95], v[132:135], v[164:167], v[92:95]
	v_mfma_f32_16x16x32_bf16 v[88:91], v[140:143], v[164:167], v[88:91]
	v_mfma_f32_16x16x32_bf16 v[84:87], v[132:135], v[216:219], v[84:87]
	v_mfma_f32_16x16x32_bf16 v[80:83], v[140:143], v[216:219], v[80:83]
	v_mfma_f32_16x16x32_bf16 v[76:79], v[132:135], v[224:227], v[76:79]
	v_mfma_f32_16x16x32_bf16 v[72:75], v[140:143], v[224:227], v[72:75]
	v_mfma_f32_16x16x32_bf16 v[68:71], v[132:135], v[232:235], v[68:71]
	v_mfma_f32_16x16x32_bf16 v[64:67], v[140:143], v[232:235], v[64:67]
	v_mfma_f32_16x16x32_bf16 v[28:31], v[144:147], v[160:163], v[28:31]
	v_mfma_f32_16x16x32_bf16 v[24:27], v[152:155], v[160:163], v[24:27]
	v_mfma_f32_16x16x32_bf16 v[20:23], v[144:147], v[196:199], v[20:23]
	v_mfma_f32_16x16x32_bf16 v[16:19], v[152:155], v[196:199], v[16:19]
	v_mfma_f32_16x16x32_bf16 v[12:15], v[144:147], v[220:223], v[12:15]
	v_mfma_f32_16x16x32_bf16 v[8:11], v[152:155], v[220:223], v[8:11]
	v_mfma_f32_16x16x32_bf16 v[4:7], v[144:147], v[228:231], v[4:7]
	v_mfma_f32_16x16x32_bf16 v[0:3], v[152:155], v[228:231], v[0:3]
	v_mfma_f32_16x16x32_bf16 v[28:31], v[148:151], v[164:167], v[28:31]
	v_mfma_f32_16x16x32_bf16 v[24:27], v[156:159], v[164:167], v[24:27]
	v_mfma_f32_16x16x32_bf16 v[20:23], v[148:151], v[216:219], v[20:23]
	v_mfma_f32_16x16x32_bf16 v[16:19], v[156:159], v[216:219], v[16:19]
	v_mfma_f32_16x16x32_bf16 v[12:15], v[148:151], v[224:227], v[12:15]
	v_mfma_f32_16x16x32_bf16 v[8:11], v[156:159], v[224:227], v[8:11]
	v_mfma_f32_16x16x32_bf16 v[4:7], v[148:151], v[232:235], v[4:7]
	v_mfma_f32_16x16x32_bf16 v[0:3], v[156:159], v[232:235], v[0:3]
	s_setprio 0
	s_barrier
	s_add_i32 s66, 0, 0x18000
	s_add_i32 s67, 0, 0x1c000
	v_add_u32_e32 v140, s66, v210
	v_add_u32_e32 v156, s67, v210
	ds_read_b128 v[128:131], v140
	ds_read_b128 v[132:135], v140 offset:1024
	ds_read_b128 v[136:139], v140 offset:2048
	ds_read_b128 v[140:143], v140 offset:3072
	ds_read_b128 v[144:147], v156
	ds_read_b128 v[148:151], v156 offset:1024
	ds_read_b128 v[152:155], v156 offset:2048
	ds_read_b128 v[156:159], v156 offset:3072
	s_add_u32 s36, s36, 0x40000
	s_addc_u32 s37, s37, 0
	s_mov_b32 m0, s49
	ds_read_b128 v[160:163], v214 offset:32768
	ds_read_b128 v[164:167], v214 offset:33792
	ds_read_b128 v[196:199], v214 offset:34816
	ds_read_b128 v[216:219], v214 offset:35840
	ds_read_b128 v[220:223], v214 offset:36864
	ds_read_b128 v[224:227], v214 offset:37888
	ds_read_b128 v[228:231], v214 offset:38912
	ds_read_b128 v[232:235], v214 offset:39936
	global_load_lds_dwordx4 v170, s[36:37]
	s_mov_b32 m0, s50
	s_nop 0
	global_load_lds_dwordx4 v174, s[36:37]
	s_waitcnt vmcnt(8)
	s_waitcnt lgkmcnt(0)
	s_barrier
	s_setprio 1
	s_waitcnt lgkmcnt(0)
	v_mfma_f32_16x16x32_bf16 v[124:127], v[128:131], v[160:163], v[124:127]
	v_mfma_f32_16x16x32_bf16 v[120:123], v[136:139], v[160:163], v[120:123]
	v_mfma_f32_16x16x32_bf16 v[116:119], v[128:131], v[196:199], v[116:119]
	v_mfma_f32_16x16x32_bf16 v[112:115], v[136:139], v[196:199], v[112:115]
	v_mfma_f32_16x16x32_bf16 v[108:111], v[128:131], v[220:223], v[108:111]
	v_mfma_f32_16x16x32_bf16 v[104:107], v[136:139], v[220:223], v[104:107]
	v_mfma_f32_16x16x32_bf16 v[100:103], v[128:131], v[228:231], v[100:103]
	v_mfma_f32_16x16x32_bf16 v[96:99], v[136:139], v[228:231], v[96:99]
	v_mfma_f32_16x16x32_bf16 v[124:127], v[132:135], v[164:167], v[124:127]
	v_mfma_f32_16x16x32_bf16 v[120:123], v[140:143], v[164:167], v[120:123]
	v_mfma_f32_16x16x32_bf16 v[116:119], v[132:135], v[216:219], v[116:119]
	v_mfma_f32_16x16x32_bf16 v[112:115], v[140:143], v[216:219], v[112:115]
	v_mfma_f32_16x16x32_bf16 v[108:111], v[132:135], v[224:227], v[108:111]
	v_mfma_f32_16x16x32_bf16 v[104:107], v[140:143], v[224:227], v[104:107]
	v_mfma_f32_16x16x32_bf16 v[100:103], v[132:135], v[232:235], v[100:103]
	v_mfma_f32_16x16x32_bf16 v[96:99], v[140:143], v[232:235], v[96:99]
	v_mfma_f32_16x16x32_bf16 v[60:63], v[144:147], v[160:163], v[60:63]
	v_mfma_f32_16x16x32_bf16 v[56:59], v[152:155], v[160:163], v[56:59]
	v_mfma_f32_16x16x32_bf16 v[52:55], v[144:147], v[196:199], v[52:55]
	v_mfma_f32_16x16x32_bf16 v[48:51], v[152:155], v[196:199], v[48:51]
	v_mfma_f32_16x16x32_bf16 v[44:47], v[144:147], v[220:223], v[44:47]
	v_mfma_f32_16x16x32_bf16 v[40:43], v[152:155], v[220:223], v[40:43]
	v_mfma_f32_16x16x32_bf16 v[36:39], v[144:147], v[228:231], v[36:39]
	v_mfma_f32_16x16x32_bf16 v[32:35], v[152:155], v[228:231], v[32:35]
	v_mfma_f32_16x16x32_bf16 v[60:63], v[148:151], v[164:167], v[60:63]
	v_mfma_f32_16x16x32_bf16 v[56:59], v[156:159], v[164:167], v[56:59]
	v_mfma_f32_16x16x32_bf16 v[52:55], v[148:151], v[216:219], v[52:55]
	v_mfma_f32_16x16x32_bf16 v[48:51], v[156:159], v[216:219], v[48:51]
	v_mfma_f32_16x16x32_bf16 v[44:47], v[148:151], v[224:227], v[44:47]
	v_mfma_f32_16x16x32_bf16 v[40:43], v[156:159], v[224:227], v[40:43]
	v_mfma_f32_16x16x32_bf16 v[36:39], v[148:151], v[232:235], v[36:39]
	v_mfma_f32_16x16x32_bf16 v[32:35], v[156:159], v[232:235], v[32:35]
	s_setprio 0
	s_barrier
	s_add_u32 s36, s34, 0x8000
	s_addc_u32 s37, s35, 0
	s_add_i32 s66, s66, s46
	s_mov_b32 m0, s66
	ds_read_b128 v[160:163], v214 offset:49152
	ds_read_b128 v[164:167], v214 offset:50176
	ds_read_b128 v[196:199], v214 offset:51200
	ds_read_b128 v[216:219], v214 offset:52224
	ds_read_b128 v[220:223], v214 offset:53248
	ds_read_b128 v[224:227], v214 offset:54272
	ds_read_b128 v[228:231], v214 offset:55296
	ds_read_b128 v[232:235], v214 offset:56320
	global_load_lds_dwordx4 v172, s[36:37]
	s_add_i32 m0, s66, 0x2000
	s_add_u32 s34, s34, 0xc000
	v_lshl_add_u64 v[238:239], s[36:37], 0, v[176:177]
	s_addc_u32 s35, s35, 0
	s_add_i32 s36, s67, s46
	global_load_lds_dwordx4 v[238:239], off
	s_mov_b32 m0, s36
	v_lshl_add_u64 v[200:201], v[200:201], 0, s[16:17]
	global_load_lds_dwordx4 v172, s[34:35]
	s_add_i32 m0, s36, 0x2000
	s_nop 0
	global_load_lds_dwordx4 v176, s[34:35]
	s_mov_b32 m0, s55
	s_nop 0
	global_load_lds_dwordx4 v[200:201], off
	v_lshl_add_u64 v[200:201], v[236:237], 0, s[16:17]
	s_mov_b32 m0, s56
	s_nop 0
	global_load_lds_dwordx4 v[200:201], off
	s_waitcnt vmcnt(8)
	s_waitcnt lgkmcnt(0)
	s_barrier
	s_setprio 1
	s_waitcnt lgkmcnt(0)
	v_mfma_f32_16x16x32_bf16 v[92:95], v[128:131], v[160:163], v[92:95]
	v_mfma_f32_16x16x32_bf16 v[88:91], v[136:139], v[160:163], v[88:91]
	v_mfma_f32_16x16x32_bf16 v[84:87], v[128:131], v[196:199], v[84:87]
	v_mfma_f32_16x16x32_bf16 v[80:83], v[136:139], v[196:199], v[80:83]
	v_mfma_f32_16x16x32_bf16 v[76:79], v[128:131], v[220:223], v[76:79]
	v_mfma_f32_16x16x32_bf16 v[72:75], v[136:139], v[220:223], v[72:75]
	v_mfma_f32_16x16x32_bf16 v[68:71], v[128:131], v[228:231], v[68:71]
	v_mfma_f32_16x16x32_bf16 v[64:67], v[136:139], v[228:231], v[64:67]
	v_mfma_f32_16x16x32_bf16 v[92:95], v[132:135], v[164:167], v[92:95]
	v_mfma_f32_16x16x32_bf16 v[88:91], v[140:143], v[164:167], v[88:91]
	v_mfma_f32_16x16x32_bf16 v[84:87], v[132:135], v[216:219], v[84:87]
	v_mfma_f32_16x16x32_bf16 v[80:83], v[140:143], v[216:219], v[80:83]
	v_mfma_f32_16x16x32_bf16 v[76:79], v[132:135], v[224:227], v[76:79]
	v_mfma_f32_16x16x32_bf16 v[72:75], v[140:143], v[224:227], v[72:75]
	v_mfma_f32_16x16x32_bf16 v[68:71], v[132:135], v[232:235], v[68:71]
	v_mfma_f32_16x16x32_bf16 v[64:67], v[140:143], v[232:235], v[64:67]
	v_mfma_f32_16x16x32_bf16 v[28:31], v[144:147], v[160:163], v[28:31]
	v_mfma_f32_16x16x32_bf16 v[24:27], v[152:155], v[160:163], v[24:27]
	v_mfma_f32_16x16x32_bf16 v[20:23], v[144:147], v[196:199], v[20:23]
	v_mfma_f32_16x16x32_bf16 v[16:19], v[152:155], v[196:199], v[16:19]
	v_mfma_f32_16x16x32_bf16 v[12:15], v[144:147], v[220:223], v[12:15]
	v_mfma_f32_16x16x32_bf16 v[8:11], v[152:155], v[220:223], v[8:11]
	v_mfma_f32_16x16x32_bf16 v[4:7], v[144:147], v[228:231], v[4:7]
	v_mfma_f32_16x16x32_bf16 v[0:3], v[152:155], v[228:231], v[0:3]
	v_mfma_f32_16x16x32_bf16 v[28:31], v[148:151], v[164:167], v[28:31]
	v_mfma_f32_16x16x32_bf16 v[24:27], v[156:159], v[164:167], v[24:27]
	v_mfma_f32_16x16x32_bf16 v[20:23], v[148:151], v[216:219], v[20:23]
	v_mfma_f32_16x16x32_bf16 v[16:19], v[156:159], v[216:219], v[16:19]
	v_mfma_f32_16x16x32_bf16 v[12:15], v[148:151], v[224:227], v[12:15]
	v_mfma_f32_16x16x32_bf16 v[8:11], v[156:159], v[224:227], v[8:11]
	v_mfma_f32_16x16x32_bf16 v[4:7], v[148:151], v[232:235], v[4:7]
	v_mfma_f32_16x16x32_bf16 v[0:3], v[156:159], v[232:235], v[0:3]
	s_setprio 0
	s_barrier
	s_add_i32 s39, s39, 2
	s_add_u32 s25, s25, 0x10000
	s_addc_u32 s38, s38, 0
	s_add_u32 s30, s30, 0x100
	s_addc_u32 s31, s31, 0
	s_cmp_gt_u32 s39, 13
	s_cbranch_scc0 .LBB0_492
	s_and_b64 vcc, exec, s[18:19]
	s_cbranch_vccz .LBB0_503
	s_barrier
	v_lshl_add_u32 v216, s0, 8, v169
	s_cmp_gt_i32 s6, 4
	s_mov_b64 s[0:1], -1
	s_cbranch_scc1 .LBB0_504

.LBB0_1071:
	ds_read_b128 v[128:131], v170
	ds_read_b128 v[148:151], v170 offset:1024
	ds_read_b128 v[152:155], v170 offset:2048
	ds_read_b128 v[174:177], v170 offset:3072
	ds_read_b128 v[178:181], v171
	ds_read_b128 v[182:185], v171 offset:1024
	ds_read_b128 v[186:189], v171 offset:2048
	ds_read_b128 v[190:193], v171 offset:3072
	s_add_u32 s30, s28, 0xfffe0080
	s_addc_u32 s31, s29, -1
	s_cmp_eq_u32 s56, 4
	s_cselect_b32 s35, s17, s31
	s_cselect_b32 s34, s52, s30
	s_cselect_b32 s31, s19, s55
	s_cselect_b32 s30, s53, s54
	s_add_i32 m0, s25, 0xc000
	ds_read_b128 v[194:197], v172
	ds_read_b128 v[198:201], v172 offset:1024
	ds_read_b128 v[210:213], v172 offset:2048
	ds_read_b128 v[214:217], v172 offset:3072
	ds_read_b128 v[218:221], v172 offset:4096
	ds_read_b128 v[222:225], v172 offset:5120
	ds_read_b128 v[226:229], v172 offset:6144
	ds_read_b128 v[230:233], v172 offset:7168
	global_load_lds_dwordx4 v142, s[28:29]
	s_add_i32 m0, s25, 0xe000
	s_nop 0
	global_load_lds_dwordx4 v140, s[28:29]
	s_waitcnt vmcnt(8)
	s_waitcnt lgkmcnt(0)
	s_barrier
	s_setprio 1
	s_waitcnt lgkmcnt(0)
	v_mfma_f32_16x16x32_bf16 v[124:127], v[128:131], v[194:197], v[124:127]
	v_mfma_f32_16x16x32_bf16 v[120:123], v[152:155], v[194:197], v[120:123]
	v_mfma_f32_16x16x32_bf16 v[116:119], v[128:131], v[210:213], v[116:119]
	v_mfma_f32_16x16x32_bf16 v[112:115], v[152:155], v[210:213], v[112:115]
	v_mfma_f32_16x16x32_bf16 v[92:95], v[128:131], v[218:221], v[92:95]
	v_mfma_f32_16x16x32_bf16 v[88:91], v[152:155], v[218:221], v[88:91]
	v_mfma_f32_16x16x32_bf16 v[84:87], v[128:131], v[226:229], v[84:87]
	v_mfma_f32_16x16x32_bf16 v[72:75], v[152:155], v[226:229], v[72:75]
	v_mfma_f32_16x16x32_bf16 v[124:127], v[148:151], v[198:201], v[124:127]
	v_mfma_f32_16x16x32_bf16 v[120:123], v[174:177], v[198:201], v[120:123]
	v_mfma_f32_16x16x32_bf16 v[116:119], v[148:151], v[214:217], v[116:119]
	v_mfma_f32_16x16x32_bf16 v[112:115], v[174:177], v[214:217], v[112:115]
	v_mfma_f32_16x16x32_bf16 v[92:95], v[148:151], v[222:225], v[92:95]
	v_mfma_f32_16x16x32_bf16 v[88:91], v[174:177], v[222:225], v[88:91]
	v_mfma_f32_16x16x32_bf16 v[84:87], v[148:151], v[230:233], v[84:87]
	v_mfma_f32_16x16x32_bf16 v[72:75], v[174:177], v[230:233], v[72:75]
	v_mfma_f32_16x16x32_bf16 v[108:111], v[178:181], v[194:197], v[108:111]
	v_mfma_f32_16x16x32_bf16 v[104:107], v[186:189], v[194:197], v[104:107]
	v_mfma_f32_16x16x32_bf16 v[100:103], v[178:181], v[210:213], v[100:103]
	v_mfma_f32_16x16x32_bf16 v[96:99], v[186:189], v[210:213], v[96:99]
	v_mfma_f32_16x16x32_bf16 v[80:83], v[178:181], v[218:221], v[80:83]
	v_mfma_f32_16x16x32_bf16 v[76:79], v[186:189], v[218:221], v[76:79]
	v_mfma_f32_16x16x32_bf16 v[68:71], v[178:181], v[226:229], v[68:71]
	v_mfma_f32_16x16x32_bf16 v[64:67], v[186:189], v[226:229], v[64:67]
	v_mfma_f32_16x16x32_bf16 v[108:111], v[182:185], v[198:201], v[108:111]
	v_mfma_f32_16x16x32_bf16 v[104:107], v[190:193], v[198:201], v[104:107]
	v_mfma_f32_16x16x32_bf16 v[100:103], v[182:185], v[214:217], v[100:103]
	v_mfma_f32_16x16x32_bf16 v[96:99], v[190:193], v[214:217], v[96:99]
	v_mfma_f32_16x16x32_bf16 v[80:83], v[182:185], v[222:225], v[80:83]
	v_mfma_f32_16x16x32_bf16 v[76:79], v[190:193], v[222:225], v[76:79]
	v_mfma_f32_16x16x32_bf16 v[68:71], v[182:185], v[230:233], v[68:71]
	v_mfma_f32_16x16x32_bf16 v[64:67], v[190:193], v[230:233], v[64:67]
	s_setprio 0
	s_barrier
	s_add_i32 s57, s49, s42
	s_mov_b32 m0, s57
	ds_read_b128 v[194:197], v172 offset:16384
	ds_read_b128 v[198:201], v172 offset:17408
	ds_read_b128 v[210:213], v172 offset:18432
	ds_read_b128 v[214:217], v172 offset:19456
	ds_read_b128 v[218:221], v172 offset:20480
	ds_read_b128 v[222:225], v172 offset:21504
	ds_read_b128 v[226:229], v172 offset:22528
	ds_read_b128 v[230:233], v172 offset:23552
	global_load_lds_dwordx4 v134, s[30:31]
	s_add_i32 m0, s57, 0x2000
	s_add_u32 s58, s30, 0x4000
	s_addc_u32 s59, s31, 0
	s_add_i32 s57, s50, s42
	global_load_lds_dwordx4 v138, s[30:31]
	s_mov_b32 m0, s57
	v_lshl_add_u64 v[236:237], s[34:35], 0, v[136:137]
	global_load_lds_dwordx4 v134, s[58:59]
	s_add_i32 m0, s57, 0x2000
	s_nop 0
	global_load_lds_dwordx4 v138, s[58:59]
	v_lshl_add_u64 v[234:235], s[34:35], 0, v[132:133]
	s_mov_b32 m0, s25
	s_nop 0
	global_load_lds_dwordx4 v[234:235], off
	s_mov_b32 m0, s27
	s_nop 0
	global_load_lds_dwordx4 v[236:237], off
	s_waitcnt vmcnt(8)
	s_waitcnt lgkmcnt(0)
	s_barrier
	s_setprio 1
	s_waitcnt lgkmcnt(0)
	v_mfma_f32_16x16x32_bf16 v[60:63], v[128:131], v[194:197], v[60:63]
	v_mfma_f32_16x16x32_bf16 v[56:59], v[152:155], v[194:197], v[56:59]
	v_mfma_f32_16x16x32_bf16 v[48:51], v[128:131], v[210:213], v[48:51]
	v_mfma_f32_16x16x32_bf16 v[40:43], v[152:155], v[210:213], v[40:43]
	v_mfma_f32_16x16x32_bf16 v[32:35], v[128:131], v[218:221], v[32:35]
	v_mfma_f32_16x16x32_bf16 v[24:27], v[152:155], v[218:221], v[24:27]
	v_mfma_f32_16x16x32_bf16 v[16:19], v[128:131], v[226:229], v[16:19]
	v_mfma_f32_16x16x32_bf16 v[8:11], v[152:155], v[226:229], v[8:11]
	v_mfma_f32_16x16x32_bf16 v[60:63], v[148:151], v[198:201], v[60:63]
	v_mfma_f32_16x16x32_bf16 v[56:59], v[174:177], v[198:201], v[56:59]
	v_mfma_f32_16x16x32_bf16 v[48:51], v[148:151], v[214:217], v[48:51]
	v_mfma_f32_16x16x32_bf16 v[40:43], v[174:177], v[214:217], v[40:43]
	v_mfma_f32_16x16x32_bf16 v[32:35], v[148:151], v[222:225], v[32:35]
	v_mfma_f32_16x16x32_bf16 v[24:27], v[174:177], v[222:225], v[24:27]
	v_mfma_f32_16x16x32_bf16 v[16:19], v[148:151], v[230:233], v[16:19]
	v_mfma_f32_16x16x32_bf16 v[8:11], v[174:177], v[230:233], v[8:11]
	v_mfma_f32_16x16x32_bf16 v[52:55], v[178:181], v[194:197], v[52:55]
	v_mfma_f32_16x16x32_bf16 v[44:47], v[186:189], v[194:197], v[44:47]
	v_mfma_f32_16x16x32_bf16 v[36:39], v[178:181], v[210:213], v[36:39]
	v_mfma_f32_16x16x32_bf16 v[28:31], v[186:189], v[210:213], v[28:31]
	v_mfma_f32_16x16x32_bf16 v[20:23], v[178:181], v[218:221], v[20:23]
	v_mfma_f32_16x16x32_bf16 v[12:15], v[186:189], v[218:221], v[12:15]
	v_mfma_f32_16x16x32_bf16 v[4:7], v[178:181], v[226:229], v[4:7]
	v_mfma_f32_16x16x32_bf16 v[0:3], v[186:189], v[226:229], v[0:3]
	v_mfma_f32_16x16x32_bf16 v[52:55], v[182:185], v[198:201], v[52:55]
	v_mfma_f32_16x16x32_bf16 v[44:47], v[190:193], v[198:201], v[44:47]
	v_mfma_f32_16x16x32_bf16 v[36:39], v[182:185], v[214:217], v[36:39]
	v_mfma_f32_16x16x32_bf16 v[28:31], v[190:193], v[214:217], v[28:31]
	v_mfma_f32_16x16x32_bf16 v[20:23], v[182:185], v[222:225], v[20:23]
	v_mfma_f32_16x16x32_bf16 v[12:15], v[190:193], v[222:225], v[12:15]
	v_mfma_f32_16x16x32_bf16 v[4:7], v[182:185], v[230:233], v[4:7]
	v_mfma_f32_16x16x32_bf16 v[0:3], v[190:193], v[230:233], v[0:3]
	s_setprio 0
	s_barrier
	s_add_i32 s57, 0, 0x18000
	v_add_u32_e32 v173, s57, v168
	s_add_i32 s58, 0, 0x1c000
	ds_read_b128 v[128:131], v173
	ds_read_b128 v[148:151], v173 offset:1024
	ds_read_b128 v[152:155], v173 offset:2048
	ds_read_b128 v[174:177], v173 offset:3072
	v_add_u32_e32 v173, s58, v168
	ds_read_b128 v[178:181], v173
	ds_read_b128 v[182:185], v173 offset:1024
	ds_read_b128 v[186:189], v173 offset:2048
	ds_read_b128 v[190:193], v173 offset:3072
	s_add_u32 s34, s34, 0x20000
	s_addc_u32 s35, s35, 0
	s_mov_b32 m0, s43
	ds_read_b128 v[194:197], v172 offset:32768
	ds_read_b128 v[198:201], v172 offset:33792
	ds_read_b128 v[210:213], v172 offset:34816
	ds_read_b128 v[214:217], v172 offset:35840
	ds_read_b128 v[218:221], v172 offset:36864
	ds_read_b128 v[222:225], v172 offset:37888
	ds_read_b128 v[226:229], v172 offset:38912
	ds_read_b128 v[230:233], v172 offset:39936
	global_load_lds_dwordx4 v132, s[34:35]
	s_mov_b32 m0, s44
	s_nop 0
	global_load_lds_dwordx4 v136, s[34:35]
	s_waitcnt vmcnt(8)
	s_waitcnt lgkmcnt(0)
	s_barrier
	s_setprio 1
	s_waitcnt lgkmcnt(0)
	v_mfma_f32_16x16x32_bf16 v[124:127], v[128:131], v[194:197], v[124:127]
	v_mfma_f32_16x16x32_bf16 v[120:123], v[152:155], v[194:197], v[120:123]
	v_mfma_f32_16x16x32_bf16 v[116:119], v[128:131], v[210:213], v[116:119]
	v_mfma_f32_16x16x32_bf16 v[112:115], v[152:155], v[210:213], v[112:115]
	v_mfma_f32_16x16x32_bf16 v[92:95], v[128:131], v[218:221], v[92:95]
	v_mfma_f32_16x16x32_bf16 v[88:91], v[152:155], v[218:221], v[88:91]
	v_mfma_f32_16x16x32_bf16 v[84:87], v[128:131], v[226:229], v[84:87]
	v_mfma_f32_16x16x32_bf16 v[72:75], v[152:155], v[226:229], v[72:75]
	v_mfma_f32_16x16x32_bf16 v[124:127], v[148:151], v[198:201], v[124:127]
	v_mfma_f32_16x16x32_bf16 v[120:123], v[174:177], v[198:201], v[120:123]
	v_mfma_f32_16x16x32_bf16 v[116:119], v[148:151], v[214:217], v[116:119]
	v_mfma_f32_16x16x32_bf16 v[112:115], v[174:177], v[214:217], v[112:115]
	v_mfma_f32_16x16x32_bf16 v[92:95], v[148:151], v[222:225], v[92:95]
	v_mfma_f32_16x16x32_bf16 v[88:91], v[174:177], v[222:225], v[88:91]
	v_mfma_f32_16x16x32_bf16 v[84:87], v[148:151], v[230:233], v[84:87]
	v_mfma_f32_16x16x32_bf16 v[72:75], v[174:177], v[230:233], v[72:75]
	v_mfma_f32_16x16x32_bf16 v[108:111], v[178:181], v[194:197], v[108:111]
	v_mfma_f32_16x16x32_bf16 v[104:107], v[186:189], v[194:197], v[104:107]
	v_mfma_f32_16x16x32_bf16 v[100:103], v[178:181], v[210:213], v[100:103]
	v_mfma_f32_16x16x32_bf16 v[96:99], v[186:189], v[210:213], v[96:99]
	v_mfma_f32_16x16x32_bf16 v[80:83], v[178:181], v[218:221], v[80:83]
	v_mfma_f32_16x16x32_bf16 v[76:79], v[186:189], v[218:221], v[76:79]
	v_mfma_f32_16x16x32_bf16 v[68:71], v[178:181], v[226:229], v[68:71]
	v_mfma_f32_16x16x32_bf16 v[64:67], v[186:189], v[226:229], v[64:67]
	v_mfma_f32_16x16x32_bf16 v[108:111], v[182:185], v[198:201], v[108:111]
	v_mfma_f32_16x16x32_bf16 v[104:107], v[190:193], v[198:201], v[104:107]
	v_mfma_f32_16x16x32_bf16 v[100:103], v[182:185], v[214:217], v[100:103]
	v_mfma_f32_16x16x32_bf16 v[96:99], v[190:193], v[214:217], v[96:99]
	v_mfma_f32_16x16x32_bf16 v[80:83], v[182:185], v[222:225], v[80:83]
	v_mfma_f32_16x16x32_bf16 v[76:79], v[190:193], v[222:225], v[76:79]
	v_mfma_f32_16x16x32_bf16 v[68:71], v[182:185], v[230:233], v[68:71]
	v_mfma_f32_16x16x32_bf16 v[64:67], v[190:193], v[230:233], v[64:67]
	s_setprio 0
	s_barrier
	s_add_u32 s34, s30, 0x8000
	s_addc_u32 s35, s31, 0
	s_add_i32 s57, s57, s42
	s_mov_b32 m0, s57
	ds_read_b128 v[194:197], v172 offset:49152
	ds_read_b128 v[198:201], v172 offset:50176
	ds_read_b128 v[210:213], v172 offset:51200
	ds_read_b128 v[214:217], v172 offset:52224
	ds_read_b128 v[218:221], v172 offset:53248
	ds_read_b128 v[222:225], v172 offset:54272
	ds_read_b128 v[226:229], v172 offset:55296
	ds_read_b128 v[230:233], v172 offset:56320
	global_load_lds_dwordx4 v134, s[34:35]
	s_add_i32 m0, s57, 0x2000
	s_add_u32 s30, s30, 0xc000
	v_lshl_add_u64 v[238:239], s[34:35], 0, v[138:139]
	s_addc_u32 s31, s31, 0
	s_add_i32 s34, s58, s42
	global_load_lds_dwordx4 v[238:239], off
	s_mov_b32 m0, s34
	v_lshl_add_u64 v[234:235], v[234:235], 0, s[12:13]
	global_load_lds_dwordx4 v134, s[30:31]
	s_add_i32 m0, s34, 0x2000
	s_nop 0
	global_load_lds_dwordx4 v138, s[30:31]
	s_mov_b32 m0, s46
	s_nop 0
	global_load_lds_dwordx4 v[234:235], off
	v_lshl_add_u64 v[234:235], v[236:237], 0, s[12:13]
	s_mov_b32 m0, s47
	s_nop 0
	global_load_lds_dwordx4 v[234:235], off
	s_waitcnt vmcnt(8)
	s_waitcnt lgkmcnt(0)
	s_barrier
	s_setprio 1
	s_waitcnt lgkmcnt(0)
	v_mfma_f32_16x16x32_bf16 v[60:63], v[128:131], v[194:197], v[60:63]
	v_mfma_f32_16x16x32_bf16 v[56:59], v[152:155], v[194:197], v[56:59]
	v_mfma_f32_16x16x32_bf16 v[48:51], v[128:131], v[210:213], v[48:51]
	v_mfma_f32_16x16x32_bf16 v[40:43], v[152:155], v[210:213], v[40:43]
	v_mfma_f32_16x16x32_bf16 v[32:35], v[128:131], v[218:221], v[32:35]
	v_mfma_f32_16x16x32_bf16 v[24:27], v[152:155], v[218:221], v[24:27]
	v_mfma_f32_16x16x32_bf16 v[16:19], v[128:131], v[226:229], v[16:19]
	v_mfma_f32_16x16x32_bf16 v[8:11], v[152:155], v[226:229], v[8:11]
	v_mfma_f32_16x16x32_bf16 v[60:63], v[148:151], v[198:201], v[60:63]
	v_mfma_f32_16x16x32_bf16 v[56:59], v[174:177], v[198:201], v[56:59]
	v_mfma_f32_16x16x32_bf16 v[48:51], v[148:151], v[214:217], v[48:51]
	v_mfma_f32_16x16x32_bf16 v[40:43], v[174:177], v[214:217], v[40:43]
	v_mfma_f32_16x16x32_bf16 v[32:35], v[148:151], v[222:225], v[32:35]
	v_mfma_f32_16x16x32_bf16 v[24:27], v[174:177], v[222:225], v[24:27]
	v_mfma_f32_16x16x32_bf16 v[16:19], v[148:151], v[230:233], v[16:19]
	v_mfma_f32_16x16x32_bf16 v[8:11], v[174:177], v[230:233], v[8:11]
	v_mfma_f32_16x16x32_bf16 v[52:55], v[178:181], v[194:197], v[52:55]
	v_mfma_f32_16x16x32_bf16 v[44:47], v[186:189], v[194:197], v[44:47]
	v_mfma_f32_16x16x32_bf16 v[36:39], v[178:181], v[210:213], v[36:39]
	v_mfma_f32_16x16x32_bf16 v[28:31], v[186:189], v[210:213], v[28:31]
	v_mfma_f32_16x16x32_bf16 v[20:23], v[178:181], v[218:221], v[20:23]
	v_mfma_f32_16x16x32_bf16 v[12:15], v[186:189], v[218:221], v[12:15]
	v_mfma_f32_16x16x32_bf16 v[4:7], v[178:181], v[226:229], v[4:7]
	v_mfma_f32_16x16x32_bf16 v[0:3], v[186:189], v[226:229], v[0:3]
	v_mfma_f32_16x16x32_bf16 v[52:55], v[182:185], v[198:201], v[52:55]
	v_mfma_f32_16x16x32_bf16 v[44:47], v[190:193], v[198:201], v[44:47]
	v_mfma_f32_16x16x32_bf16 v[36:39], v[182:185], v[214:217], v[36:39]
	v_mfma_f32_16x16x32_bf16 v[28:31], v[190:193], v[214:217], v[28:31]
	v_mfma_f32_16x16x32_bf16 v[20:23], v[182:185], v[222:225], v[20:23]
	v_mfma_f32_16x16x32_bf16 v[12:15], v[190:193], v[222:225], v[12:15]
	v_mfma_f32_16x16x32_bf16 v[4:7], v[182:185], v[230:233], v[4:7]
	v_mfma_f32_16x16x32_bf16 v[0:3], v[190:193], v[230:233], v[0:3]
	s_setprio 0
	s_barrier
	s_add_i32 s56, s56, 2
	s_add_u32 s54, s54, 0x10000
	s_addc_u32 s55, s55, 0
	s_add_u32 s28, s28, 0x100
	s_addc_u32 s29, s29, 0
	s_cmp_gt_u32 s56, 5
	s_cbranch_scc0 .LBB0_1071
	s_and_b64 vcc, exec, s[14:15]
	s_cbranch_vccz .LBB0_1074
	s_barrier

.LBB0_1095:
	ds_read_b128 v[144:147], v155
	ds_read_b128 v[148:151], v155 offset:1024
	ds_read_b128 v[158:161], v155 offset:2048
	ds_read_b128 v[162:165], v155 offset:3072
	ds_read_b128 v[166:169], v156
	ds_read_b128 v[170:173], v156 offset:1024
	ds_read_b128 v[174:177], v156 offset:2048
	ds_read_b128 v[178:181], v156 offset:3072
	s_add_u32 s28, s26, 0xfffe0080
	s_addc_u32 s29, s27, -1
	s_cmp_eq_u32 s54, 4
	s_cselect_b32 s31, s15, s29
	s_cselect_b32 s30, s50, s28
	s_cselect_b32 s29, s17, s53
	s_cselect_b32 s28, s51, s52
	s_add_i32 m0, s23, 0xc000
	ds_read_b128 v[182:185], v157
	ds_read_b128 v[186:189], v157 offset:1024
	ds_read_b128 v[190:193], v157 offset:2048
	ds_read_b128 v[194:197], v157 offset:3072
	ds_read_b128 v[198:201], v157 offset:4096
	ds_read_b128 v[210:213], v157 offset:5120
	ds_read_b128 v[214:217], v157 offset:6144
	ds_read_b128 v[218:221], v157 offset:7168
	global_load_lds_dwordx4 v130, s[26:27]
	s_add_i32 m0, s23, 0xe000
	s_nop 0
	global_load_lds_dwordx4 v128, s[26:27]
	s_waitcnt vmcnt(8)
	s_waitcnt lgkmcnt(0)
	s_barrier
	s_setprio 1
	s_waitcnt lgkmcnt(0)
	v_mfma_f32_16x16x32_bf16 v[124:127], v[144:147], v[182:185], v[124:127]
	v_mfma_f32_16x16x32_bf16 v[120:123], v[158:161], v[182:185], v[120:123]
	v_mfma_f32_16x16x32_bf16 v[112:115], v[144:147], v[190:193], v[112:115]
	v_mfma_f32_16x16x32_bf16 v[104:107], v[158:161], v[190:193], v[104:107]
	v_mfma_f32_16x16x32_bf16 v[92:95], v[144:147], v[198:201], v[92:95]
	v_mfma_f32_16x16x32_bf16 v[88:91], v[158:161], v[198:201], v[88:91]
	v_mfma_f32_16x16x32_bf16 v[80:83], v[144:147], v[214:217], v[80:83]
	v_mfma_f32_16x16x32_bf16 v[72:75], v[158:161], v[214:217], v[72:75]
	v_mfma_f32_16x16x32_bf16 v[124:127], v[148:151], v[186:189], v[124:127]
	v_mfma_f32_16x16x32_bf16 v[120:123], v[162:165], v[186:189], v[120:123]
	v_mfma_f32_16x16x32_bf16 v[112:115], v[148:151], v[194:197], v[112:115]
	v_mfma_f32_16x16x32_bf16 v[104:107], v[162:165], v[194:197], v[104:107]
	v_mfma_f32_16x16x32_bf16 v[92:95], v[148:151], v[210:213], v[92:95]
	v_mfma_f32_16x16x32_bf16 v[88:91], v[162:165], v[210:213], v[88:91]
	v_mfma_f32_16x16x32_bf16 v[80:83], v[148:151], v[218:221], v[80:83]
	v_mfma_f32_16x16x32_bf16 v[72:75], v[162:165], v[218:221], v[72:75]
	v_mfma_f32_16x16x32_bf16 v[116:119], v[166:169], v[182:185], v[116:119]
	v_mfma_f32_16x16x32_bf16 v[108:111], v[174:177], v[182:185], v[108:111]
	v_mfma_f32_16x16x32_bf16 v[100:103], v[166:169], v[190:193], v[100:103]
	v_mfma_f32_16x16x32_bf16 v[96:99], v[174:177], v[190:193], v[96:99]
	v_mfma_f32_16x16x32_bf16 v[84:87], v[166:169], v[198:201], v[84:87]
	v_mfma_f32_16x16x32_bf16 v[76:79], v[174:177], v[198:201], v[76:79]
	v_mfma_f32_16x16x32_bf16 v[68:71], v[166:169], v[214:217], v[68:71]
	v_mfma_f32_16x16x32_bf16 v[64:67], v[174:177], v[214:217], v[64:67]
	v_mfma_f32_16x16x32_bf16 v[116:119], v[170:173], v[186:189], v[116:119]
	v_mfma_f32_16x16x32_bf16 v[108:111], v[178:181], v[186:189], v[108:111]
	v_mfma_f32_16x16x32_bf16 v[100:103], v[170:173], v[194:197], v[100:103]
	v_mfma_f32_16x16x32_bf16 v[96:99], v[178:181], v[194:197], v[96:99]
	v_mfma_f32_16x16x32_bf16 v[84:87], v[170:173], v[210:213], v[84:87]
	v_mfma_f32_16x16x32_bf16 v[76:79], v[178:181], v[210:213], v[76:79]
	v_mfma_f32_16x16x32_bf16 v[68:71], v[170:173], v[218:221], v[68:71]
	v_mfma_f32_16x16x32_bf16 v[64:67], v[178:181], v[218:221], v[64:67]
	s_setprio 0
	s_barrier
	s_add_i32 s55, s47, s40
	s_mov_b32 m0, s55
	ds_read_b128 v[182:185], v157 offset:16384
	ds_read_b128 v[186:189], v157 offset:17408
	ds_read_b128 v[190:193], v157 offset:18432
	ds_read_b128 v[194:197], v157 offset:19456
	ds_read_b128 v[198:201], v157 offset:20480
	ds_read_b128 v[210:213], v157 offset:21504
	ds_read_b128 v[214:217], v157 offset:22528
	ds_read_b128 v[218:221], v157 offset:23552
	global_load_lds_dwordx4 v134, s[28:29]
	s_add_i32 m0, s55, 0x2000
	s_add_u32 s56, s28, 0x4000
	s_addc_u32 s57, s29, 0
	s_add_i32 s55, s48, s40
	global_load_lds_dwordx4 v138, s[28:29]
	s_mov_b32 m0, s55
	v_lshl_add_u64 v[224:225], s[30:31], 0, v[136:137]
	global_load_lds_dwordx4 v134, s[56:57]
	s_add_i32 m0, s55, 0x2000
	s_nop 0
	global_load_lds_dwordx4 v138, s[56:57]
	v_lshl_add_u64 v[222:223], s[30:31], 0, v[132:133]
	s_mov_b32 m0, s23
	s_nop 0
	global_load_lds_dwordx4 v[222:223], off
	s_mov_b32 m0, s25
	s_nop 0
	global_load_lds_dwordx4 v[224:225], off
	s_waitcnt vmcnt(8)
	s_waitcnt lgkmcnt(0)
	s_barrier
	s_setprio 1
	s_waitcnt lgkmcnt(0)
	v_mfma_f32_16x16x32_bf16 v[60:63], v[144:147], v[182:185], v[60:63]
	v_mfma_f32_16x16x32_bf16 v[56:59], v[158:161], v[182:185], v[56:59]
	v_mfma_f32_16x16x32_bf16 v[48:51], v[144:147], v[190:193], v[48:51]
	v_mfma_f32_16x16x32_bf16 v[40:43], v[158:161], v[190:193], v[40:43]
	v_mfma_f32_16x16x32_bf16 v[28:31], v[144:147], v[198:201], v[28:31]
	v_mfma_f32_16x16x32_bf16 v[24:27], v[158:161], v[198:201], v[24:27]
	v_mfma_f32_16x16x32_bf16 v[16:19], v[144:147], v[214:217], v[16:19]
	v_mfma_f32_16x16x32_bf16 v[8:11], v[158:161], v[214:217], v[8:11]
	v_mfma_f32_16x16x32_bf16 v[60:63], v[148:151], v[186:189], v[60:63]
	v_mfma_f32_16x16x32_bf16 v[56:59], v[162:165], v[186:189], v[56:59]
	v_mfma_f32_16x16x32_bf16 v[48:51], v[148:151], v[194:197], v[48:51]
	v_mfma_f32_16x16x32_bf16 v[40:43], v[162:165], v[194:197], v[40:43]
	v_mfma_f32_16x16x32_bf16 v[28:31], v[148:151], v[210:213], v[28:31]
	v_mfma_f32_16x16x32_bf16 v[24:27], v[162:165], v[210:213], v[24:27]
	v_mfma_f32_16x16x32_bf16 v[16:19], v[148:151], v[218:221], v[16:19]
	v_mfma_f32_16x16x32_bf16 v[8:11], v[162:165], v[218:221], v[8:11]
	v_mfma_f32_16x16x32_bf16 v[52:55], v[166:169], v[182:185], v[52:55]
	v_mfma_f32_16x16x32_bf16 v[44:47], v[174:177], v[182:185], v[44:47]
	v_mfma_f32_16x16x32_bf16 v[36:39], v[166:169], v[190:193], v[36:39]
	v_mfma_f32_16x16x32_bf16 v[32:35], v[174:177], v[190:193], v[32:35]
	v_mfma_f32_16x16x32_bf16 v[20:23], v[166:169], v[198:201], v[20:23]
	v_mfma_f32_16x16x32_bf16 v[12:15], v[174:177], v[198:201], v[12:15]
	v_mfma_f32_16x16x32_bf16 v[4:7], v[166:169], v[214:217], v[4:7]
	v_mfma_f32_16x16x32_bf16 v[0:3], v[174:177], v[214:217], v[0:3]
	v_mfma_f32_16x16x32_bf16 v[52:55], v[170:173], v[186:189], v[52:55]
	v_mfma_f32_16x16x32_bf16 v[44:47], v[178:181], v[186:189], v[44:47]
	v_mfma_f32_16x16x32_bf16 v[36:39], v[170:173], v[194:197], v[36:39]
	v_mfma_f32_16x16x32_bf16 v[32:35], v[178:181], v[194:197], v[32:35]
	v_mfma_f32_16x16x32_bf16 v[20:23], v[170:173], v[210:213], v[20:23]
	v_mfma_f32_16x16x32_bf16 v[12:15], v[178:181], v[210:213], v[12:15]
	v_mfma_f32_16x16x32_bf16 v[4:7], v[170:173], v[218:221], v[4:7]
	v_mfma_f32_16x16x32_bf16 v[0:3], v[178:181], v[218:221], v[0:3]
	s_setprio 0
	s_barrier
	s_add_i32 s55, 0, 0x18000
	s_add_i32 s56, 0, 0x1c000
	v_add_u32_e32 v162, s55, v153
	v_add_u32_e32 v178, s56, v153
	ds_read_b128 v[144:147], v162
	ds_read_b128 v[148:151], v162 offset:1024
	ds_read_b128 v[158:161], v162 offset:2048
	ds_read_b128 v[162:165], v162 offset:3072
	ds_read_b128 v[166:169], v178
	ds_read_b128 v[170:173], v178 offset:1024
	ds_read_b128 v[174:177], v178 offset:2048
	ds_read_b128 v[178:181], v178 offset:3072
	s_add_u32 s30, s30, 0x20000
	s_addc_u32 s31, s31, 0
	s_mov_b32 m0, s41
	ds_read_b128 v[182:185], v157 offset:32768
	ds_read_b128 v[186:189], v157 offset:33792
	ds_read_b128 v[190:193], v157 offset:34816
	ds_read_b128 v[194:197], v157 offset:35840
	ds_read_b128 v[198:201], v157 offset:36864
	ds_read_b128 v[210:213], v157 offset:37888
	ds_read_b128 v[214:217], v157 offset:38912
	ds_read_b128 v[218:221], v157 offset:39936
	global_load_lds_dwordx4 v132, s[30:31]
	s_mov_b32 m0, s42
	s_nop 0
	global_load_lds_dwordx4 v136, s[30:31]
	s_waitcnt vmcnt(8)
	s_waitcnt lgkmcnt(0)
	s_barrier
	s_setprio 1
	s_waitcnt lgkmcnt(0)
	v_mfma_f32_16x16x32_bf16 v[124:127], v[144:147], v[182:185], v[124:127]
	v_mfma_f32_16x16x32_bf16 v[120:123], v[158:161], v[182:185], v[120:123]
	v_mfma_f32_16x16x32_bf16 v[112:115], v[144:147], v[190:193], v[112:115]
	v_mfma_f32_16x16x32_bf16 v[104:107], v[158:161], v[190:193], v[104:107]
	v_mfma_f32_16x16x32_bf16 v[92:95], v[144:147], v[198:201], v[92:95]
	v_mfma_f32_16x16x32_bf16 v[88:91], v[158:161], v[198:201], v[88:91]
	v_mfma_f32_16x16x32_bf16 v[80:83], v[144:147], v[214:217], v[80:83]
	v_mfma_f32_16x16x32_bf16 v[72:75], v[158:161], v[214:217], v[72:75]
	v_mfma_f32_16x16x32_bf16 v[124:127], v[148:151], v[186:189], v[124:127]
	v_mfma_f32_16x16x32_bf16 v[120:123], v[162:165], v[186:189], v[120:123]
	v_mfma_f32_16x16x32_bf16 v[112:115], v[148:151], v[194:197], v[112:115]
	v_mfma_f32_16x16x32_bf16 v[104:107], v[162:165], v[194:197], v[104:107]
	v_mfma_f32_16x16x32_bf16 v[92:95], v[148:151], v[210:213], v[92:95]
	v_mfma_f32_16x16x32_bf16 v[88:91], v[162:165], v[210:213], v[88:91]
	v_mfma_f32_16x16x32_bf16 v[80:83], v[148:151], v[218:221], v[80:83]
	v_mfma_f32_16x16x32_bf16 v[72:75], v[162:165], v[218:221], v[72:75]
	v_mfma_f32_16x16x32_bf16 v[116:119], v[166:169], v[182:185], v[116:119]
	v_mfma_f32_16x16x32_bf16 v[108:111], v[174:177], v[182:185], v[108:111]
	v_mfma_f32_16x16x32_bf16 v[100:103], v[166:169], v[190:193], v[100:103]
	v_mfma_f32_16x16x32_bf16 v[96:99], v[174:177], v[190:193], v[96:99]
	v_mfma_f32_16x16x32_bf16 v[84:87], v[166:169], v[198:201], v[84:87]
	v_mfma_f32_16x16x32_bf16 v[76:79], v[174:177], v[198:201], v[76:79]
	v_mfma_f32_16x16x32_bf16 v[68:71], v[166:169], v[214:217], v[68:71]
	v_mfma_f32_16x16x32_bf16 v[64:67], v[174:177], v[214:217], v[64:67]
	v_mfma_f32_16x16x32_bf16 v[116:119], v[170:173], v[186:189], v[116:119]
	v_mfma_f32_16x16x32_bf16 v[108:111], v[178:181], v[186:189], v[108:111]
	v_mfma_f32_16x16x32_bf16 v[100:103], v[170:173], v[194:197], v[100:103]
	v_mfma_f32_16x16x32_bf16 v[96:99], v[178:181], v[194:197], v[96:99]
	v_mfma_f32_16x16x32_bf16 v[84:87], v[170:173], v[210:213], v[84:87]
	v_mfma_f32_16x16x32_bf16 v[76:79], v[178:181], v[210:213], v[76:79]
	v_mfma_f32_16x16x32_bf16 v[68:71], v[170:173], v[218:221], v[68:71]
	v_mfma_f32_16x16x32_bf16 v[64:67], v[178:181], v[218:221], v[64:67]
	s_setprio 0
	s_barrier
	s_add_u32 s30, s28, 0x8000
	s_addc_u32 s31, s29, 0
	s_add_i32 s55, s55, s40
	s_mov_b32 m0, s55
	ds_read_b128 v[182:185], v157 offset:49152
	ds_read_b128 v[186:189], v157 offset:50176
	ds_read_b128 v[190:193], v157 offset:51200
	ds_read_b128 v[194:197], v157 offset:52224
	ds_read_b128 v[198:201], v157 offset:53248
	ds_read_b128 v[210:213], v157 offset:54272
	ds_read_b128 v[214:217], v157 offset:55296
	ds_read_b128 v[218:221], v157 offset:56320
	global_load_lds_dwordx4 v134, s[30:31]
	s_add_i32 m0, s55, 0x2000
	s_add_u32 s28, s28, 0xc000
	v_lshl_add_u64 v[226:227], s[30:31], 0, v[138:139]
	s_addc_u32 s29, s29, 0
	s_add_i32 s30, s56, s40
	global_load_lds_dwordx4 v[226:227], off
	s_mov_b32 m0, s30
	v_lshl_add_u64 v[222:223], v[222:223], 0, s[8:9]
	global_load_lds_dwordx4 v134, s[28:29]
	s_add_i32 m0, s30, 0x2000
	s_nop 0
	global_load_lds_dwordx4 v138, s[28:29]
	s_mov_b32 m0, s44
	s_nop 0
	global_load_lds_dwordx4 v[222:223], off
	v_lshl_add_u64 v[222:223], v[224:225], 0, s[8:9]
	s_mov_b32 m0, s45
	s_nop 0
	global_load_lds_dwordx4 v[222:223], off
	s_waitcnt vmcnt(8)
	s_waitcnt lgkmcnt(0)
	s_barrier
	s_setprio 1
	s_waitcnt lgkmcnt(0)
	v_mfma_f32_16x16x32_bf16 v[60:63], v[144:147], v[182:185], v[60:63]
	v_mfma_f32_16x16x32_bf16 v[56:59], v[158:161], v[182:185], v[56:59]
	v_mfma_f32_16x16x32_bf16 v[48:51], v[144:147], v[190:193], v[48:51]
	v_mfma_f32_16x16x32_bf16 v[40:43], v[158:161], v[190:193], v[40:43]
	v_mfma_f32_16x16x32_bf16 v[28:31], v[144:147], v[198:201], v[28:31]
	v_mfma_f32_16x16x32_bf16 v[24:27], v[158:161], v[198:201], v[24:27]
	v_mfma_f32_16x16x32_bf16 v[16:19], v[144:147], v[214:217], v[16:19]
	v_mfma_f32_16x16x32_bf16 v[8:11], v[158:161], v[214:217], v[8:11]
	v_mfma_f32_16x16x32_bf16 v[60:63], v[148:151], v[186:189], v[60:63]
	v_mfma_f32_16x16x32_bf16 v[56:59], v[162:165], v[186:189], v[56:59]
	v_mfma_f32_16x16x32_bf16 v[48:51], v[148:151], v[194:197], v[48:51]
	v_mfma_f32_16x16x32_bf16 v[40:43], v[162:165], v[194:197], v[40:43]
	v_mfma_f32_16x16x32_bf16 v[28:31], v[148:151], v[210:213], v[28:31]
	v_mfma_f32_16x16x32_bf16 v[24:27], v[162:165], v[210:213], v[24:27]
	v_mfma_f32_16x16x32_bf16 v[16:19], v[148:151], v[218:221], v[16:19]
	v_mfma_f32_16x16x32_bf16 v[8:11], v[162:165], v[218:221], v[8:11]
	v_mfma_f32_16x16x32_bf16 v[52:55], v[166:169], v[182:185], v[52:55]
	v_mfma_f32_16x16x32_bf16 v[44:47], v[174:177], v[182:185], v[44:47]
	v_mfma_f32_16x16x32_bf16 v[36:39], v[166:169], v[190:193], v[36:39]
	v_mfma_f32_16x16x32_bf16 v[32:35], v[174:177], v[190:193], v[32:35]
	v_mfma_f32_16x16x32_bf16 v[20:23], v[166:169], v[198:201], v[20:23]
	v_mfma_f32_16x16x32_bf16 v[12:15], v[174:177], v[198:201], v[12:15]
	v_mfma_f32_16x16x32_bf16 v[4:7], v[166:169], v[214:217], v[4:7]
	v_mfma_f32_16x16x32_bf16 v[0:3], v[174:177], v[214:217], v[0:3]
	v_mfma_f32_16x16x32_bf16 v[52:55], v[170:173], v[186:189], v[52:55]
	v_mfma_f32_16x16x32_bf16 v[44:47], v[178:181], v[186:189], v[44:47]
	v_mfma_f32_16x16x32_bf16 v[36:39], v[170:173], v[194:197], v[36:39]
	v_mfma_f32_16x16x32_bf16 v[32:35], v[178:181], v[194:197], v[32:35]
	v_mfma_f32_16x16x32_bf16 v[20:23], v[170:173], v[210:213], v[20:23]
	v_mfma_f32_16x16x32_bf16 v[12:15], v[178:181], v[210:213], v[12:15]
	v_mfma_f32_16x16x32_bf16 v[4:7], v[170:173], v[218:221], v[4:7]
	v_mfma_f32_16x16x32_bf16 v[0:3], v[178:181], v[218:221], v[0:3]
	s_setprio 0
	s_barrier
	s_add_i32 s54, s54, 2
	s_add_u32 s52, s52, 0x10000
	s_addc_u32 s53, s53, 0
	s_add_u32 s26, s26, 0x100
	s_addc_u32 s27, s27, 0
	s_cmp_gt_u32 s54, 5
	s_cbranch_scc0 .LBB0_1095
	s_and_b64 vcc, exec, s[10:11]
	s_cbranch_vccz .LBB0_1098
	s_barrier

.LBB0_1171:
	v_add_u32_e32 v168, s77, v182
	v_add_u32_e32 v204, s78, v182
	ds_read_b128 v[156:159], v168
	ds_read_b128 v[160:163], v168 offset:1024
	ds_read_b128 v[164:167], v168 offset:2048
	ds_read_b128 v[168:171], v168 offset:3072
	ds_read_b128 v[172:175], v204
	ds_read_b128 v[176:179], v204 offset:1024
	ds_read_b128 v[212:215], v204 offset:2048
	ds_read_b128 v[216:219], v204 offset:3072
	s_add_u32 s48, s46, 0xfffc0080
	s_addc_u32 s49, s47, -1
	s_cmp_eq_u32 s54, 12
	s_cselect_b32 s51, s35, s49
	s_cselect_b32 s50, s43, s48
	s_cselect_b32 s49, s37, s53
	s_cselect_b32 s48, s45, s52
	s_add_i32 m0, s65, 0xc000
	ds_read_b128 v[220:223], v199
	ds_read_b128 v[224:227], v199 offset:1024
	ds_read_b128 v[228:231], v199 offset:2048
	ds_read_b128 v[232:235], v199 offset:3072
	ds_read_b128 v[236:239], v199 offset:4096
	ds_read_b128 v[240:243], v199 offset:5120
	ds_read_b128 v[244:247], v199 offset:6144
	ds_read_b128 v[248:251], v199 offset:7168
	global_load_lds_dwordx4 v154, s[46:47]
	s_add_i32 m0, s65, 0xe000
	s_nop 0
	global_load_lds_dwordx4 v152, s[46:47]
	s_waitcnt vmcnt(8)
	s_waitcnt lgkmcnt(0)
	s_barrier
	s_setprio 1
	s_waitcnt lgkmcnt(0)
	v_mfma_f32_16x16x32_bf16 v[124:127], v[156:159], v[220:223], v[124:127]
	v_mfma_f32_16x16x32_bf16 v[120:123], v[164:167], v[220:223], v[120:123]
	v_mfma_f32_16x16x32_bf16 v[116:119], v[156:159], v[228:231], v[116:119]
	v_mfma_f32_16x16x32_bf16 v[112:115], v[164:167], v[228:231], v[112:115]
	v_mfma_f32_16x16x32_bf16 v[92:95], v[156:159], v[236:239], v[92:95]
	v_mfma_f32_16x16x32_bf16 v[88:91], v[164:167], v[236:239], v[88:91]
	v_mfma_f32_16x16x32_bf16 v[84:87], v[156:159], v[244:247], v[84:87]
	v_mfma_f32_16x16x32_bf16 v[80:83], v[164:167], v[244:247], v[80:83]
	v_mfma_f32_16x16x32_bf16 v[124:127], v[160:163], v[224:227], v[124:127]
	v_mfma_f32_16x16x32_bf16 v[120:123], v[168:171], v[224:227], v[120:123]
	v_mfma_f32_16x16x32_bf16 v[116:119], v[160:163], v[232:235], v[116:119]
	v_mfma_f32_16x16x32_bf16 v[112:115], v[168:171], v[232:235], v[112:115]
	v_mfma_f32_16x16x32_bf16 v[92:95], v[160:163], v[240:243], v[92:95]
	v_mfma_f32_16x16x32_bf16 v[88:91], v[168:171], v[240:243], v[88:91]
	v_mfma_f32_16x16x32_bf16 v[84:87], v[160:163], v[248:251], v[84:87]
	v_mfma_f32_16x16x32_bf16 v[80:83], v[168:171], v[248:251], v[80:83]
	v_mfma_f32_16x16x32_bf16 v[108:111], v[172:175], v[220:223], v[108:111]
	v_mfma_f32_16x16x32_bf16 v[104:107], v[212:215], v[220:223], v[104:107]
	v_mfma_f32_16x16x32_bf16 v[100:103], v[172:175], v[228:231], v[100:103]
	v_mfma_f32_16x16x32_bf16 v[96:99], v[212:215], v[228:231], v[96:99]
	v_mfma_f32_16x16x32_bf16 v[76:79], v[172:175], v[236:239], v[76:79]
	v_mfma_f32_16x16x32_bf16 v[72:75], v[212:215], v[236:239], v[72:75]
	v_mfma_f32_16x16x32_bf16 v[68:71], v[172:175], v[244:247], v[68:71]
	v_mfma_f32_16x16x32_bf16 v[64:67], v[212:215], v[244:247], v[64:67]
	v_mfma_f32_16x16x32_bf16 v[108:111], v[176:179], v[224:227], v[108:111]
	v_mfma_f32_16x16x32_bf16 v[104:107], v[216:219], v[224:227], v[104:107]
	v_mfma_f32_16x16x32_bf16 v[100:103], v[176:179], v[232:235], v[100:103]
	v_mfma_f32_16x16x32_bf16 v[96:99], v[216:219], v[232:235], v[96:99]
	v_mfma_f32_16x16x32_bf16 v[76:79], v[176:179], v[240:243], v[76:79]
	v_mfma_f32_16x16x32_bf16 v[72:75], v[216:219], v[240:243], v[72:75]
	v_mfma_f32_16x16x32_bf16 v[68:71], v[176:179], v[248:251], v[68:71]
	v_mfma_f32_16x16x32_bf16 v[64:67], v[216:219], v[248:251], v[64:67]
	s_setprio 0
	s_barrier
	s_add_i32 s55, s77, s64
	s_mov_b32 m0, s55
	ds_read_b128 v[220:223], v199 offset:16384
	ds_read_b128 v[224:227], v199 offset:17408
	ds_read_b128 v[228:231], v199 offset:18432
	ds_read_b128 v[232:235], v199 offset:19456
	ds_read_b128 v[236:239], v199 offset:20480
	ds_read_b128 v[240:243], v199 offset:21504
	ds_read_b128 v[244:247], v199 offset:22528
	ds_read_b128 v[248:251], v199 offset:23552
	global_load_lds_dwordx4 v130, s[48:49]
	s_add_i32 m0, s55, 0x2000
	s_add_u32 s56, s48, 0x4000
	s_addc_u32 s57, s49, 0
	s_add_i32 s55, s78, s64
	global_load_lds_dwordx4 v134, s[48:49]
	s_mov_b32 m0, s55
	v_lshl_add_u64 v[204:205], s[50:51], 0, v[132:133]
	global_load_lds_dwordx4 v130, s[56:57]
	s_add_i32 m0, s55, 0x2000
	s_nop 0
	global_load_lds_dwordx4 v134, s[56:57]
	v_lshl_add_u64 v[252:253], s[50:51], 0, v[128:129]
	s_mov_b32 m0, s65
	s_nop 0
	global_load_lds_dwordx4 v[252:253], off
	s_mov_b32 m0, s66
	s_nop 0
	global_load_lds_dwordx4 v[204:205], off
	s_waitcnt vmcnt(8)
	s_waitcnt lgkmcnt(0)
	s_barrier
	s_setprio 1
	s_waitcnt lgkmcnt(0)
	v_mfma_f32_16x16x32_bf16 v[60:63], v[156:159], v[220:223], v[60:63]
	v_mfma_f32_16x16x32_bf16 v[56:59], v[164:167], v[220:223], v[56:59]
	v_mfma_f32_16x16x32_bf16 v[52:55], v[156:159], v[228:231], v[52:55]
	v_mfma_f32_16x16x32_bf16 v[48:51], v[164:167], v[228:231], v[48:51]
	v_mfma_f32_16x16x32_bf16 v[28:31], v[156:159], v[236:239], v[28:31]
	v_mfma_f32_16x16x32_bf16 v[24:27], v[164:167], v[236:239], v[24:27]
	v_mfma_f32_16x16x32_bf16 v[20:23], v[156:159], v[244:247], v[20:23]
	v_mfma_f32_16x16x32_bf16 v[12:15], v[164:167], v[244:247], v[12:15]
	v_mfma_f32_16x16x32_bf16 v[60:63], v[160:163], v[224:227], v[60:63]
	v_mfma_f32_16x16x32_bf16 v[56:59], v[168:171], v[224:227], v[56:59]
	v_mfma_f32_16x16x32_bf16 v[52:55], v[160:163], v[232:235], v[52:55]
	v_mfma_f32_16x16x32_bf16 v[48:51], v[168:171], v[232:235], v[48:51]
	v_mfma_f32_16x16x32_bf16 v[28:31], v[160:163], v[240:243], v[28:31]
	v_mfma_f32_16x16x32_bf16 v[24:27], v[168:171], v[240:243], v[24:27]
	v_mfma_f32_16x16x32_bf16 v[20:23], v[160:163], v[248:251], v[20:23]
	v_mfma_f32_16x16x32_bf16 v[12:15], v[168:171], v[248:251], v[12:15]
	v_mfma_f32_16x16x32_bf16 v[44:47], v[172:175], v[220:223], v[44:47]
	v_mfma_f32_16x16x32_bf16 v[40:43], v[212:215], v[220:223], v[40:43]
	v_mfma_f32_16x16x32_bf16 v[36:39], v[172:175], v[228:231], v[36:39]
	v_mfma_f32_16x16x32_bf16 v[32:35], v[212:215], v[228:231], v[32:35]
	v_mfma_f32_16x16x32_bf16 v[16:19], v[172:175], v[236:239], v[16:19]
	v_mfma_f32_16x16x32_bf16 v[8:11], v[212:215], v[236:239], v[8:11]
	v_mfma_f32_16x16x32_bf16 v[4:7], v[172:175], v[244:247], v[4:7]
	v_mfma_f32_16x16x32_bf16 v[0:3], v[212:215], v[244:247], v[0:3]
	v_mfma_f32_16x16x32_bf16 v[44:47], v[176:179], v[224:227], v[44:47]
	v_mfma_f32_16x16x32_bf16 v[40:43], v[216:219], v[224:227], v[40:43]
	v_mfma_f32_16x16x32_bf16 v[36:39], v[176:179], v[232:235], v[36:39]
	v_mfma_f32_16x16x32_bf16 v[32:35], v[216:219], v[232:235], v[32:35]
	v_mfma_f32_16x16x32_bf16 v[16:19], v[176:179], v[240:243], v[16:19]
	v_mfma_f32_16x16x32_bf16 v[8:11], v[216:219], v[240:243], v[8:11]
	v_mfma_f32_16x16x32_bf16 v[4:7], v[176:179], v[248:251], v[4:7]
	v_mfma_f32_16x16x32_bf16 v[0:3], v[216:219], v[248:251], v[0:3]
	s_setprio 0
	s_barrier
	s_add_i32 s55, 0, 0x18000
	s_add_i32 s56, 0, 0x1c000
	v_add_u32_e32 v168, s55, v182
	v_add_u32_e32 v206, s56, v182
	ds_read_b128 v[156:159], v168
	ds_read_b128 v[160:163], v168 offset:1024
	ds_read_b128 v[164:167], v168 offset:2048
	ds_read_b128 v[168:171], v168 offset:3072
	ds_read_b128 v[172:175], v206
	ds_read_b128 v[176:179], v206 offset:1024
	ds_read_b128 v[212:215], v206 offset:2048
	ds_read_b128 v[216:219], v206 offset:3072
	s_add_u32 s50, s50, 0x40000
	s_addc_u32 s51, s51, 0
	s_mov_b32 m0, s67
	ds_read_b128 v[220:223], v199 offset:32768
	ds_read_b128 v[224:227], v199 offset:33792
	ds_read_b128 v[228:231], v199 offset:34816
	ds_read_b128 v[232:235], v199 offset:35840
	ds_read_b128 v[236:239], v199 offset:36864
	ds_read_b128 v[240:243], v199 offset:37888
	ds_read_b128 v[244:247], v199 offset:38912
	ds_read_b128 v[248:251], v199 offset:39936
	global_load_lds_dwordx4 v128, s[50:51]
	s_mov_b32 m0, s68
	s_nop 0
	global_load_lds_dwordx4 v132, s[50:51]
	s_waitcnt vmcnt(8)
	s_waitcnt lgkmcnt(0)
	s_barrier
	s_setprio 1
	s_waitcnt lgkmcnt(0)
	v_mfma_f32_16x16x32_bf16 v[124:127], v[156:159], v[220:223], v[124:127]
	v_mfma_f32_16x16x32_bf16 v[120:123], v[164:167], v[220:223], v[120:123]
	v_mfma_f32_16x16x32_bf16 v[116:119], v[156:159], v[228:231], v[116:119]
	v_mfma_f32_16x16x32_bf16 v[112:115], v[164:167], v[228:231], v[112:115]
	v_mfma_f32_16x16x32_bf16 v[92:95], v[156:159], v[236:239], v[92:95]
	v_mfma_f32_16x16x32_bf16 v[88:91], v[164:167], v[236:239], v[88:91]
	v_mfma_f32_16x16x32_bf16 v[84:87], v[156:159], v[244:247], v[84:87]
	v_mfma_f32_16x16x32_bf16 v[80:83], v[164:167], v[244:247], v[80:83]
	v_mfma_f32_16x16x32_bf16 v[124:127], v[160:163], v[224:227], v[124:127]
	v_mfma_f32_16x16x32_bf16 v[120:123], v[168:171], v[224:227], v[120:123]
	v_mfma_f32_16x16x32_bf16 v[116:119], v[160:163], v[232:235], v[116:119]
	v_mfma_f32_16x16x32_bf16 v[112:115], v[168:171], v[232:235], v[112:115]
	v_mfma_f32_16x16x32_bf16 v[92:95], v[160:163], v[240:243], v[92:95]
	v_mfma_f32_16x16x32_bf16 v[88:91], v[168:171], v[240:243], v[88:91]
	v_mfma_f32_16x16x32_bf16 v[84:87], v[160:163], v[248:251], v[84:87]
	v_mfma_f32_16x16x32_bf16 v[80:83], v[168:171], v[248:251], v[80:83]
	v_mfma_f32_16x16x32_bf16 v[108:111], v[172:175], v[220:223], v[108:111]
	v_mfma_f32_16x16x32_bf16 v[104:107], v[212:215], v[220:223], v[104:107]
	v_mfma_f32_16x16x32_bf16 v[100:103], v[172:175], v[228:231], v[100:103]
	v_mfma_f32_16x16x32_bf16 v[96:99], v[212:215], v[228:231], v[96:99]
	v_mfma_f32_16x16x32_bf16 v[76:79], v[172:175], v[236:239], v[76:79]
	v_mfma_f32_16x16x32_bf16 v[72:75], v[212:215], v[236:239], v[72:75]
	v_mfma_f32_16x16x32_bf16 v[68:71], v[172:175], v[244:247], v[68:71]
	v_mfma_f32_16x16x32_bf16 v[64:67], v[212:215], v[244:247], v[64:67]
	v_mfma_f32_16x16x32_bf16 v[108:111], v[176:179], v[224:227], v[108:111]
	v_mfma_f32_16x16x32_bf16 v[104:107], v[216:219], v[224:227], v[104:107]
	v_mfma_f32_16x16x32_bf16 v[100:103], v[176:179], v[232:235], v[100:103]
	v_mfma_f32_16x16x32_bf16 v[96:99], v[216:219], v[232:235], v[96:99]
	v_mfma_f32_16x16x32_bf16 v[76:79], v[176:179], v[240:243], v[76:79]
	v_mfma_f32_16x16x32_bf16 v[72:75], v[216:219], v[240:243], v[72:75]
	v_mfma_f32_16x16x32_bf16 v[68:71], v[176:179], v[248:251], v[68:71]
	v_mfma_f32_16x16x32_bf16 v[64:67], v[216:219], v[248:251], v[64:67]
	s_setprio 0
	s_barrier
	s_add_u32 s50, s48, 0x8000
	s_addc_u32 s51, s49, 0
	s_add_i32 s55, s55, s64
	s_mov_b32 m0, s55
	ds_read_b128 v[220:223], v199 offset:49152
	ds_read_b128 v[224:227], v199 offset:50176
	ds_read_b128 v[228:231], v199 offset:51200
	ds_read_b128 v[232:235], v199 offset:52224
	ds_read_b128 v[236:239], v199 offset:53248
	ds_read_b128 v[240:243], v199 offset:54272
	ds_read_b128 v[244:247], v199 offset:55296
	ds_read_b128 v[248:251], v199 offset:56320
	global_load_lds_dwordx4 v130, s[50:51]
	s_add_i32 m0, s55, 0x2000
	s_add_u32 s48, s48, 0xc000
	v_lshl_add_u64 v[206:207], s[50:51], 0, v[134:135]
	s_addc_u32 s49, s49, 0
	s_add_i32 s50, s56, s64
	global_load_lds_dwordx4 v[206:207], off
	s_mov_b32 m0, s50
	v_lshl_add_u64 v[204:205], v[204:205], 0, s[14:15]
	global_load_lds_dwordx4 v130, s[48:49]
	s_add_i32 m0, s50, 0x2000
	s_nop 0
	global_load_lds_dwordx4 v134, s[48:49]
	v_lshl_add_u64 v[206:207], v[252:253], 0, s[14:15]
	s_mov_b32 m0, s74
	s_nop 0
	global_load_lds_dwordx4 v[206:207], off
	s_mov_b32 m0, s75
	s_nop 0
	global_load_lds_dwordx4 v[204:205], off
	s_waitcnt vmcnt(8)
	s_waitcnt lgkmcnt(0)
	s_barrier
	s_setprio 1
	s_waitcnt lgkmcnt(0)
	v_mfma_f32_16x16x32_bf16 v[60:63], v[156:159], v[220:223], v[60:63]
	v_mfma_f32_16x16x32_bf16 v[56:59], v[164:167], v[220:223], v[56:59]
	v_mfma_f32_16x16x32_bf16 v[52:55], v[156:159], v[228:231], v[52:55]
	v_mfma_f32_16x16x32_bf16 v[48:51], v[164:167], v[228:231], v[48:51]
	v_mfma_f32_16x16x32_bf16 v[28:31], v[156:159], v[236:239], v[28:31]
	v_mfma_f32_16x16x32_bf16 v[24:27], v[164:167], v[236:239], v[24:27]
	v_mfma_f32_16x16x32_bf16 v[20:23], v[156:159], v[244:247], v[20:23]
	v_mfma_f32_16x16x32_bf16 v[12:15], v[164:167], v[244:247], v[12:15]
	v_mfma_f32_16x16x32_bf16 v[60:63], v[160:163], v[224:227], v[60:63]
	v_mfma_f32_16x16x32_bf16 v[56:59], v[168:171], v[224:227], v[56:59]
	v_mfma_f32_16x16x32_bf16 v[52:55], v[160:163], v[232:235], v[52:55]
	v_mfma_f32_16x16x32_bf16 v[48:51], v[168:171], v[232:235], v[48:51]
	v_mfma_f32_16x16x32_bf16 v[28:31], v[160:163], v[240:243], v[28:31]
	v_mfma_f32_16x16x32_bf16 v[24:27], v[168:171], v[240:243], v[24:27]
	v_mfma_f32_16x16x32_bf16 v[20:23], v[160:163], v[248:251], v[20:23]
	v_mfma_f32_16x16x32_bf16 v[12:15], v[168:171], v[248:251], v[12:15]
	v_mfma_f32_16x16x32_bf16 v[44:47], v[172:175], v[220:223], v[44:47]
	v_mfma_f32_16x16x32_bf16 v[40:43], v[212:215], v[220:223], v[40:43]
	v_mfma_f32_16x16x32_bf16 v[36:39], v[172:175], v[228:231], v[36:39]
	v_mfma_f32_16x16x32_bf16 v[32:35], v[212:215], v[228:231], v[32:35]
	v_mfma_f32_16x16x32_bf16 v[16:19], v[172:175], v[236:239], v[16:19]
	v_mfma_f32_16x16x32_bf16 v[8:11], v[212:215], v[236:239], v[8:11]
	v_mfma_f32_16x16x32_bf16 v[4:7], v[172:175], v[244:247], v[4:7]
	v_mfma_f32_16x16x32_bf16 v[0:3], v[212:215], v[244:247], v[0:3]
	v_mfma_f32_16x16x32_bf16 v[44:47], v[176:179], v[224:227], v[44:47]
	v_mfma_f32_16x16x32_bf16 v[40:43], v[216:219], v[224:227], v[40:43]
	v_mfma_f32_16x16x32_bf16 v[36:39], v[176:179], v[232:235], v[36:39]
	v_mfma_f32_16x16x32_bf16 v[32:35], v[216:219], v[232:235], v[32:35]
	v_mfma_f32_16x16x32_bf16 v[16:19], v[176:179], v[240:243], v[16:19]
	v_mfma_f32_16x16x32_bf16 v[8:11], v[216:219], v[240:243], v[8:11]
	v_mfma_f32_16x16x32_bf16 v[4:7], v[176:179], v[248:251], v[4:7]
	v_mfma_f32_16x16x32_bf16 v[0:3], v[216:219], v[248:251], v[0:3]
	s_setprio 0
	s_barrier
	s_add_i32 s54, s54, 2
	s_add_u32 s52, s52, 0x10000
	s_addc_u32 s53, s53, 0
	s_add_u32 s46, s46, 0x100
	s_addc_u32 s47, s47, 0
	s_cmp_gt_u32 s54, 13
	s_cbranch_scc0 .LBB0_1171
	s_and_b64 vcc, exec, s[18:19]
	s_cbranch_vccz .LBB0_1174
	s_barrier

.LBB0_1253:
	ds_read_b128 v[170:173], v167
	ds_read_b128 v[174:177], v167 offset:1024
	ds_read_b128 v[178:181], v167 offset:2048
	ds_read_b128 v[182:185], v167 offset:3072
	ds_read_b128 v[186:189], v168
	ds_read_b128 v[190:193], v168 offset:1024
	ds_read_b128 v[194:197], v168 offset:2048
	ds_read_b128 v[198:201], v168 offset:3072
	s_add_u32 s26, s24, 0xfffc0080
	s_addc_u32 s27, s25, -1
	s_cmp_eq_u32 s54, 12
	s_cselect_b32 s29, s11, s27
	s_cselect_b32 s28, s50, s26
	s_cselect_b32 s27, s13, s53
	s_cselect_b32 s26, s51, s52
	s_add_i32 m0, s21, 0xc000
	ds_read_b128 v[210:213], v169
	ds_read_b128 v[214:217], v169 offset:1024
	ds_read_b128 v[218:221], v169 offset:2048
	ds_read_b128 v[222:225], v169 offset:3072
	ds_read_b128 v[226:229], v169 offset:4096
	ds_read_b128 v[230:233], v169 offset:5120
	ds_read_b128 v[234:237], v169 offset:6144
	ds_read_b128 v[238:241], v169 offset:7168
	global_load_lds_dwordx4 v158, s[24:25]
	s_add_i32 m0, s21, 0xe000
	s_nop 0
	global_load_lds_dwordx4 v156, s[24:25]
	s_waitcnt vmcnt(8)
	s_waitcnt lgkmcnt(0)
	s_barrier
	s_setprio 1
	s_waitcnt lgkmcnt(0)
	v_mfma_f32_16x16x32_bf16 v[124:127], v[170:173], v[210:213], v[124:127]
	v_mfma_f32_16x16x32_bf16 v[116:119], v[178:181], v[210:213], v[116:119]
	v_mfma_f32_16x16x32_bf16 v[108:111], v[170:173], v[218:221], v[108:111]
	v_mfma_f32_16x16x32_bf16 v[100:103], v[178:181], v[218:221], v[100:103]
	v_mfma_f32_16x16x32_bf16 v[92:95], v[170:173], v[226:229], v[92:95]
	v_mfma_f32_16x16x32_bf16 v[84:87], v[178:181], v[226:229], v[84:87]
	v_mfma_f32_16x16x32_bf16 v[76:79], v[170:173], v[234:237], v[76:79]
	v_mfma_f32_16x16x32_bf16 v[68:71], v[178:181], v[234:237], v[68:71]
	v_mfma_f32_16x16x32_bf16 v[124:127], v[174:177], v[214:217], v[124:127]
	v_mfma_f32_16x16x32_bf16 v[116:119], v[182:185], v[214:217], v[116:119]
	v_mfma_f32_16x16x32_bf16 v[108:111], v[174:177], v[222:225], v[108:111]
	v_mfma_f32_16x16x32_bf16 v[100:103], v[182:185], v[222:225], v[100:103]
	v_mfma_f32_16x16x32_bf16 v[92:95], v[174:177], v[230:233], v[92:95]
	v_mfma_f32_16x16x32_bf16 v[84:87], v[182:185], v[230:233], v[84:87]
	v_mfma_f32_16x16x32_bf16 v[76:79], v[174:177], v[238:241], v[76:79]
	v_mfma_f32_16x16x32_bf16 v[68:71], v[182:185], v[238:241], v[68:71]
	v_mfma_f32_16x16x32_bf16 v[120:123], v[186:189], v[210:213], v[120:123]
	v_mfma_f32_16x16x32_bf16 v[112:115], v[194:197], v[210:213], v[112:115]
	v_mfma_f32_16x16x32_bf16 v[104:107], v[186:189], v[218:221], v[104:107]
	v_mfma_f32_16x16x32_bf16 v[96:99], v[194:197], v[218:221], v[96:99]
	v_mfma_f32_16x16x32_bf16 v[88:91], v[186:189], v[226:229], v[88:91]
	v_mfma_f32_16x16x32_bf16 v[80:83], v[194:197], v[226:229], v[80:83]
	v_mfma_f32_16x16x32_bf16 v[72:75], v[186:189], v[234:237], v[72:75]
	v_mfma_f32_16x16x32_bf16 v[64:67], v[194:197], v[234:237], v[64:67]
	v_mfma_f32_16x16x32_bf16 v[120:123], v[190:193], v[214:217], v[120:123]
	v_mfma_f32_16x16x32_bf16 v[112:115], v[198:201], v[214:217], v[112:115]
	v_mfma_f32_16x16x32_bf16 v[104:107], v[190:193], v[222:225], v[104:107]
	v_mfma_f32_16x16x32_bf16 v[96:99], v[198:201], v[222:225], v[96:99]
	v_mfma_f32_16x16x32_bf16 v[88:91], v[190:193], v[230:233], v[88:91]
	v_mfma_f32_16x16x32_bf16 v[80:83], v[198:201], v[230:233], v[80:83]
	v_mfma_f32_16x16x32_bf16 v[72:75], v[190:193], v[238:241], v[72:75]
	v_mfma_f32_16x16x32_bf16 v[64:67], v[198:201], v[238:241], v[64:67]
	s_setprio 0
	s_barrier
	s_add_i32 s55, s48, s35
	s_mov_b32 m0, s55
	ds_read_b128 v[210:213], v169 offset:16384
	ds_read_b128 v[214:217], v169 offset:17408
	ds_read_b128 v[218:221], v169 offset:18432
	ds_read_b128 v[222:225], v169 offset:19456
	ds_read_b128 v[226:229], v169 offset:20480
	ds_read_b128 v[230:233], v169 offset:21504
	ds_read_b128 v[234:237], v169 offset:22528
	ds_read_b128 v[238:241], v169 offset:23552
	global_load_lds_dwordx4 v134, s[26:27]
	s_add_i32 m0, s55, 0x2000
	s_add_u32 s56, s26, 0x4000
	s_addc_u32 s57, s27, 0
	s_add_i32 s55, s49, s35
	global_load_lds_dwordx4 v130, s[26:27]
	s_mov_b32 m0, s55
	v_lshl_add_u64 v[204:205], s[28:29], 0, v[132:133]
	global_load_lds_dwordx4 v134, s[56:57]
	s_add_i32 m0, s55, 0x2000
	s_nop 0
	global_load_lds_dwordx4 v130, s[56:57]
	v_lshl_add_u64 v[164:165], s[28:29], 0, v[136:137]
	s_mov_b32 m0, s21
	s_nop 0
	global_load_lds_dwordx4 v[164:165], off
	s_mov_b32 m0, s23
	s_nop 0
	global_load_lds_dwordx4 v[204:205], off
	s_waitcnt vmcnt(8)
	s_waitcnt lgkmcnt(0)
	s_barrier
	s_setprio 1
	s_waitcnt lgkmcnt(0)
	v_mfma_f32_16x16x32_bf16 v[60:63], v[170:173], v[210:213], v[60:63]
	v_mfma_f32_16x16x32_bf16 v[52:55], v[178:181], v[210:213], v[52:55]
	v_mfma_f32_16x16x32_bf16 v[44:47], v[170:173], v[218:221], v[44:47]
	v_mfma_f32_16x16x32_bf16 v[36:39], v[178:181], v[218:221], v[36:39]
	v_mfma_f32_16x16x32_bf16 v[28:31], v[170:173], v[226:229], v[28:31]
	v_mfma_f32_16x16x32_bf16 v[20:23], v[178:181], v[226:229], v[20:23]
	v_mfma_f32_16x16x32_bf16 v[12:15], v[170:173], v[234:237], v[12:15]
	v_mfma_f32_16x16x32_bf16 v[4:7], v[178:181], v[234:237], v[4:7]
	v_mfma_f32_16x16x32_bf16 v[60:63], v[174:177], v[214:217], v[60:63]
	v_mfma_f32_16x16x32_bf16 v[52:55], v[182:185], v[214:217], v[52:55]
	v_mfma_f32_16x16x32_bf16 v[44:47], v[174:177], v[222:225], v[44:47]
	v_mfma_f32_16x16x32_bf16 v[36:39], v[182:185], v[222:225], v[36:39]
	v_mfma_f32_16x16x32_bf16 v[28:31], v[174:177], v[230:233], v[28:31]
	v_mfma_f32_16x16x32_bf16 v[20:23], v[182:185], v[230:233], v[20:23]
	v_mfma_f32_16x16x32_bf16 v[12:15], v[174:177], v[238:241], v[12:15]
	v_mfma_f32_16x16x32_bf16 v[4:7], v[182:185], v[238:241], v[4:7]
	v_mfma_f32_16x16x32_bf16 v[56:59], v[186:189], v[210:213], v[56:59]
	v_mfma_f32_16x16x32_bf16 v[48:51], v[194:197], v[210:213], v[48:51]
	v_mfma_f32_16x16x32_bf16 v[40:43], v[186:189], v[218:221], v[40:43]
	v_mfma_f32_16x16x32_bf16 v[32:35], v[194:197], v[218:221], v[32:35]
	v_mfma_f32_16x16x32_bf16 v[24:27], v[186:189], v[226:229], v[24:27]
	v_mfma_f32_16x16x32_bf16 v[16:19], v[194:197], v[226:229], v[16:19]
	v_mfma_f32_16x16x32_bf16 v[8:11], v[186:189], v[234:237], v[8:11]
	v_mfma_f32_16x16x32_bf16 v[0:3], v[194:197], v[234:237], v[0:3]
	v_mfma_f32_16x16x32_bf16 v[56:59], v[190:193], v[214:217], v[56:59]
	v_mfma_f32_16x16x32_bf16 v[48:51], v[198:201], v[214:217], v[48:51]
	v_mfma_f32_16x16x32_bf16 v[40:43], v[190:193], v[222:225], v[40:43]
	v_mfma_f32_16x16x32_bf16 v[32:35], v[198:201], v[222:225], v[32:35]
	v_mfma_f32_16x16x32_bf16 v[24:27], v[190:193], v[230:233], v[24:27]
	v_mfma_f32_16x16x32_bf16 v[16:19], v[198:201], v[230:233], v[16:19]
	v_mfma_f32_16x16x32_bf16 v[8:11], v[190:193], v[238:241], v[8:11]
	v_mfma_f32_16x16x32_bf16 v[0:3], v[198:201], v[238:241], v[0:3]
	s_setprio 0
	s_barrier
	s_add_i32 s55, 0, 0x18000
	s_add_i32 s56, 0, 0x1c000
	v_add_u32_e32 v182, s55, v129
	v_add_u32_e32 v198, s56, v129
	ds_read_b128 v[170:173], v182
	ds_read_b128 v[174:177], v182 offset:1024
	ds_read_b128 v[178:181], v182 offset:2048
	ds_read_b128 v[182:185], v182 offset:3072
	ds_read_b128 v[186:189], v198
	ds_read_b128 v[190:193], v198 offset:1024
	ds_read_b128 v[194:197], v198 offset:2048
	ds_read_b128 v[198:201], v198 offset:3072
	s_add_u32 s28, s28, 0x40000
	s_addc_u32 s29, s29, 0
	s_mov_b32 m0, s39
	ds_read_b128 v[210:213], v169 offset:32768
	ds_read_b128 v[214:217], v169 offset:33792
	ds_read_b128 v[218:221], v169 offset:34816
	ds_read_b128 v[222:225], v169 offset:35840
	ds_read_b128 v[226:229], v169 offset:36864
	ds_read_b128 v[230:233], v169 offset:37888
	ds_read_b128 v[234:237], v169 offset:38912
	ds_read_b128 v[238:241], v169 offset:39936
	global_load_lds_dwordx4 v136, s[28:29]
	s_mov_b32 m0, s40
	s_nop 0
	global_load_lds_dwordx4 v132, s[28:29]
	s_waitcnt vmcnt(8)
	s_waitcnt lgkmcnt(0)
	s_barrier
	s_setprio 1
	s_waitcnt lgkmcnt(0)
	v_mfma_f32_16x16x32_bf16 v[124:127], v[170:173], v[210:213], v[124:127]
	v_mfma_f32_16x16x32_bf16 v[116:119], v[178:181], v[210:213], v[116:119]
	v_mfma_f32_16x16x32_bf16 v[108:111], v[170:173], v[218:221], v[108:111]
	v_mfma_f32_16x16x32_bf16 v[100:103], v[178:181], v[218:221], v[100:103]
	v_mfma_f32_16x16x32_bf16 v[92:95], v[170:173], v[226:229], v[92:95]
	v_mfma_f32_16x16x32_bf16 v[84:87], v[178:181], v[226:229], v[84:87]
	v_mfma_f32_16x16x32_bf16 v[76:79], v[170:173], v[234:237], v[76:79]
	v_mfma_f32_16x16x32_bf16 v[68:71], v[178:181], v[234:237], v[68:71]
	v_mfma_f32_16x16x32_bf16 v[124:127], v[174:177], v[214:217], v[124:127]
	v_mfma_f32_16x16x32_bf16 v[116:119], v[182:185], v[214:217], v[116:119]
	v_mfma_f32_16x16x32_bf16 v[108:111], v[174:177], v[222:225], v[108:111]
	v_mfma_f32_16x16x32_bf16 v[100:103], v[182:185], v[222:225], v[100:103]
	v_mfma_f32_16x16x32_bf16 v[92:95], v[174:177], v[230:233], v[92:95]
	v_mfma_f32_16x16x32_bf16 v[84:87], v[182:185], v[230:233], v[84:87]
	v_mfma_f32_16x16x32_bf16 v[76:79], v[174:177], v[238:241], v[76:79]
	v_mfma_f32_16x16x32_bf16 v[68:71], v[182:185], v[238:241], v[68:71]
	v_mfma_f32_16x16x32_bf16 v[120:123], v[186:189], v[210:213], v[120:123]
	v_mfma_f32_16x16x32_bf16 v[112:115], v[194:197], v[210:213], v[112:115]
	v_mfma_f32_16x16x32_bf16 v[104:107], v[186:189], v[218:221], v[104:107]
	v_mfma_f32_16x16x32_bf16 v[96:99], v[194:197], v[218:221], v[96:99]
	v_mfma_f32_16x16x32_bf16 v[88:91], v[186:189], v[226:229], v[88:91]
	v_mfma_f32_16x16x32_bf16 v[80:83], v[194:197], v[226:229], v[80:83]
	v_mfma_f32_16x16x32_bf16 v[72:75], v[186:189], v[234:237], v[72:75]
	v_mfma_f32_16x16x32_bf16 v[64:67], v[194:197], v[234:237], v[64:67]
	v_mfma_f32_16x16x32_bf16 v[120:123], v[190:193], v[214:217], v[120:123]
	v_mfma_f32_16x16x32_bf16 v[112:115], v[198:201], v[214:217], v[112:115]
	v_mfma_f32_16x16x32_bf16 v[104:107], v[190:193], v[222:225], v[104:107]
	v_mfma_f32_16x16x32_bf16 v[96:99], v[198:201], v[222:225], v[96:99]
	v_mfma_f32_16x16x32_bf16 v[88:91], v[190:193], v[230:233], v[88:91]
	v_mfma_f32_16x16x32_bf16 v[80:83], v[198:201], v[230:233], v[80:83]
	v_mfma_f32_16x16x32_bf16 v[72:75], v[190:193], v[238:241], v[72:75]
	v_mfma_f32_16x16x32_bf16 v[64:67], v[198:201], v[238:241], v[64:67]
	s_setprio 0
	s_barrier
	s_add_u32 s28, s26, 0x8000
	s_addc_u32 s29, s27, 0
	s_add_i32 s55, s55, s35
	s_mov_b32 m0, s55
	ds_read_b128 v[210:213], v169 offset:49152
	ds_read_b128 v[214:217], v169 offset:50176
	ds_read_b128 v[218:221], v169 offset:51200
	ds_read_b128 v[222:225], v169 offset:52224
	ds_read_b128 v[226:229], v169 offset:53248
	ds_read_b128 v[230:233], v169 offset:54272
	ds_read_b128 v[234:237], v169 offset:55296
	ds_read_b128 v[238:241], v169 offset:56320
	global_load_lds_dwordx4 v134, s[28:29]
	s_add_i32 m0, s55, 0x2000
	s_add_u32 s26, s26, 0xc000
	v_lshl_add_u64 v[206:207], s[28:29], 0, v[130:131]
	s_addc_u32 s27, s27, 0
	s_add_i32 s28, s56, s35
	global_load_lds_dwordx4 v[206:207], off
	s_mov_b32 m0, s28
	v_lshl_add_u64 v[164:165], v[164:165], 0, s[6:7]
	global_load_lds_dwordx4 v134, s[26:27]
	s_add_i32 m0, s28, 0x2000
	s_nop 0
	global_load_lds_dwordx4 v130, s[26:27]
	s_mov_b32 m0, s45
	s_nop 0
	global_load_lds_dwordx4 v[164:165], off
	v_lshl_add_u64 v[164:165], v[204:205], 0, s[6:7]
	s_mov_b32 m0, s46
	s_nop 0
	global_load_lds_dwordx4 v[164:165], off
	s_waitcnt vmcnt(8)
	s_waitcnt lgkmcnt(0)
	s_barrier
	s_setprio 1
	s_waitcnt lgkmcnt(0)
	v_mfma_f32_16x16x32_bf16 v[60:63], v[170:173], v[210:213], v[60:63]
	v_mfma_f32_16x16x32_bf16 v[52:55], v[178:181], v[210:213], v[52:55]
	v_mfma_f32_16x16x32_bf16 v[44:47], v[170:173], v[218:221], v[44:47]
	v_mfma_f32_16x16x32_bf16 v[36:39], v[178:181], v[218:221], v[36:39]
	v_mfma_f32_16x16x32_bf16 v[28:31], v[170:173], v[226:229], v[28:31]
	v_mfma_f32_16x16x32_bf16 v[20:23], v[178:181], v[226:229], v[20:23]
	v_mfma_f32_16x16x32_bf16 v[12:15], v[170:173], v[234:237], v[12:15]
	v_mfma_f32_16x16x32_bf16 v[4:7], v[178:181], v[234:237], v[4:7]
	v_mfma_f32_16x16x32_bf16 v[60:63], v[174:177], v[214:217], v[60:63]
	v_mfma_f32_16x16x32_bf16 v[52:55], v[182:185], v[214:217], v[52:55]
	v_mfma_f32_16x16x32_bf16 v[44:47], v[174:177], v[222:225], v[44:47]
	v_mfma_f32_16x16x32_bf16 v[36:39], v[182:185], v[222:225], v[36:39]
	v_mfma_f32_16x16x32_bf16 v[28:31], v[174:177], v[230:233], v[28:31]
	v_mfma_f32_16x16x32_bf16 v[20:23], v[182:185], v[230:233], v[20:23]
	v_mfma_f32_16x16x32_bf16 v[12:15], v[174:177], v[238:241], v[12:15]
	v_mfma_f32_16x16x32_bf16 v[4:7], v[182:185], v[238:241], v[4:7]
	v_mfma_f32_16x16x32_bf16 v[56:59], v[186:189], v[210:213], v[56:59]
	v_mfma_f32_16x16x32_bf16 v[48:51], v[194:197], v[210:213], v[48:51]
	v_mfma_f32_16x16x32_bf16 v[40:43], v[186:189], v[218:221], v[40:43]
	v_mfma_f32_16x16x32_bf16 v[32:35], v[194:197], v[218:221], v[32:35]
	v_mfma_f32_16x16x32_bf16 v[24:27], v[186:189], v[226:229], v[24:27]
	v_mfma_f32_16x16x32_bf16 v[16:19], v[194:197], v[226:229], v[16:19]
	v_mfma_f32_16x16x32_bf16 v[8:11], v[186:189], v[234:237], v[8:11]
	v_mfma_f32_16x16x32_bf16 v[0:3], v[194:197], v[234:237], v[0:3]
	v_mfma_f32_16x16x32_bf16 v[56:59], v[190:193], v[214:217], v[56:59]
	v_mfma_f32_16x16x32_bf16 v[48:51], v[198:201], v[214:217], v[48:51]
	v_mfma_f32_16x16x32_bf16 v[40:43], v[190:193], v[222:225], v[40:43]
	v_mfma_f32_16x16x32_bf16 v[32:35], v[198:201], v[222:225], v[32:35]
	v_mfma_f32_16x16x32_bf16 v[24:27], v[190:193], v[230:233], v[24:27]
	v_mfma_f32_16x16x32_bf16 v[16:19], v[198:201], v[230:233], v[16:19]
	v_mfma_f32_16x16x32_bf16 v[8:11], v[190:193], v[238:241], v[8:11]
	v_mfma_f32_16x16x32_bf16 v[0:3], v[198:201], v[238:241], v[0:3]
	s_setprio 0
	s_barrier
	s_add_i32 s54, s54, 2
	s_add_u32 s52, s52, 0x10000
	s_addc_u32 s53, s53, 0
	s_add_u32 s24, s24, 0x100
	s_addc_u32 s25, s25, 0
	s_cmp_gt_u32 s54, 13
	s_cbranch_scc0 .LBB0_1253
	s_and_b64 vcc, exec, s[8:9]
	s_cbranch_vccz .LBB0_1256
	s_barrier

.LBB0_1481:
	v_add_u32_e32 v168, s61, v182
	v_add_u32_e32 v204, s62, v182
	ds_read_b128 v[156:159], v168
	ds_read_b128 v[160:163], v168 offset:1024
	ds_read_b128 v[164:167], v168 offset:2048
	ds_read_b128 v[168:171], v168 offset:3072
	ds_read_b128 v[172:175], v204
	ds_read_b128 v[176:179], v204 offset:1024
	ds_read_b128 v[212:215], v204 offset:2048
	ds_read_b128 v[216:219], v204 offset:3072
	s_add_u32 s38, s36, 0x4000
	s_addc_u32 s39, s37, 0
	s_cmp_eq_u32 s70, 40
	s_cselect_b32 s42, s0, s38
	s_cselect_b32 s43, s1, s39
	s_cselect_b32 s40, s34, s68
	s_cselect_b32 s41, s35, s69
	s_add_u32 s38, s42, 0x8000
	s_addc_u32 s39, s43, 0
	s_add_i32 m0, s48, 0xc000
	ds_read_b128 v[220:223], v199
	ds_read_b128 v[224:227], v199 offset:1024
	ds_read_b128 v[228:231], v199 offset:2048
	ds_read_b128 v[232:235], v199 offset:3072
	ds_read_b128 v[236:239], v199 offset:4096
	ds_read_b128 v[240:243], v199 offset:5120
	ds_read_b128 v[244:247], v199 offset:6144
	ds_read_b128 v[248:251], v199 offset:7168
	global_load_lds_dwordx4 v150, s[36:37]
	s_add_i32 m0, s48, 0xe000
	s_nop 0
	global_load_lds_dwordx4 v148, s[36:37]
	s_waitcnt vmcnt(8)
	s_waitcnt lgkmcnt(0)
	s_barrier
	s_setprio 1
	s_waitcnt lgkmcnt(0)
	v_mfma_f32_16x16x32_bf16 v[124:127], v[156:159], v[220:223], v[124:127]
	v_mfma_f32_16x16x32_bf16 v[120:123], v[164:167], v[220:223], v[120:123]
	v_mfma_f32_16x16x32_bf16 v[116:119], v[156:159], v[228:231], v[116:119]
	v_mfma_f32_16x16x32_bf16 v[112:115], v[164:167], v[228:231], v[112:115]
	v_mfma_f32_16x16x32_bf16 v[92:95], v[156:159], v[236:239], v[92:95]
	v_mfma_f32_16x16x32_bf16 v[88:91], v[164:167], v[236:239], v[88:91]
	v_mfma_f32_16x16x32_bf16 v[84:87], v[156:159], v[244:247], v[84:87]
	v_mfma_f32_16x16x32_bf16 v[80:83], v[164:167], v[244:247], v[80:83]
	v_mfma_f32_16x16x32_bf16 v[124:127], v[160:163], v[224:227], v[124:127]
	v_mfma_f32_16x16x32_bf16 v[120:123], v[168:171], v[224:227], v[120:123]
	v_mfma_f32_16x16x32_bf16 v[116:119], v[160:163], v[232:235], v[116:119]
	v_mfma_f32_16x16x32_bf16 v[112:115], v[168:171], v[232:235], v[112:115]
	v_mfma_f32_16x16x32_bf16 v[92:95], v[160:163], v[240:243], v[92:95]
	v_mfma_f32_16x16x32_bf16 v[88:91], v[168:171], v[240:243], v[88:91]
	v_mfma_f32_16x16x32_bf16 v[84:87], v[160:163], v[248:251], v[84:87]
	v_mfma_f32_16x16x32_bf16 v[80:83], v[168:171], v[248:251], v[80:83]
	v_mfma_f32_16x16x32_bf16 v[108:111], v[172:175], v[220:223], v[108:111]
	v_mfma_f32_16x16x32_bf16 v[104:107], v[212:215], v[220:223], v[104:107]
	v_mfma_f32_16x16x32_bf16 v[100:103], v[172:175], v[228:231], v[100:103]
	v_mfma_f32_16x16x32_bf16 v[96:99], v[212:215], v[228:231], v[96:99]
	v_mfma_f32_16x16x32_bf16 v[76:79], v[172:175], v[236:239], v[76:79]
	v_mfma_f32_16x16x32_bf16 v[72:75], v[212:215], v[236:239], v[72:75]
	v_mfma_f32_16x16x32_bf16 v[68:71], v[172:175], v[244:247], v[68:71]
	v_mfma_f32_16x16x32_bf16 v[64:67], v[212:215], v[244:247], v[64:67]
	v_mfma_f32_16x16x32_bf16 v[108:111], v[176:179], v[224:227], v[108:111]
	v_mfma_f32_16x16x32_bf16 v[104:107], v[216:219], v[224:227], v[104:107]
	v_mfma_f32_16x16x32_bf16 v[100:103], v[176:179], v[232:235], v[100:103]
	v_mfma_f32_16x16x32_bf16 v[96:99], v[216:219], v[232:235], v[96:99]
	v_mfma_f32_16x16x32_bf16 v[76:79], v[176:179], v[240:243], v[76:79]
	v_mfma_f32_16x16x32_bf16 v[72:75], v[216:219], v[240:243], v[72:75]
	v_mfma_f32_16x16x32_bf16 v[68:71], v[176:179], v[248:251], v[68:71]
	v_mfma_f32_16x16x32_bf16 v[64:67], v[216:219], v[248:251], v[64:67]
	s_setprio 0
	s_barrier
	s_add_i32 s71, s61, s47
	s_mov_b32 m0, s71
	ds_read_b128 v[220:223], v199 offset:16384
	ds_read_b128 v[224:227], v199 offset:17408
	ds_read_b128 v[228:231], v199 offset:18432
	ds_read_b128 v[232:235], v199 offset:19456
	ds_read_b128 v[236:239], v199 offset:20480
	ds_read_b128 v[240:243], v199 offset:21504
	ds_read_b128 v[244:247], v199 offset:22528
	ds_read_b128 v[248:251], v199 offset:23552
	global_load_lds_dwordx4 v128, s[40:41]
	s_add_i32 m0, s71, 0x2000
	s_add_u32 s72, s40, 0x4000
	s_addc_u32 s73, s41, 0
	s_add_i32 s71, s62, s47
	global_load_lds_dwordx4 v130, s[40:41]
	s_mov_b32 m0, s71
	s_nop 0
	global_load_lds_dwordx4 v128, s[72:73]
	s_add_i32 m0, s71, 0x2000
	s_nop 0
	global_load_lds_dwordx4 v130, s[72:73]
	s_mov_b32 m0, s48
	s_nop 0
	global_load_lds_dwordx4 v128, s[42:43]
	v_lshl_add_u64 v[204:205], s[42:43], 0, v[130:131]
	s_mov_b32 m0, s49
	s_nop 0
	global_load_lds_dwordx4 v[204:205], off
	s_waitcnt vmcnt(8)
	s_waitcnt lgkmcnt(0)
	s_barrier
	s_setprio 1
	s_waitcnt lgkmcnt(0)
	v_mfma_f32_16x16x32_bf16 v[60:63], v[156:159], v[220:223], v[60:63]
	v_mfma_f32_16x16x32_bf16 v[56:59], v[164:167], v[220:223], v[56:59]
	v_mfma_f32_16x16x32_bf16 v[52:55], v[156:159], v[228:231], v[52:55]
	v_mfma_f32_16x16x32_bf16 v[48:51], v[164:167], v[228:231], v[48:51]
	v_mfma_f32_16x16x32_bf16 v[28:31], v[156:159], v[236:239], v[28:31]
	v_mfma_f32_16x16x32_bf16 v[24:27], v[164:167], v[236:239], v[24:27]
	v_mfma_f32_16x16x32_bf16 v[20:23], v[156:159], v[244:247], v[20:23]
	v_mfma_f32_16x16x32_bf16 v[12:15], v[164:167], v[244:247], v[12:15]
	v_mfma_f32_16x16x32_bf16 v[60:63], v[160:163], v[224:227], v[60:63]
	v_mfma_f32_16x16x32_bf16 v[56:59], v[168:171], v[224:227], v[56:59]
	v_mfma_f32_16x16x32_bf16 v[52:55], v[160:163], v[232:235], v[52:55]
	v_mfma_f32_16x16x32_bf16 v[48:51], v[168:171], v[232:235], v[48:51]
	v_mfma_f32_16x16x32_bf16 v[28:31], v[160:163], v[240:243], v[28:31]
	v_mfma_f32_16x16x32_bf16 v[24:27], v[168:171], v[240:243], v[24:27]
	v_mfma_f32_16x16x32_bf16 v[20:23], v[160:163], v[248:251], v[20:23]
	v_mfma_f32_16x16x32_bf16 v[12:15], v[168:171], v[248:251], v[12:15]
	v_mfma_f32_16x16x32_bf16 v[44:47], v[172:175], v[220:223], v[44:47]
	v_mfma_f32_16x16x32_bf16 v[40:43], v[212:215], v[220:223], v[40:43]
	v_mfma_f32_16x16x32_bf16 v[36:39], v[172:175], v[228:231], v[36:39]
	v_mfma_f32_16x16x32_bf16 v[32:35], v[212:215], v[228:231], v[32:35]
	v_mfma_f32_16x16x32_bf16 v[16:19], v[172:175], v[236:239], v[16:19]
	v_mfma_f32_16x16x32_bf16 v[8:11], v[212:215], v[236:239], v[8:11]
	v_mfma_f32_16x16x32_bf16 v[4:7], v[172:175], v[244:247], v[4:7]
	v_mfma_f32_16x16x32_bf16 v[0:3], v[212:215], v[244:247], v[0:3]
	v_mfma_f32_16x16x32_bf16 v[44:47], v[176:179], v[224:227], v[44:47]
	v_mfma_f32_16x16x32_bf16 v[40:43], v[216:219], v[224:227], v[40:43]
	v_mfma_f32_16x16x32_bf16 v[36:39], v[176:179], v[232:235], v[36:39]
	v_mfma_f32_16x16x32_bf16 v[32:35], v[216:219], v[232:235], v[32:35]
	v_mfma_f32_16x16x32_bf16 v[16:19], v[176:179], v[240:243], v[16:19]
	v_mfma_f32_16x16x32_bf16 v[8:11], v[216:219], v[240:243], v[8:11]
	v_mfma_f32_16x16x32_bf16 v[4:7], v[176:179], v[248:251], v[4:7]
	v_mfma_f32_16x16x32_bf16 v[0:3], v[216:219], v[248:251], v[0:3]
	s_setprio 0
	s_barrier
	s_add_i32 s71, 0, 0x18000
	s_add_i32 s72, 0, 0x1c000
	v_add_u32_e32 v168, s71, v182
	v_add_u32_e32 v204, s72, v182
	ds_read_b128 v[156:159], v168
	ds_read_b128 v[160:163], v168 offset:1024
	ds_read_b128 v[164:167], v168 offset:2048
	ds_read_b128 v[168:171], v168 offset:3072
	ds_read_b128 v[172:175], v204
	ds_read_b128 v[176:179], v204 offset:1024
	ds_read_b128 v[212:215], v204 offset:2048
	ds_read_b128 v[216:219], v204 offset:3072
	s_add_u32 s42, s42, 0x4000
	s_addc_u32 s43, s43, 0
	s_mov_b32 m0, s50
	ds_read_b128 v[220:223], v199 offset:32768
	ds_read_b128 v[224:227], v199 offset:33792
	ds_read_b128 v[228:231], v199 offset:34816
	ds_read_b128 v[232:235], v199 offset:35840
	ds_read_b128 v[236:239], v199 offset:36864
	ds_read_b128 v[240:243], v199 offset:37888
	ds_read_b128 v[244:247], v199 offset:38912
	ds_read_b128 v[248:251], v199 offset:39936
	global_load_lds_dwordx4 v128, s[42:43]
	s_mov_b32 m0, s51
	s_nop 0
	global_load_lds_dwordx4 v130, s[42:43]
	s_waitcnt vmcnt(8)
	s_waitcnt lgkmcnt(0)
	s_barrier
	s_setprio 1
	s_waitcnt lgkmcnt(0)
	v_mfma_f32_16x16x32_bf16 v[124:127], v[156:159], v[220:223], v[124:127]
	v_mfma_f32_16x16x32_bf16 v[120:123], v[164:167], v[220:223], v[120:123]
	v_mfma_f32_16x16x32_bf16 v[116:119], v[156:159], v[228:231], v[116:119]
	v_mfma_f32_16x16x32_bf16 v[112:115], v[164:167], v[228:231], v[112:115]
	v_mfma_f32_16x16x32_bf16 v[92:95], v[156:159], v[236:239], v[92:95]
	v_mfma_f32_16x16x32_bf16 v[88:91], v[164:167], v[236:239], v[88:91]
	v_mfma_f32_16x16x32_bf16 v[84:87], v[156:159], v[244:247], v[84:87]
	v_mfma_f32_16x16x32_bf16 v[80:83], v[164:167], v[244:247], v[80:83]
	v_mfma_f32_16x16x32_bf16 v[124:127], v[160:163], v[224:227], v[124:127]
	v_mfma_f32_16x16x32_bf16 v[120:123], v[168:171], v[224:227], v[120:123]
	v_mfma_f32_16x16x32_bf16 v[116:119], v[160:163], v[232:235], v[116:119]
	v_mfma_f32_16x16x32_bf16 v[112:115], v[168:171], v[232:235], v[112:115]
	v_mfma_f32_16x16x32_bf16 v[92:95], v[160:163], v[240:243], v[92:95]
	v_mfma_f32_16x16x32_bf16 v[88:91], v[168:171], v[240:243], v[88:91]
	v_mfma_f32_16x16x32_bf16 v[84:87], v[160:163], v[248:251], v[84:87]
	v_mfma_f32_16x16x32_bf16 v[80:83], v[168:171], v[248:251], v[80:83]
	v_mfma_f32_16x16x32_bf16 v[108:111], v[172:175], v[220:223], v[108:111]
	v_mfma_f32_16x16x32_bf16 v[104:107], v[212:215], v[220:223], v[104:107]
	v_mfma_f32_16x16x32_bf16 v[100:103], v[172:175], v[228:231], v[100:103]
	v_mfma_f32_16x16x32_bf16 v[96:99], v[212:215], v[228:231], v[96:99]
	v_mfma_f32_16x16x32_bf16 v[76:79], v[172:175], v[236:239], v[76:79]
	v_mfma_f32_16x16x32_bf16 v[72:75], v[212:215], v[236:239], v[72:75]
	v_mfma_f32_16x16x32_bf16 v[68:71], v[172:175], v[244:247], v[68:71]
	v_mfma_f32_16x16x32_bf16 v[64:67], v[212:215], v[244:247], v[64:67]
	v_mfma_f32_16x16x32_bf16 v[108:111], v[176:179], v[224:227], v[108:111]
	v_mfma_f32_16x16x32_bf16 v[104:107], v[216:219], v[224:227], v[104:107]
	v_mfma_f32_16x16x32_bf16 v[100:103], v[176:179], v[232:235], v[100:103]
	v_mfma_f32_16x16x32_bf16 v[96:99], v[216:219], v[232:235], v[96:99]
	v_mfma_f32_16x16x32_bf16 v[76:79], v[176:179], v[240:243], v[76:79]
	v_mfma_f32_16x16x32_bf16 v[72:75], v[216:219], v[240:243], v[72:75]
	v_mfma_f32_16x16x32_bf16 v[68:71], v[176:179], v[248:251], v[68:71]
	v_mfma_f32_16x16x32_bf16 v[64:67], v[216:219], v[248:251], v[64:67]
	s_setprio 0
	s_barrier
	s_add_u32 s42, s40, 0x8000
	s_addc_u32 s43, s41, 0
	s_add_i32 s71, s71, s47
	s_mov_b32 m0, s71
	ds_read_b128 v[220:223], v199 offset:49152
	ds_read_b128 v[224:227], v199 offset:50176
	ds_read_b128 v[228:231], v199 offset:51200
	ds_read_b128 v[232:235], v199 offset:52224
	ds_read_b128 v[236:239], v199 offset:53248
	ds_read_b128 v[240:243], v199 offset:54272
	ds_read_b128 v[244:247], v199 offset:55296
	ds_read_b128 v[248:251], v199 offset:56320
	global_load_lds_dwordx4 v128, s[42:43]
	s_add_i32 m0, s71, 0x2000
	s_add_u32 s40, s40, 0xc000
	v_lshl_add_u64 v[204:205], s[42:43], 0, v[130:131]
	s_addc_u32 s41, s41, 0
	s_add_i32 s42, s72, s47
	global_load_lds_dwordx4 v[204:205], off
	s_mov_b32 m0, s42
	s_nop 0
	global_load_lds_dwordx4 v128, s[40:41]
	s_add_i32 m0, s42, 0x2000
	s_nop 0
	global_load_lds_dwordx4 v130, s[40:41]
	s_mov_b32 m0, s57
	s_nop 0
	global_load_lds_dwordx4 v128, s[38:39]
	v_lshl_add_u64 v[204:205], s[38:39], 0, v[130:131]
	s_mov_b32 m0, s58
	s_nop 0
	global_load_lds_dwordx4 v[204:205], off
	s_waitcnt vmcnt(8)
	s_waitcnt lgkmcnt(0)
	s_barrier
	s_setprio 1
	s_waitcnt lgkmcnt(0)
	v_mfma_f32_16x16x32_bf16 v[60:63], v[156:159], v[220:223], v[60:63]
	v_mfma_f32_16x16x32_bf16 v[56:59], v[164:167], v[220:223], v[56:59]
	v_mfma_f32_16x16x32_bf16 v[52:55], v[156:159], v[228:231], v[52:55]
	v_mfma_f32_16x16x32_bf16 v[48:51], v[164:167], v[228:231], v[48:51]
	v_mfma_f32_16x16x32_bf16 v[28:31], v[156:159], v[236:239], v[28:31]
	v_mfma_f32_16x16x32_bf16 v[24:27], v[164:167], v[236:239], v[24:27]
	v_mfma_f32_16x16x32_bf16 v[20:23], v[156:159], v[244:247], v[20:23]
	v_mfma_f32_16x16x32_bf16 v[12:15], v[164:167], v[244:247], v[12:15]
	v_mfma_f32_16x16x32_bf16 v[60:63], v[160:163], v[224:227], v[60:63]
	v_mfma_f32_16x16x32_bf16 v[56:59], v[168:171], v[224:227], v[56:59]
	v_mfma_f32_16x16x32_bf16 v[52:55], v[160:163], v[232:235], v[52:55]
	v_mfma_f32_16x16x32_bf16 v[48:51], v[168:171], v[232:235], v[48:51]
	v_mfma_f32_16x16x32_bf16 v[28:31], v[160:163], v[240:243], v[28:31]
	v_mfma_f32_16x16x32_bf16 v[24:27], v[168:171], v[240:243], v[24:27]
	v_mfma_f32_16x16x32_bf16 v[20:23], v[160:163], v[248:251], v[20:23]
	v_mfma_f32_16x16x32_bf16 v[12:15], v[168:171], v[248:251], v[12:15]
	v_mfma_f32_16x16x32_bf16 v[44:47], v[172:175], v[220:223], v[44:47]
	v_mfma_f32_16x16x32_bf16 v[40:43], v[212:215], v[220:223], v[40:43]
	v_mfma_f32_16x16x32_bf16 v[36:39], v[172:175], v[228:231], v[36:39]
	v_mfma_f32_16x16x32_bf16 v[32:35], v[212:215], v[228:231], v[32:35]
	v_mfma_f32_16x16x32_bf16 v[16:19], v[172:175], v[236:239], v[16:19]
	v_mfma_f32_16x16x32_bf16 v[8:11], v[212:215], v[236:239], v[8:11]
	v_mfma_f32_16x16x32_bf16 v[4:7], v[172:175], v[244:247], v[4:7]
	v_mfma_f32_16x16x32_bf16 v[0:3], v[212:215], v[244:247], v[0:3]
	v_mfma_f32_16x16x32_bf16 v[44:47], v[176:179], v[224:227], v[44:47]
	v_mfma_f32_16x16x32_bf16 v[40:43], v[216:219], v[224:227], v[40:43]
	v_mfma_f32_16x16x32_bf16 v[36:39], v[176:179], v[232:235], v[36:39]
	v_mfma_f32_16x16x32_bf16 v[32:35], v[216:219], v[232:235], v[32:35]
	v_mfma_f32_16x16x32_bf16 v[16:19], v[176:179], v[240:243], v[16:19]
	v_mfma_f32_16x16x32_bf16 v[8:11], v[216:219], v[240:243], v[8:11]
	v_mfma_f32_16x16x32_bf16 v[4:7], v[176:179], v[248:251], v[4:7]
	v_mfma_f32_16x16x32_bf16 v[0:3], v[216:219], v[248:251], v[0:3]
	s_setprio 0
	s_barrier
	s_add_i32 s70, s70, 2
	s_add_u32 s68, s68, 0x10000
	s_addc_u32 s69, s69, 0
	s_add_u32 s36, s36, 0x10000
	s_addc_u32 s37, s37, 0
	s_cmp_gt_u32 s70, 41
	s_cbranch_scc0 .LBB0_1481
	s_and_b64 vcc, exec, s[18:19]
	s_cbranch_vccz .LBB0_1484
	s_barrier

.LBB0_1563:
	ds_read_b128 v[168:171], v165
	ds_read_b128 v[172:175], v165 offset:1024
	ds_read_b128 v[176:179], v165 offset:2048
	ds_read_b128 v[180:183], v165 offset:3072
	ds_read_b128 v[184:187], v166
	ds_read_b128 v[188:191], v166 offset:1024
	ds_read_b128 v[192:195], v166 offset:2048
	ds_read_b128 v[196:199], v166 offset:3072
	s_add_u32 s22, s20, 0xfffc0080
	s_addc_u32 s23, s21, -1
	s_cmp_eq_u32 s49, 12
	s_cselect_b32 s25, s9, s23
	s_cselect_b32 s24, s45, s22
	s_cselect_b32 s23, s11, s48
	s_cselect_b32 s22, s46, s47
	s_add_i32 m0, s17, 0xc000
	ds_read_b128 v[210:213], v167
	ds_read_b128 v[214:217], v167 offset:1024
	ds_read_b128 v[218:221], v167 offset:2048
	ds_read_b128 v[222:225], v167 offset:3072
	ds_read_b128 v[226:229], v167 offset:4096
	ds_read_b128 v[230:233], v167 offset:5120
	ds_read_b128 v[234:237], v167 offset:6144
	ds_read_b128 v[238:241], v167 offset:7168
	global_load_lds_dwordx4 v156, s[20:21]
	s_add_i32 m0, s17, 0xe000
	s_nop 0
	global_load_lds_dwordx4 v154, s[20:21]
	s_waitcnt vmcnt(8)
	s_waitcnt lgkmcnt(0)
	s_barrier
	s_setprio 1
	s_waitcnt lgkmcnt(0)
	v_mfma_f32_16x16x32_bf16 v[124:127], v[168:171], v[210:213], v[124:127]
	v_mfma_f32_16x16x32_bf16 v[116:119], v[176:179], v[210:213], v[116:119]
	v_mfma_f32_16x16x32_bf16 v[108:111], v[168:171], v[218:221], v[108:111]
	v_mfma_f32_16x16x32_bf16 v[100:103], v[176:179], v[218:221], v[100:103]
	v_mfma_f32_16x16x32_bf16 v[92:95], v[168:171], v[226:229], v[92:95]
	v_mfma_f32_16x16x32_bf16 v[84:87], v[176:179], v[226:229], v[84:87]
	v_mfma_f32_16x16x32_bf16 v[76:79], v[168:171], v[234:237], v[76:79]
	v_mfma_f32_16x16x32_bf16 v[68:71], v[176:179], v[234:237], v[68:71]
	v_mfma_f32_16x16x32_bf16 v[124:127], v[172:175], v[214:217], v[124:127]
	v_mfma_f32_16x16x32_bf16 v[116:119], v[180:183], v[214:217], v[116:119]
	v_mfma_f32_16x16x32_bf16 v[108:111], v[172:175], v[222:225], v[108:111]
	v_mfma_f32_16x16x32_bf16 v[100:103], v[180:183], v[222:225], v[100:103]
	v_mfma_f32_16x16x32_bf16 v[92:95], v[172:175], v[230:233], v[92:95]
	v_mfma_f32_16x16x32_bf16 v[84:87], v[180:183], v[230:233], v[84:87]
	v_mfma_f32_16x16x32_bf16 v[76:79], v[172:175], v[238:241], v[76:79]
	v_mfma_f32_16x16x32_bf16 v[68:71], v[180:183], v[238:241], v[68:71]
	v_mfma_f32_16x16x32_bf16 v[120:123], v[184:187], v[210:213], v[120:123]
	v_mfma_f32_16x16x32_bf16 v[112:115], v[192:195], v[210:213], v[112:115]
	v_mfma_f32_16x16x32_bf16 v[104:107], v[184:187], v[218:221], v[104:107]
	v_mfma_f32_16x16x32_bf16 v[96:99], v[192:195], v[218:221], v[96:99]
	v_mfma_f32_16x16x32_bf16 v[88:91], v[184:187], v[226:229], v[88:91]
	v_mfma_f32_16x16x32_bf16 v[80:83], v[192:195], v[226:229], v[80:83]
	v_mfma_f32_16x16x32_bf16 v[72:75], v[184:187], v[234:237], v[72:75]
	v_mfma_f32_16x16x32_bf16 v[64:67], v[192:195], v[234:237], v[64:67]
	v_mfma_f32_16x16x32_bf16 v[120:123], v[188:191], v[214:217], v[120:123]
	v_mfma_f32_16x16x32_bf16 v[112:115], v[196:199], v[214:217], v[112:115]
	v_mfma_f32_16x16x32_bf16 v[104:107], v[188:191], v[222:225], v[104:107]
	v_mfma_f32_16x16x32_bf16 v[96:99], v[196:199], v[222:225], v[96:99]
	v_mfma_f32_16x16x32_bf16 v[88:91], v[188:191], v[230:233], v[88:91]
	v_mfma_f32_16x16x32_bf16 v[80:83], v[196:199], v[230:233], v[80:83]
	v_mfma_f32_16x16x32_bf16 v[72:75], v[188:191], v[238:241], v[72:75]
	v_mfma_f32_16x16x32_bf16 v[64:67], v[196:199], v[238:241], v[64:67]
	s_setprio 0
	s_barrier
	s_add_i32 s50, s43, s33
	s_mov_b32 m0, s50
	s_cmp_lg_u32 s54, 0
	s_cbranch_scc1 .Lts0_skip1
	ds_read_b128 v[210:213], v167 offset:16384
	ds_read_b128 v[214:217], v167 offset:17408
	ds_read_b128 v[218:221], v167 offset:18432
	ds_read_b128 v[222:225], v167 offset:19456
	ds_read_b128 v[226:229], v167 offset:20480
	ds_read_b128 v[230:233], v167 offset:21504
	ds_read_b128 v[234:237], v167 offset:22528
	ds_read_b128 v[238:241], v167 offset:23552
.Lts0_skip1:
	global_load_lds_dwordx4 v132, s[22:23]
	s_add_i32 m0, s50, 0x2000
	s_add_u32 s50, s22, 0x4000
	s_addc_u32 s51, s23, 0
	s_add_i32 s52, s44, s33
	global_load_lds_dwordx4 v128, s[22:23]
	s_mov_b32 m0, s52
	v_lshl_add_u64 v[200:201], s[24:25], 0, v[130:131]
	global_load_lds_dwordx4 v132, s[50:51]
	s_add_i32 m0, s52, 0x2000
	s_nop 0
	global_load_lds_dwordx4 v128, s[50:51]
	v_lshl_add_u64 v[162:163], s[24:25], 0, v[134:135]
	s_mov_b32 m0, s17
	s_nop 0
	global_load_lds_dwordx4 v[162:163], off
	s_mov_b32 m0, s19
	s_nop 0
	global_load_lds_dwordx4 v[200:201], off
	s_waitcnt vmcnt(8)
	s_waitcnt lgkmcnt(0)
	s_barrier
	s_cmp_lg_u32 s54, 0
	s_cbranch_scc1 .Lts0_skip0
	s_setprio 1
	s_waitcnt lgkmcnt(0)
	v_mfma_f32_16x16x32_bf16 v[60:63], v[168:171], v[210:213], v[60:63]
	v_mfma_f32_16x16x32_bf16 v[52:55], v[176:179], v[210:213], v[52:55]
	v_mfma_f32_16x16x32_bf16 v[44:47], v[168:171], v[218:221], v[44:47]
	v_mfma_f32_16x16x32_bf16 v[36:39], v[176:179], v[218:221], v[36:39]
	v_mfma_f32_16x16x32_bf16 v[28:31], v[168:171], v[226:229], v[28:31]
	v_mfma_f32_16x16x32_bf16 v[20:23], v[176:179], v[226:229], v[20:23]
	v_mfma_f32_16x16x32_bf16 v[12:15], v[168:171], v[234:237], v[12:15]
	v_mfma_f32_16x16x32_bf16 v[4:7], v[176:179], v[234:237], v[4:7]
	v_mfma_f32_16x16x32_bf16 v[60:63], v[172:175], v[214:217], v[60:63]
	v_mfma_f32_16x16x32_bf16 v[52:55], v[180:183], v[214:217], v[52:55]
	v_mfma_f32_16x16x32_bf16 v[44:47], v[172:175], v[222:225], v[44:47]
	v_mfma_f32_16x16x32_bf16 v[36:39], v[180:183], v[222:225], v[36:39]
	v_mfma_f32_16x16x32_bf16 v[28:31], v[172:175], v[230:233], v[28:31]
	v_mfma_f32_16x16x32_bf16 v[20:23], v[180:183], v[230:233], v[20:23]
	v_mfma_f32_16x16x32_bf16 v[12:15], v[172:175], v[238:241], v[12:15]
	v_mfma_f32_16x16x32_bf16 v[4:7], v[180:183], v[238:241], v[4:7]
	v_mfma_f32_16x16x32_bf16 v[56:59], v[184:187], v[210:213], v[56:59]
	v_mfma_f32_16x16x32_bf16 v[48:51], v[192:195], v[210:213], v[48:51]
	v_mfma_f32_16x16x32_bf16 v[40:43], v[184:187], v[218:221], v[40:43]
	v_mfma_f32_16x16x32_bf16 v[32:35], v[192:195], v[218:221], v[32:35]
	v_mfma_f32_16x16x32_bf16 v[24:27], v[184:187], v[226:229], v[24:27]
	v_mfma_f32_16x16x32_bf16 v[16:19], v[192:195], v[226:229], v[16:19]
	v_mfma_f32_16x16x32_bf16 v[8:11], v[184:187], v[234:237], v[8:11]
	v_mfma_f32_16x16x32_bf16 v[0:3], v[192:195], v[234:237], v[0:3]
	v_mfma_f32_16x16x32_bf16 v[56:59], v[188:191], v[214:217], v[56:59]
	v_mfma_f32_16x16x32_bf16 v[48:51], v[196:199], v[214:217], v[48:51]
	v_mfma_f32_16x16x32_bf16 v[40:43], v[188:191], v[222:225], v[40:43]
	v_mfma_f32_16x16x32_bf16 v[32:35], v[196:199], v[222:225], v[32:35]
	v_mfma_f32_16x16x32_bf16 v[24:27], v[188:191], v[230:233], v[24:27]
	v_mfma_f32_16x16x32_bf16 v[16:19], v[196:199], v[230:233], v[16:19]
	v_mfma_f32_16x16x32_bf16 v[8:11], v[188:191], v[238:241], v[8:11]
	v_mfma_f32_16x16x32_bf16 v[0:3], v[196:199], v[238:241], v[0:3]
	s_setprio 0
.Lts0_skip0:
	s_barrier
	s_add_i32 s50, 0, 0x18000
	s_add_i32 s51, 0, 0x1c000
	v_add_u32_e32 v180, s50, v164
	v_add_u32_e32 v196, s51, v164
	ds_read_b128 v[168:171], v180
	ds_read_b128 v[172:175], v180 offset:1024
	ds_read_b128 v[176:179], v180 offset:2048
	ds_read_b128 v[180:183], v180 offset:3072
	ds_read_b128 v[184:187], v196
	ds_read_b128 v[188:191], v196 offset:1024
	ds_read_b128 v[192:195], v196 offset:2048
	ds_read_b128 v[196:199], v196 offset:3072
	s_add_u32 s24, s24, 0x40000
	s_addc_u32 s25, s25, 0
	s_mov_b32 m0, s36
	ds_read_b128 v[210:213], v167 offset:32768
	ds_read_b128 v[214:217], v167 offset:33792
	ds_read_b128 v[218:221], v167 offset:34816
	ds_read_b128 v[222:225], v167 offset:35840
	ds_read_b128 v[226:229], v167 offset:36864
	ds_read_b128 v[230:233], v167 offset:37888
	ds_read_b128 v[234:237], v167 offset:38912
	ds_read_b128 v[238:241], v167 offset:39936
	global_load_lds_dwordx4 v134, s[24:25]
	s_mov_b32 m0, s37
	s_nop 0
	global_load_lds_dwordx4 v130, s[24:25]
	s_waitcnt vmcnt(8)
	s_waitcnt lgkmcnt(0)
	s_barrier
	s_setprio 1
	s_waitcnt lgkmcnt(0)
	v_mfma_f32_16x16x32_bf16 v[124:127], v[168:171], v[210:213], v[124:127]
	v_mfma_f32_16x16x32_bf16 v[116:119], v[176:179], v[210:213], v[116:119]
	v_mfma_f32_16x16x32_bf16 v[108:111], v[168:171], v[218:221], v[108:111]
	v_mfma_f32_16x16x32_bf16 v[100:103], v[176:179], v[218:221], v[100:103]
	v_mfma_f32_16x16x32_bf16 v[92:95], v[168:171], v[226:229], v[92:95]
	v_mfma_f32_16x16x32_bf16 v[84:87], v[176:179], v[226:229], v[84:87]
	v_mfma_f32_16x16x32_bf16 v[76:79], v[168:171], v[234:237], v[76:79]
	v_mfma_f32_16x16x32_bf16 v[68:71], v[176:179], v[234:237], v[68:71]
	v_mfma_f32_16x16x32_bf16 v[124:127], v[172:175], v[214:217], v[124:127]
	v_mfma_f32_16x16x32_bf16 v[116:119], v[180:183], v[214:217], v[116:119]
	v_mfma_f32_16x16x32_bf16 v[108:111], v[172:175], v[222:225], v[108:111]
	v_mfma_f32_16x16x32_bf16 v[100:103], v[180:183], v[222:225], v[100:103]
	v_mfma_f32_16x16x32_bf16 v[92:95], v[172:175], v[230:233], v[92:95]
	v_mfma_f32_16x16x32_bf16 v[84:87], v[180:183], v[230:233], v[84:87]
	v_mfma_f32_16x16x32_bf16 v[76:79], v[172:175], v[238:241], v[76:79]
	v_mfma_f32_16x16x32_bf16 v[68:71], v[180:183], v[238:241], v[68:71]
	v_mfma_f32_16x16x32_bf16 v[120:123], v[184:187], v[210:213], v[120:123]
	v_mfma_f32_16x16x32_bf16 v[112:115], v[192:195], v[210:213], v[112:115]
	v_mfma_f32_16x16x32_bf16 v[104:107], v[184:187], v[218:221], v[104:107]
	v_mfma_f32_16x16x32_bf16 v[96:99], v[192:195], v[218:221], v[96:99]
	v_mfma_f32_16x16x32_bf16 v[88:91], v[184:187], v[226:229], v[88:91]
	v_mfma_f32_16x16x32_bf16 v[80:83], v[192:195], v[226:229], v[80:83]
	v_mfma_f32_16x16x32_bf16 v[72:75], v[184:187], v[234:237], v[72:75]
	v_mfma_f32_16x16x32_bf16 v[64:67], v[192:195], v[234:237], v[64:67]
	v_mfma_f32_16x16x32_bf16 v[120:123], v[188:191], v[214:217], v[120:123]
	v_mfma_f32_16x16x32_bf16 v[112:115], v[196:199], v[214:217], v[112:115]
	v_mfma_f32_16x16x32_bf16 v[104:107], v[188:191], v[222:225], v[104:107]
	v_mfma_f32_16x16x32_bf16 v[96:99], v[196:199], v[222:225], v[96:99]
	v_mfma_f32_16x16x32_bf16 v[88:91], v[188:191], v[230:233], v[88:91]
	v_mfma_f32_16x16x32_bf16 v[80:83], v[196:199], v[230:233], v[80:83]
	v_mfma_f32_16x16x32_bf16 v[72:75], v[188:191], v[238:241], v[72:75]
	v_mfma_f32_16x16x32_bf16 v[64:67], v[196:199], v[238:241], v[64:67]
	s_setprio 0
	s_barrier
	s_add_u32 s24, s22, 0x8000
	s_addc_u32 s25, s23, 0
	s_add_i32 s50, s50, s33
	s_mov_b32 m0, s50
	s_cmp_lg_u32 s54, 0
	s_cbranch_scc1 .Lts0_skip3
	ds_read_b128 v[210:213], v167 offset:49152
	ds_read_b128 v[214:217], v167 offset:50176
	ds_read_b128 v[218:221], v167 offset:51200
	ds_read_b128 v[222:225], v167 offset:52224
	ds_read_b128 v[226:229], v167 offset:53248
	ds_read_b128 v[230:233], v167 offset:54272
	ds_read_b128 v[234:237], v167 offset:55296
	ds_read_b128 v[238:241], v167 offset:56320
.Lts0_skip3:
	global_load_lds_dwordx4 v132, s[24:25]
	s_add_i32 m0, s50, 0x2000
	s_add_u32 s22, s22, 0xc000
	v_lshl_add_u64 v[204:205], s[24:25], 0, v[128:129]
	s_addc_u32 s23, s23, 0
	s_add_i32 s24, s51, s33
	global_load_lds_dwordx4 v[204:205], off
	s_mov_b32 m0, s24
	v_lshl_add_u64 v[162:163], v[162:163], 0, s[4:5]
	global_load_lds_dwordx4 v132, s[22:23]
	s_add_i32 m0, s24, 0x2000
	s_nop 0
	global_load_lds_dwordx4 v128, s[22:23]
	s_mov_b32 m0, s40
	s_nop 0
	global_load_lds_dwordx4 v[162:163], off
	v_lshl_add_u64 v[162:163], v[200:201], 0, s[4:5]
	s_mov_b32 m0, s41
	s_nop 0
	global_load_lds_dwordx4 v[162:163], off
	s_waitcnt vmcnt(8)
	s_waitcnt lgkmcnt(0)
	s_barrier
	s_cmp_lg_u32 s54, 0
	s_cbranch_scc1 .Lts0_skip2
	s_setprio 1
	s_waitcnt lgkmcnt(0)
	v_mfma_f32_16x16x32_bf16 v[60:63], v[168:171], v[210:213], v[60:63]
	v_mfma_f32_16x16x32_bf16 v[52:55], v[176:179], v[210:213], v[52:55]
	v_mfma_f32_16x16x32_bf16 v[44:47], v[168:171], v[218:221], v[44:47]
	v_mfma_f32_16x16x32_bf16 v[36:39], v[176:179], v[218:221], v[36:39]
	v_mfma_f32_16x16x32_bf16 v[28:31], v[168:171], v[226:229], v[28:31]
	v_mfma_f32_16x16x32_bf16 v[20:23], v[176:179], v[226:229], v[20:23]
	v_mfma_f32_16x16x32_bf16 v[12:15], v[168:171], v[234:237], v[12:15]
	v_mfma_f32_16x16x32_bf16 v[4:7], v[176:179], v[234:237], v[4:7]
	v_mfma_f32_16x16x32_bf16 v[60:63], v[172:175], v[214:217], v[60:63]
	v_mfma_f32_16x16x32_bf16 v[52:55], v[180:183], v[214:217], v[52:55]
	v_mfma_f32_16x16x32_bf16 v[44:47], v[172:175], v[222:225], v[44:47]
	v_mfma_f32_16x16x32_bf16 v[36:39], v[180:183], v[222:225], v[36:39]
	v_mfma_f32_16x16x32_bf16 v[28:31], v[172:175], v[230:233], v[28:31]
	v_mfma_f32_16x16x32_bf16 v[20:23], v[180:183], v[230:233], v[20:23]
	v_mfma_f32_16x16x32_bf16 v[12:15], v[172:175], v[238:241], v[12:15]
	v_mfma_f32_16x16x32_bf16 v[4:7], v[180:183], v[238:241], v[4:7]
	v_mfma_f32_16x16x32_bf16 v[56:59], v[184:187], v[210:213], v[56:59]
	v_mfma_f32_16x16x32_bf16 v[48:51], v[192:195], v[210:213], v[48:51]
	v_mfma_f32_16x16x32_bf16 v[40:43], v[184:187], v[218:221], v[40:43]
	v_mfma_f32_16x16x32_bf16 v[32:35], v[192:195], v[218:221], v[32:35]
	v_mfma_f32_16x16x32_bf16 v[24:27], v[184:187], v[226:229], v[24:27]
	v_mfma_f32_16x16x32_bf16 v[16:19], v[192:195], v[226:229], v[16:19]
	v_mfma_f32_16x16x32_bf16 v[8:11], v[184:187], v[234:237], v[8:11]
	v_mfma_f32_16x16x32_bf16 v[0:3], v[192:195], v[234:237], v[0:3]
	v_mfma_f32_16x16x32_bf16 v[56:59], v[188:191], v[214:217], v[56:59]
	v_mfma_f32_16x16x32_bf16 v[48:51], v[196:199], v[214:217], v[48:51]
	v_mfma_f32_16x16x32_bf16 v[40:43], v[188:191], v[222:225], v[40:43]
	v_mfma_f32_16x16x32_bf16 v[32:35], v[196:199], v[222:225], v[32:35]
	v_mfma_f32_16x16x32_bf16 v[24:27], v[188:191], v[230:233], v[24:27]
	v_mfma_f32_16x16x32_bf16 v[16:19], v[196:199], v[230:233], v[16:19]
	v_mfma_f32_16x16x32_bf16 v[8:11], v[188:191], v[238:241], v[8:11]
	v_mfma_f32_16x16x32_bf16 v[0:3], v[196:199], v[238:241], v[0:3]
	s_setprio 0

.LBB0_1645:
	v_add_u32_e32 v168, s69, v182
	v_add_u32_e32 v204, s70, v182
	ds_read_b128 v[156:159], v168
	ds_read_b128 v[160:163], v168 offset:1024
	ds_read_b128 v[164:167], v168 offset:2048
	ds_read_b128 v[168:171], v168 offset:3072
	ds_read_b128 v[172:175], v204
	ds_read_b128 v[176:179], v204 offset:1024
	ds_read_b128 v[212:215], v204 offset:2048
	ds_read_b128 v[216:219], v204 offset:3072
	s_add_u32 s38, s36, 0x4000
	s_addc_u32 s39, s37, 0
	s_cmp_eq_u32 s47, 40
	s_cselect_b32 s42, s0, s38
	s_cselect_b32 s43, s1, s39
	s_cselect_b32 s40, s34, s45
	s_cselect_b32 s41, s35, s46
	s_add_u32 s38, s42, 0x8000
	s_addc_u32 s39, s43, 0
	s_add_i32 m0, s56, 0xc000
	ds_read_b128 v[220:223], v199
	ds_read_b128 v[224:227], v199 offset:1024
	ds_read_b128 v[228:231], v199 offset:2048
	ds_read_b128 v[232:235], v199 offset:3072
	ds_read_b128 v[236:239], v199 offset:4096
	ds_read_b128 v[240:243], v199 offset:5120
	ds_read_b128 v[244:247], v199 offset:6144
	ds_read_b128 v[248:251], v199 offset:7168
	global_load_lds_dwordx4 v150, s[36:37]
	s_add_i32 m0, s56, 0xe000
	s_nop 0
	global_load_lds_dwordx4 v148, s[36:37]
	s_waitcnt vmcnt(8)
	s_waitcnt lgkmcnt(0)
	s_barrier
	s_setprio 1
	s_waitcnt lgkmcnt(0)
	v_mfma_f32_16x16x32_bf16 v[124:127], v[156:159], v[220:223], v[124:127]
	v_mfma_f32_16x16x32_bf16 v[120:123], v[164:167], v[220:223], v[120:123]
	v_mfma_f32_16x16x32_bf16 v[116:119], v[156:159], v[228:231], v[116:119]
	v_mfma_f32_16x16x32_bf16 v[112:115], v[164:167], v[228:231], v[112:115]
	v_mfma_f32_16x16x32_bf16 v[92:95], v[156:159], v[236:239], v[92:95]
	v_mfma_f32_16x16x32_bf16 v[88:91], v[164:167], v[236:239], v[88:91]
	v_mfma_f32_16x16x32_bf16 v[84:87], v[156:159], v[244:247], v[84:87]
	v_mfma_f32_16x16x32_bf16 v[80:83], v[164:167], v[244:247], v[80:83]
	v_mfma_f32_16x16x32_bf16 v[124:127], v[160:163], v[224:227], v[124:127]
	v_mfma_f32_16x16x32_bf16 v[120:123], v[168:171], v[224:227], v[120:123]
	v_mfma_f32_16x16x32_bf16 v[116:119], v[160:163], v[232:235], v[116:119]
	v_mfma_f32_16x16x32_bf16 v[112:115], v[168:171], v[232:235], v[112:115]
	v_mfma_f32_16x16x32_bf16 v[92:95], v[160:163], v[240:243], v[92:95]
	v_mfma_f32_16x16x32_bf16 v[88:91], v[168:171], v[240:243], v[88:91]
	v_mfma_f32_16x16x32_bf16 v[84:87], v[160:163], v[248:251], v[84:87]
	v_mfma_f32_16x16x32_bf16 v[80:83], v[168:171], v[248:251], v[80:83]
	v_mfma_f32_16x16x32_bf16 v[108:111], v[172:175], v[220:223], v[108:111]
	v_mfma_f32_16x16x32_bf16 v[104:107], v[212:215], v[220:223], v[104:107]
	v_mfma_f32_16x16x32_bf16 v[100:103], v[172:175], v[228:231], v[100:103]
	v_mfma_f32_16x16x32_bf16 v[96:99], v[212:215], v[228:231], v[96:99]
	v_mfma_f32_16x16x32_bf16 v[76:79], v[172:175], v[236:239], v[76:79]
	v_mfma_f32_16x16x32_bf16 v[72:75], v[212:215], v[236:239], v[72:75]
	v_mfma_f32_16x16x32_bf16 v[68:71], v[172:175], v[244:247], v[68:71]
	v_mfma_f32_16x16x32_bf16 v[64:67], v[212:215], v[244:247], v[64:67]
	v_mfma_f32_16x16x32_bf16 v[108:111], v[176:179], v[224:227], v[108:111]
	v_mfma_f32_16x16x32_bf16 v[104:107], v[216:219], v[224:227], v[104:107]
	v_mfma_f32_16x16x32_bf16 v[100:103], v[176:179], v[232:235], v[100:103]
	v_mfma_f32_16x16x32_bf16 v[96:99], v[216:219], v[232:235], v[96:99]
	v_mfma_f32_16x16x32_bf16 v[76:79], v[176:179], v[240:243], v[76:79]
	v_mfma_f32_16x16x32_bf16 v[72:75], v[216:219], v[240:243], v[72:75]
	v_mfma_f32_16x16x32_bf16 v[68:71], v[176:179], v[248:251], v[68:71]
	v_mfma_f32_16x16x32_bf16 v[64:67], v[216:219], v[248:251], v[64:67]
	s_setprio 0
	s_barrier
	s_add_i32 s48, s69, s55
	s_mov_b32 m0, s48
	ds_read_b128 v[220:223], v199 offset:16384
	ds_read_b128 v[224:227], v199 offset:17408
	ds_read_b128 v[228:231], v199 offset:18432
	ds_read_b128 v[232:235], v199 offset:19456
	ds_read_b128 v[236:239], v199 offset:20480
	ds_read_b128 v[240:243], v199 offset:21504
	ds_read_b128 v[244:247], v199 offset:22528
	ds_read_b128 v[248:251], v199 offset:23552
	global_load_lds_dwordx4 v128, s[40:41]
	s_add_i32 m0, s48, 0x2000
	s_add_u32 s48, s40, 0x4000
	s_addc_u32 s49, s41, 0
	s_add_i32 s50, s70, s55
	global_load_lds_dwordx4 v130, s[40:41]
	s_mov_b32 m0, s50
	s_nop 0
	global_load_lds_dwordx4 v128, s[48:49]
	s_add_i32 m0, s50, 0x2000
	s_nop 0
	global_load_lds_dwordx4 v130, s[48:49]
	s_mov_b32 m0, s56
	s_nop 0
	global_load_lds_dwordx4 v128, s[42:43]
	v_lshl_add_u64 v[204:205], s[42:43], 0, v[130:131]
	s_mov_b32 m0, s57
	s_nop 0
	global_load_lds_dwordx4 v[204:205], off
	s_waitcnt vmcnt(8)
	s_waitcnt lgkmcnt(0)
	s_barrier
	s_setprio 1
	s_waitcnt lgkmcnt(0)
	v_mfma_f32_16x16x32_bf16 v[60:63], v[156:159], v[220:223], v[60:63]
	v_mfma_f32_16x16x32_bf16 v[56:59], v[164:167], v[220:223], v[56:59]
	v_mfma_f32_16x16x32_bf16 v[52:55], v[156:159], v[228:231], v[52:55]
	v_mfma_f32_16x16x32_bf16 v[48:51], v[164:167], v[228:231], v[48:51]
	v_mfma_f32_16x16x32_bf16 v[28:31], v[156:159], v[236:239], v[28:31]
	v_mfma_f32_16x16x32_bf16 v[24:27], v[164:167], v[236:239], v[24:27]
	v_mfma_f32_16x16x32_bf16 v[20:23], v[156:159], v[244:247], v[20:23]
	v_mfma_f32_16x16x32_bf16 v[12:15], v[164:167], v[244:247], v[12:15]
	v_mfma_f32_16x16x32_bf16 v[60:63], v[160:163], v[224:227], v[60:63]
	v_mfma_f32_16x16x32_bf16 v[56:59], v[168:171], v[224:227], v[56:59]
	v_mfma_f32_16x16x32_bf16 v[52:55], v[160:163], v[232:235], v[52:55]
	v_mfma_f32_16x16x32_bf16 v[48:51], v[168:171], v[232:235], v[48:51]
	v_mfma_f32_16x16x32_bf16 v[28:31], v[160:163], v[240:243], v[28:31]
	v_mfma_f32_16x16x32_bf16 v[24:27], v[168:171], v[240:243], v[24:27]
	v_mfma_f32_16x16x32_bf16 v[20:23], v[160:163], v[248:251], v[20:23]
	v_mfma_f32_16x16x32_bf16 v[12:15], v[168:171], v[248:251], v[12:15]
	v_mfma_f32_16x16x32_bf16 v[44:47], v[172:175], v[220:223], v[44:47]
	v_mfma_f32_16x16x32_bf16 v[40:43], v[212:215], v[220:223], v[40:43]
	v_mfma_f32_16x16x32_bf16 v[36:39], v[172:175], v[228:231], v[36:39]
	v_mfma_f32_16x16x32_bf16 v[32:35], v[212:215], v[228:231], v[32:35]
	v_mfma_f32_16x16x32_bf16 v[16:19], v[172:175], v[236:239], v[16:19]
	v_mfma_f32_16x16x32_bf16 v[8:11], v[212:215], v[236:239], v[8:11]
	v_mfma_f32_16x16x32_bf16 v[4:7], v[172:175], v[244:247], v[4:7]
	v_mfma_f32_16x16x32_bf16 v[0:3], v[212:215], v[244:247], v[0:3]
	v_mfma_f32_16x16x32_bf16 v[44:47], v[176:179], v[224:227], v[44:47]
	v_mfma_f32_16x16x32_bf16 v[40:43], v[216:219], v[224:227], v[40:43]
	v_mfma_f32_16x16x32_bf16 v[36:39], v[176:179], v[232:235], v[36:39]
	v_mfma_f32_16x16x32_bf16 v[32:35], v[216:219], v[232:235], v[32:35]
	v_mfma_f32_16x16x32_bf16 v[16:19], v[176:179], v[240:243], v[16:19]
	v_mfma_f32_16x16x32_bf16 v[8:11], v[216:219], v[240:243], v[8:11]
	v_mfma_f32_16x16x32_bf16 v[4:7], v[176:179], v[248:251], v[4:7]
	v_mfma_f32_16x16x32_bf16 v[0:3], v[216:219], v[248:251], v[0:3]
	s_setprio 0
	s_barrier
	s_add_i32 s48, 0, 0x18000
	s_add_i32 s49, 0, 0x1c000
	v_add_u32_e32 v168, s48, v182
	v_add_u32_e32 v204, s49, v182
	ds_read_b128 v[156:159], v168
	ds_read_b128 v[160:163], v168 offset:1024
	ds_read_b128 v[164:167], v168 offset:2048
	ds_read_b128 v[168:171], v168 offset:3072
	ds_read_b128 v[172:175], v204
	ds_read_b128 v[176:179], v204 offset:1024
	ds_read_b128 v[212:215], v204 offset:2048
	ds_read_b128 v[216:219], v204 offset:3072
	s_add_u32 s42, s42, 0x4000
	s_addc_u32 s43, s43, 0
	s_mov_b32 m0, s58
	ds_read_b128 v[220:223], v199 offset:32768
	ds_read_b128 v[224:227], v199 offset:33792
	ds_read_b128 v[228:231], v199 offset:34816
	ds_read_b128 v[232:235], v199 offset:35840
	ds_read_b128 v[236:239], v199 offset:36864
	ds_read_b128 v[240:243], v199 offset:37888
	ds_read_b128 v[244:247], v199 offset:38912
	ds_read_b128 v[248:251], v199 offset:39936
	global_load_lds_dwordx4 v128, s[42:43]
	s_mov_b32 m0, s59
	s_nop 0
	global_load_lds_dwordx4 v130, s[42:43]
	s_waitcnt vmcnt(8)
	s_waitcnt lgkmcnt(0)
	s_barrier
	s_setprio 1
	s_waitcnt lgkmcnt(0)
	v_mfma_f32_16x16x32_bf16 v[124:127], v[156:159], v[220:223], v[124:127]
	v_mfma_f32_16x16x32_bf16 v[120:123], v[164:167], v[220:223], v[120:123]
	v_mfma_f32_16x16x32_bf16 v[116:119], v[156:159], v[228:231], v[116:119]
	v_mfma_f32_16x16x32_bf16 v[112:115], v[164:167], v[228:231], v[112:115]
	v_mfma_f32_16x16x32_bf16 v[92:95], v[156:159], v[236:239], v[92:95]
	v_mfma_f32_16x16x32_bf16 v[88:91], v[164:167], v[236:239], v[88:91]
	v_mfma_f32_16x16x32_bf16 v[84:87], v[156:159], v[244:247], v[84:87]
	v_mfma_f32_16x16x32_bf16 v[80:83], v[164:167], v[244:247], v[80:83]
	v_mfma_f32_16x16x32_bf16 v[124:127], v[160:163], v[224:227], v[124:127]
	v_mfma_f32_16x16x32_bf16 v[120:123], v[168:171], v[224:227], v[120:123]
	v_mfma_f32_16x16x32_bf16 v[116:119], v[160:163], v[232:235], v[116:119]
	v_mfma_f32_16x16x32_bf16 v[112:115], v[168:171], v[232:235], v[112:115]
	v_mfma_f32_16x16x32_bf16 v[92:95], v[160:163], v[240:243], v[92:95]
	v_mfma_f32_16x16x32_bf16 v[88:91], v[168:171], v[240:243], v[88:91]
	v_mfma_f32_16x16x32_bf16 v[84:87], v[160:163], v[248:251], v[84:87]
	v_mfma_f32_16x16x32_bf16 v[80:83], v[168:171], v[248:251], v[80:83]
	v_mfma_f32_16x16x32_bf16 v[108:111], v[172:175], v[220:223], v[108:111]
	v_mfma_f32_16x16x32_bf16 v[104:107], v[212:215], v[220:223], v[104:107]
	v_mfma_f32_16x16x32_bf16 v[100:103], v[172:175], v[228:231], v[100:103]
	v_mfma_f32_16x16x32_bf16 v[96:99], v[212:215], v[228:231], v[96:99]
	v_mfma_f32_16x16x32_bf16 v[76:79], v[172:175], v[236:239], v[76:79]
	v_mfma_f32_16x16x32_bf16 v[72:75], v[212:215], v[236:239], v[72:75]
	v_mfma_f32_16x16x32_bf16 v[68:71], v[172:175], v[244:247], v[68:71]
	v_mfma_f32_16x16x32_bf16 v[64:67], v[212:215], v[244:247], v[64:67]
	v_mfma_f32_16x16x32_bf16 v[108:111], v[176:179], v[224:227], v[108:111]
	v_mfma_f32_16x16x32_bf16 v[104:107], v[216:219], v[224:227], v[104:107]
	v_mfma_f32_16x16x32_bf16 v[100:103], v[176:179], v[232:235], v[100:103]
	v_mfma_f32_16x16x32_bf16 v[96:99], v[216:219], v[232:235], v[96:99]
	v_mfma_f32_16x16x32_bf16 v[76:79], v[176:179], v[240:243], v[76:79]
	v_mfma_f32_16x16x32_bf16 v[72:75], v[216:219], v[240:243], v[72:75]
	v_mfma_f32_16x16x32_bf16 v[68:71], v[176:179], v[248:251], v[68:71]
	v_mfma_f32_16x16x32_bf16 v[64:67], v[216:219], v[248:251], v[64:67]
	s_setprio 0
	s_barrier
	s_add_u32 s42, s40, 0x8000
	s_addc_u32 s43, s41, 0
	s_add_i32 s48, s48, s55
	s_mov_b32 m0, s48
	ds_read_b128 v[220:223], v199 offset:49152
	ds_read_b128 v[224:227], v199 offset:50176
	ds_read_b128 v[228:231], v199 offset:51200
	ds_read_b128 v[232:235], v199 offset:52224
	ds_read_b128 v[236:239], v199 offset:53248
	ds_read_b128 v[240:243], v199 offset:54272
	ds_read_b128 v[244:247], v199 offset:55296
	ds_read_b128 v[248:251], v199 offset:56320
	global_load_lds_dwordx4 v128, s[42:43]
	s_add_i32 m0, s48, 0x2000
	s_add_u32 s40, s40, 0xc000
	v_lshl_add_u64 v[204:205], s[42:43], 0, v[130:131]
	s_addc_u32 s41, s41, 0
	s_add_i32 s42, s49, s55
	global_load_lds_dwordx4 v[204:205], off
	s_mov_b32 m0, s42
	s_nop 0
	global_load_lds_dwordx4 v128, s[40:41]
	s_add_i32 m0, s42, 0x2000
	s_nop 0
	global_load_lds_dwordx4 v130, s[40:41]
	s_mov_b32 m0, s65
	s_nop 0
	global_load_lds_dwordx4 v128, s[38:39]
	v_lshl_add_u64 v[204:205], s[38:39], 0, v[130:131]
	s_mov_b32 m0, s66
	s_nop 0
	global_load_lds_dwordx4 v[204:205], off
	s_waitcnt vmcnt(8)
	s_waitcnt lgkmcnt(0)
	s_barrier
	s_setprio 1
	s_waitcnt lgkmcnt(0)
	v_mfma_f32_16x16x32_bf16 v[60:63], v[156:159], v[220:223], v[60:63]
	v_mfma_f32_16x16x32_bf16 v[56:59], v[164:167], v[220:223], v[56:59]
	v_mfma_f32_16x16x32_bf16 v[52:55], v[156:159], v[228:231], v[52:55]
	v_mfma_f32_16x16x32_bf16 v[48:51], v[164:167], v[228:231], v[48:51]
	v_mfma_f32_16x16x32_bf16 v[28:31], v[156:159], v[236:239], v[28:31]
	v_mfma_f32_16x16x32_bf16 v[24:27], v[164:167], v[236:239], v[24:27]
	v_mfma_f32_16x16x32_bf16 v[20:23], v[156:159], v[244:247], v[20:23]
	v_mfma_f32_16x16x32_bf16 v[12:15], v[164:167], v[244:247], v[12:15]
	v_mfma_f32_16x16x32_bf16 v[60:63], v[160:163], v[224:227], v[60:63]
	v_mfma_f32_16x16x32_bf16 v[56:59], v[168:171], v[224:227], v[56:59]
	v_mfma_f32_16x16x32_bf16 v[52:55], v[160:163], v[232:235], v[52:55]
	v_mfma_f32_16x16x32_bf16 v[48:51], v[168:171], v[232:235], v[48:51]
	v_mfma_f32_16x16x32_bf16 v[28:31], v[160:163], v[240:243], v[28:31]
	v_mfma_f32_16x16x32_bf16 v[24:27], v[168:171], v[240:243], v[24:27]
	v_mfma_f32_16x16x32_bf16 v[20:23], v[160:163], v[248:251], v[20:23]
	v_mfma_f32_16x16x32_bf16 v[12:15], v[168:171], v[248:251], v[12:15]
	v_mfma_f32_16x16x32_bf16 v[44:47], v[172:175], v[220:223], v[44:47]
	v_mfma_f32_16x16x32_bf16 v[40:43], v[212:215], v[220:223], v[40:43]
	v_mfma_f32_16x16x32_bf16 v[36:39], v[172:175], v[228:231], v[36:39]
	v_mfma_f32_16x16x32_bf16 v[32:35], v[212:215], v[228:231], v[32:35]
	v_mfma_f32_16x16x32_bf16 v[16:19], v[172:175], v[236:239], v[16:19]
	v_mfma_f32_16x16x32_bf16 v[8:11], v[212:215], v[236:239], v[8:11]
	v_mfma_f32_16x16x32_bf16 v[4:7], v[172:175], v[244:247], v[4:7]
	v_mfma_f32_16x16x32_bf16 v[0:3], v[212:215], v[244:247], v[0:3]
	v_mfma_f32_16x16x32_bf16 v[44:47], v[176:179], v[224:227], v[44:47]
	v_mfma_f32_16x16x32_bf16 v[40:43], v[216:219], v[224:227], v[40:43]
	v_mfma_f32_16x16x32_bf16 v[36:39], v[176:179], v[232:235], v[36:39]
	v_mfma_f32_16x16x32_bf16 v[32:35], v[216:219], v[232:235], v[32:35]
	v_mfma_f32_16x16x32_bf16 v[16:19], v[176:179], v[240:243], v[16:19]
	v_mfma_f32_16x16x32_bf16 v[8:11], v[216:219], v[240:243], v[8:11]
	v_mfma_f32_16x16x32_bf16 v[4:7], v[176:179], v[248:251], v[4:7]
	v_mfma_f32_16x16x32_bf16 v[0:3], v[216:219], v[248:251], v[0:3]
	s_setprio 0
	s_barrier
	s_add_i32 s47, s47, 2
	s_add_u32 s45, s45, 0x10000
	s_addc_u32 s46, s46, 0
	s_add_u32 s36, s36, 0x10000
	s_addc_u32 s37, s37, 0
	s_cmp_gt_u32 s47, 41
	s_cbranch_scc0 .LBB0_1645
	s_and_b64 vcc, exec, s[2:3]
	s_cbranch_vccz .LBB0_1648
	s_barrier

.LBB0_1729:
	ds_read_b128 v[128:131], v210
	ds_read_b128 v[132:135], v210 offset:1024
	ds_read_b128 v[136:139], v210 offset:2048
	ds_read_b128 v[140:143], v210 offset:3072
	ds_read_b128 v[144:147], v211
	ds_read_b128 v[148:151], v211 offset:1024
	ds_read_b128 v[152:155], v211 offset:2048
	ds_read_b128 v[156:159], v211 offset:3072
	s_add_u32 s26, s6, 0xfffc0080
	s_addc_u32 s27, s7, -1
	s_cmp_eq_u32 s35, 12
	s_cselect_b32 s29, s1, s27
	s_cselect_b32 s28, s19, s26
	s_cselect_b32 s27, s21, s34
	s_cselect_b32 s26, s30, s31
	s_add_i32 m0, s42, 0xc000
	ds_read_b128 v[160:163], v212
	ds_read_b128 v[164:167], v212 offset:1024
	ds_read_b128 v[194:197], v212 offset:2048
	ds_read_b128 v[214:217], v212 offset:3072
	ds_read_b128 v[218:221], v212 offset:4096
	ds_read_b128 v[222:225], v212 offset:5120
	ds_read_b128 v[226:229], v212 offset:6144
	ds_read_b128 v[230:233], v212 offset:7168
	global_load_lds_dwordx4 v188, s[6:7]
	s_add_i32 m0, s42, 0xe000
	s_nop 0
	global_load_lds_dwordx4 v186, s[6:7]
	s_waitcnt vmcnt(8)
	s_waitcnt lgkmcnt(0)
	s_barrier
	s_setprio 1
	s_waitcnt lgkmcnt(0)
	v_mfma_f32_16x16x32_bf16 v[124:127], v[128:131], v[160:163], v[124:127]
	v_mfma_f32_16x16x32_bf16 v[120:123], v[136:139], v[160:163], v[120:123]
	v_mfma_f32_16x16x32_bf16 v[116:119], v[128:131], v[194:197], v[116:119]
	v_mfma_f32_16x16x32_bf16 v[112:115], v[136:139], v[194:197], v[112:115]
	v_mfma_f32_16x16x32_bf16 v[108:111], v[128:131], v[218:221], v[108:111]
	v_mfma_f32_16x16x32_bf16 v[104:107], v[136:139], v[218:221], v[104:107]
	v_mfma_f32_16x16x32_bf16 v[100:103], v[128:131], v[226:229], v[100:103]
	v_mfma_f32_16x16x32_bf16 v[96:99], v[136:139], v[226:229], v[96:99]
	v_mfma_f32_16x16x32_bf16 v[124:127], v[132:135], v[164:167], v[124:127]
	v_mfma_f32_16x16x32_bf16 v[120:123], v[140:143], v[164:167], v[120:123]
	v_mfma_f32_16x16x32_bf16 v[116:119], v[132:135], v[214:217], v[116:119]
	v_mfma_f32_16x16x32_bf16 v[112:115], v[140:143], v[214:217], v[112:115]
	v_mfma_f32_16x16x32_bf16 v[108:111], v[132:135], v[222:225], v[108:111]
	v_mfma_f32_16x16x32_bf16 v[104:107], v[140:143], v[222:225], v[104:107]
	v_mfma_f32_16x16x32_bf16 v[100:103], v[132:135], v[230:233], v[100:103]
	v_mfma_f32_16x16x32_bf16 v[96:99], v[140:143], v[230:233], v[96:99]
	v_mfma_f32_16x16x32_bf16 v[60:63], v[144:147], v[160:163], v[60:63]
	v_mfma_f32_16x16x32_bf16 v[56:59], v[152:155], v[160:163], v[56:59]
	v_mfma_f32_16x16x32_bf16 v[52:55], v[144:147], v[194:197], v[52:55]
	v_mfma_f32_16x16x32_bf16 v[48:51], v[152:155], v[194:197], v[48:51]
	v_mfma_f32_16x16x32_bf16 v[44:47], v[144:147], v[218:221], v[44:47]
	v_mfma_f32_16x16x32_bf16 v[40:43], v[152:155], v[218:221], v[40:43]
	v_mfma_f32_16x16x32_bf16 v[36:39], v[144:147], v[226:229], v[36:39]
	v_mfma_f32_16x16x32_bf16 v[32:35], v[152:155], v[226:229], v[32:35]
	v_mfma_f32_16x16x32_bf16 v[60:63], v[148:151], v[164:167], v[60:63]
	v_mfma_f32_16x16x32_bf16 v[56:59], v[156:159], v[164:167], v[56:59]
	v_mfma_f32_16x16x32_bf16 v[52:55], v[148:151], v[214:217], v[52:55]
	v_mfma_f32_16x16x32_bf16 v[48:51], v[156:159], v[214:217], v[48:51]
	v_mfma_f32_16x16x32_bf16 v[44:47], v[148:151], v[222:225], v[44:47]
	v_mfma_f32_16x16x32_bf16 v[40:43], v[156:159], v[222:225], v[40:43]
	v_mfma_f32_16x16x32_bf16 v[36:39], v[148:151], v[230:233], v[36:39]
	v_mfma_f32_16x16x32_bf16 v[32:35], v[156:159], v[230:233], v[32:35]
	s_setprio 0
	s_barrier
	s_add_i32 s61, s56, s41
	s_mov_b32 m0, s61
	ds_read_b128 v[160:163], v212 offset:16384
	ds_read_b128 v[164:167], v212 offset:17408
	ds_read_b128 v[194:197], v212 offset:18432
	ds_read_b128 v[214:217], v212 offset:19456
	ds_read_b128 v[218:221], v212 offset:20480
	ds_read_b128 v[222:225], v212 offset:21504
	ds_read_b128 v[226:229], v212 offset:22528
	ds_read_b128 v[230:233], v212 offset:23552
	global_load_lds_dwordx4 v170, s[26:27]
	s_add_i32 m0, s61, 0x2000
	s_add_u32 s62, s26, 0x4000
	s_addc_u32 s63, s27, 0
	s_add_i32 s61, s57, s41
	global_load_lds_dwordx4 v174, s[26:27]
	s_mov_b32 m0, s61
	v_lshl_add_u64 v[204:205], s[28:29], 0, v[172:173]
	global_load_lds_dwordx4 v170, s[62:63]
	s_add_i32 m0, s61, 0x2000
	s_nop 0
	global_load_lds_dwordx4 v174, s[62:63]
	v_lshl_add_u64 v[198:199], s[28:29], 0, v[168:169]
	s_mov_b32 m0, s42
	s_nop 0
	global_load_lds_dwordx4 v[198:199], off
	s_mov_b32 m0, s43
	s_nop 0
	global_load_lds_dwordx4 v[204:205], off
	s_waitcnt vmcnt(8)
	s_waitcnt lgkmcnt(0)
	s_barrier
	s_setprio 1
	s_waitcnt lgkmcnt(0)
	v_mfma_f32_16x16x32_bf16 v[92:95], v[128:131], v[160:163], v[92:95]
	v_mfma_f32_16x16x32_bf16 v[88:91], v[136:139], v[160:163], v[88:91]
	v_mfma_f32_16x16x32_bf16 v[84:87], v[128:131], v[194:197], v[84:87]
	v_mfma_f32_16x16x32_bf16 v[80:83], v[136:139], v[194:197], v[80:83]
	v_mfma_f32_16x16x32_bf16 v[76:79], v[128:131], v[218:221], v[76:79]
	v_mfma_f32_16x16x32_bf16 v[72:75], v[136:139], v[218:221], v[72:75]
	v_mfma_f32_16x16x32_bf16 v[68:71], v[128:131], v[226:229], v[68:71]
	v_mfma_f32_16x16x32_bf16 v[64:67], v[136:139], v[226:229], v[64:67]
	v_mfma_f32_16x16x32_bf16 v[92:95], v[132:135], v[164:167], v[92:95]
	v_mfma_f32_16x16x32_bf16 v[88:91], v[140:143], v[164:167], v[88:91]
	v_mfma_f32_16x16x32_bf16 v[84:87], v[132:135], v[214:217], v[84:87]
	v_mfma_f32_16x16x32_bf16 v[80:83], v[140:143], v[214:217], v[80:83]
	v_mfma_f32_16x16x32_bf16 v[76:79], v[132:135], v[222:225], v[76:79]
	v_mfma_f32_16x16x32_bf16 v[72:75], v[140:143], v[222:225], v[72:75]
	v_mfma_f32_16x16x32_bf16 v[68:71], v[132:135], v[230:233], v[68:71]
	v_mfma_f32_16x16x32_bf16 v[64:67], v[140:143], v[230:233], v[64:67]
	v_mfma_f32_16x16x32_bf16 v[28:31], v[144:147], v[160:163], v[28:31]
	v_mfma_f32_16x16x32_bf16 v[24:27], v[152:155], v[160:163], v[24:27]
	v_mfma_f32_16x16x32_bf16 v[20:23], v[144:147], v[194:197], v[20:23]
	v_mfma_f32_16x16x32_bf16 v[16:19], v[152:155], v[194:197], v[16:19]
	v_mfma_f32_16x16x32_bf16 v[12:15], v[144:147], v[218:221], v[12:15]
	v_mfma_f32_16x16x32_bf16 v[8:11], v[152:155], v[218:221], v[8:11]
	v_mfma_f32_16x16x32_bf16 v[4:7], v[144:147], v[226:229], v[4:7]
	v_mfma_f32_16x16x32_bf16 v[0:3], v[152:155], v[226:229], v[0:3]
	v_mfma_f32_16x16x32_bf16 v[28:31], v[148:151], v[164:167], v[28:31]
	v_mfma_f32_16x16x32_bf16 v[24:27], v[156:159], v[164:167], v[24:27]
	v_mfma_f32_16x16x32_bf16 v[20:23], v[148:151], v[214:217], v[20:23]
	v_mfma_f32_16x16x32_bf16 v[16:19], v[156:159], v[214:217], v[16:19]
	v_mfma_f32_16x16x32_bf16 v[12:15], v[148:151], v[222:225], v[12:15]
	v_mfma_f32_16x16x32_bf16 v[8:11], v[156:159], v[222:225], v[8:11]
	v_mfma_f32_16x16x32_bf16 v[4:7], v[148:151], v[230:233], v[4:7]
	v_mfma_f32_16x16x32_bf16 v[0:3], v[156:159], v[230:233], v[0:3]
	s_setprio 0
	s_barrier
	s_add_i32 s61, 0, 0x18000
	s_add_i32 s62, 0, 0x1c000
	v_add_u32_e32 v140, s61, v200
	v_add_u32_e32 v156, s62, v200
	ds_read_b128 v[128:131], v140
	ds_read_b128 v[132:135], v140 offset:1024
	ds_read_b128 v[136:139], v140 offset:2048
	ds_read_b128 v[140:143], v140 offset:3072
	ds_read_b128 v[144:147], v156
	ds_read_b128 v[148:151], v156 offset:1024
	ds_read_b128 v[152:155], v156 offset:2048
	ds_read_b128 v[156:159], v156 offset:3072
	s_add_u32 s28, s28, 0x40000
	s_addc_u32 s29, s29, 0
	s_mov_b32 m0, s44
	ds_read_b128 v[160:163], v212 offset:32768
	ds_read_b128 v[164:167], v212 offset:33792
	ds_read_b128 v[194:197], v212 offset:34816
	ds_read_b128 v[214:217], v212 offset:35840
	ds_read_b128 v[218:221], v212 offset:36864
	ds_read_b128 v[222:225], v212 offset:37888
	ds_read_b128 v[226:229], v212 offset:38912
	ds_read_b128 v[230:233], v212 offset:39936
	global_load_lds_dwordx4 v168, s[28:29]
	s_mov_b32 m0, s45
	s_nop 0
	global_load_lds_dwordx4 v172, s[28:29]
	s_waitcnt vmcnt(8)
	s_waitcnt lgkmcnt(0)
	s_barrier
	s_setprio 1
	s_waitcnt lgkmcnt(0)
	v_mfma_f32_16x16x32_bf16 v[124:127], v[128:131], v[160:163], v[124:127]
	v_mfma_f32_16x16x32_bf16 v[120:123], v[136:139], v[160:163], v[120:123]
	v_mfma_f32_16x16x32_bf16 v[116:119], v[128:131], v[194:197], v[116:119]
	v_mfma_f32_16x16x32_bf16 v[112:115], v[136:139], v[194:197], v[112:115]
	v_mfma_f32_16x16x32_bf16 v[108:111], v[128:131], v[218:221], v[108:111]
	v_mfma_f32_16x16x32_bf16 v[104:107], v[136:139], v[218:221], v[104:107]
	v_mfma_f32_16x16x32_bf16 v[100:103], v[128:131], v[226:229], v[100:103]
	v_mfma_f32_16x16x32_bf16 v[96:99], v[136:139], v[226:229], v[96:99]
	v_mfma_f32_16x16x32_bf16 v[124:127], v[132:135], v[164:167], v[124:127]
	v_mfma_f32_16x16x32_bf16 v[120:123], v[140:143], v[164:167], v[120:123]
	v_mfma_f32_16x16x32_bf16 v[116:119], v[132:135], v[214:217], v[116:119]
	v_mfma_f32_16x16x32_bf16 v[112:115], v[140:143], v[214:217], v[112:115]
	v_mfma_f32_16x16x32_bf16 v[108:111], v[132:135], v[222:225], v[108:111]
	v_mfma_f32_16x16x32_bf16 v[104:107], v[140:143], v[222:225], v[104:107]
	v_mfma_f32_16x16x32_bf16 v[100:103], v[132:135], v[230:233], v[100:103]
	v_mfma_f32_16x16x32_bf16 v[96:99], v[140:143], v[230:233], v[96:99]
	v_mfma_f32_16x16x32_bf16 v[60:63], v[144:147], v[160:163], v[60:63]
	v_mfma_f32_16x16x32_bf16 v[56:59], v[152:155], v[160:163], v[56:59]
	v_mfma_f32_16x16x32_bf16 v[52:55], v[144:147], v[194:197], v[52:55]
	v_mfma_f32_16x16x32_bf16 v[48:51], v[152:155], v[194:197], v[48:51]
	v_mfma_f32_16x16x32_bf16 v[44:47], v[144:147], v[218:221], v[44:47]
	v_mfma_f32_16x16x32_bf16 v[40:43], v[152:155], v[218:221], v[40:43]
	v_mfma_f32_16x16x32_bf16 v[36:39], v[144:147], v[226:229], v[36:39]
	v_mfma_f32_16x16x32_bf16 v[32:35], v[152:155], v[226:229], v[32:35]
	v_mfma_f32_16x16x32_bf16 v[60:63], v[148:151], v[164:167], v[60:63]
	v_mfma_f32_16x16x32_bf16 v[56:59], v[156:159], v[164:167], v[56:59]
	v_mfma_f32_16x16x32_bf16 v[52:55], v[148:151], v[214:217], v[52:55]
	v_mfma_f32_16x16x32_bf16 v[48:51], v[156:159], v[214:217], v[48:51]
	v_mfma_f32_16x16x32_bf16 v[44:47], v[148:151], v[222:225], v[44:47]
	v_mfma_f32_16x16x32_bf16 v[40:43], v[156:159], v[222:225], v[40:43]
	v_mfma_f32_16x16x32_bf16 v[36:39], v[148:151], v[230:233], v[36:39]
	v_mfma_f32_16x16x32_bf16 v[32:35], v[156:159], v[230:233], v[32:35]
	s_setprio 0
	s_barrier
	s_add_u32 s28, s26, 0x8000
	s_addc_u32 s29, s27, 0
	s_add_i32 s61, s61, s41
	s_mov_b32 m0, s61
	ds_read_b128 v[160:163], v212 offset:49152
	ds_read_b128 v[164:167], v212 offset:50176
	ds_read_b128 v[194:197], v212 offset:51200
	ds_read_b128 v[214:217], v212 offset:52224
	ds_read_b128 v[218:221], v212 offset:53248
	ds_read_b128 v[222:225], v212 offset:54272
	ds_read_b128 v[226:229], v212 offset:55296
	ds_read_b128 v[230:233], v212 offset:56320
	global_load_lds_dwordx4 v170, s[28:29]
	s_add_i32 m0, s61, 0x2000
	s_add_u32 s26, s26, 0xc000
	v_lshl_add_u64 v[206:207], s[28:29], 0, v[174:175]
	s_addc_u32 s27, s27, 0
	s_add_i32 s28, s62, s41
	global_load_lds_dwordx4 v[206:207], off
	s_mov_b32 m0, s28
	v_lshl_add_u64 v[198:199], v[198:199], 0, s[12:13]
	global_load_lds_dwordx4 v170, s[26:27]
	s_add_i32 m0, s28, 0x2000
	s_nop 0
	global_load_lds_dwordx4 v174, s[26:27]
	s_mov_b32 m0, s50
	s_nop 0
	global_load_lds_dwordx4 v[198:199], off
	v_lshl_add_u64 v[198:199], v[204:205], 0, s[12:13]
	s_mov_b32 m0, s51
	s_nop 0
	global_load_lds_dwordx4 v[198:199], off
	s_waitcnt vmcnt(8)
	s_waitcnt lgkmcnt(0)
	s_barrier
	s_setprio 1
	s_waitcnt lgkmcnt(0)
	v_mfma_f32_16x16x32_bf16 v[92:95], v[128:131], v[160:163], v[92:95]
	v_mfma_f32_16x16x32_bf16 v[88:91], v[136:139], v[160:163], v[88:91]
	v_mfma_f32_16x16x32_bf16 v[84:87], v[128:131], v[194:197], v[84:87]
	v_mfma_f32_16x16x32_bf16 v[80:83], v[136:139], v[194:197], v[80:83]
	v_mfma_f32_16x16x32_bf16 v[76:79], v[128:131], v[218:221], v[76:79]
	v_mfma_f32_16x16x32_bf16 v[72:75], v[136:139], v[218:221], v[72:75]
	v_mfma_f32_16x16x32_bf16 v[68:71], v[128:131], v[226:229], v[68:71]
	v_mfma_f32_16x16x32_bf16 v[64:67], v[136:139], v[226:229], v[64:67]
	v_mfma_f32_16x16x32_bf16 v[92:95], v[132:135], v[164:167], v[92:95]
	v_mfma_f32_16x16x32_bf16 v[88:91], v[140:143], v[164:167], v[88:91]
	v_mfma_f32_16x16x32_bf16 v[84:87], v[132:135], v[214:217], v[84:87]
	v_mfma_f32_16x16x32_bf16 v[80:83], v[140:143], v[214:217], v[80:83]
	v_mfma_f32_16x16x32_bf16 v[76:79], v[132:135], v[222:225], v[76:79]
	v_mfma_f32_16x16x32_bf16 v[72:75], v[140:143], v[222:225], v[72:75]
	v_mfma_f32_16x16x32_bf16 v[68:71], v[132:135], v[230:233], v[68:71]
	v_mfma_f32_16x16x32_bf16 v[64:67], v[140:143], v[230:233], v[64:67]
	v_mfma_f32_16x16x32_bf16 v[28:31], v[144:147], v[160:163], v[28:31]
	v_mfma_f32_16x16x32_bf16 v[24:27], v[152:155], v[160:163], v[24:27]
	v_mfma_f32_16x16x32_bf16 v[20:23], v[144:147], v[194:197], v[20:23]
	v_mfma_f32_16x16x32_bf16 v[16:19], v[152:155], v[194:197], v[16:19]
	v_mfma_f32_16x16x32_bf16 v[12:15], v[144:147], v[218:221], v[12:15]
	v_mfma_f32_16x16x32_bf16 v[8:11], v[152:155], v[218:221], v[8:11]
	v_mfma_f32_16x16x32_bf16 v[4:7], v[144:147], v[226:229], v[4:7]
	v_mfma_f32_16x16x32_bf16 v[0:3], v[152:155], v[226:229], v[0:3]
	v_mfma_f32_16x16x32_bf16 v[28:31], v[148:151], v[164:167], v[28:31]
	v_mfma_f32_16x16x32_bf16 v[24:27], v[156:159], v[164:167], v[24:27]
	v_mfma_f32_16x16x32_bf16 v[20:23], v[148:151], v[214:217], v[20:23]
	v_mfma_f32_16x16x32_bf16 v[16:19], v[156:159], v[214:217], v[16:19]
	v_mfma_f32_16x16x32_bf16 v[12:15], v[148:151], v[222:225], v[12:15]
	v_mfma_f32_16x16x32_bf16 v[8:11], v[156:159], v[222:225], v[8:11]
	v_mfma_f32_16x16x32_bf16 v[4:7], v[148:151], v[230:233], v[4:7]
	v_mfma_f32_16x16x32_bf16 v[0:3], v[156:159], v[230:233], v[0:3]
	s_setprio 0
	s_barrier
	s_add_i32 s35, s35, 2
	s_add_u32 s31, s31, 0x10000
	s_addc_u32 s34, s34, 0
	s_add_u32 s6, s6, 0x100
	s_addc_u32 s7, s7, 0
	s_cmp_gt_u32 s35, 13
	s_cbranch_scc0 .LBB0_1729
	s_and_b64 vcc, exec, s[14:15]
	s_cbranch_vccz .LBB0_1740
	s_barrier
	v_lshl_add_u32 v214, s0, 8, v179
	s_cmp_gt_i32 s2, 4
	s_mov_b64 s[0:1], -1
	s_cbranch_scc1 .LBB0_1741

.LBB0_2258:
	ds_read_b128 v[128:131], v170
	ds_read_b128 v[148:151], v170 offset:1024
	ds_read_b128 v[152:155], v170 offset:2048
	ds_read_b128 v[174:177], v170 offset:3072
	ds_read_b128 v[178:181], v171
	ds_read_b128 v[182:185], v171 offset:1024
	ds_read_b128 v[186:189], v171 offset:2048
	ds_read_b128 v[190:193], v171 offset:3072
	s_add_u32 s30, s28, 0xfffe0080
	s_addc_u32 s31, s29, -1
	s_cmp_eq_u32 s56, 4
	s_cselect_b32 s35, s17, s31
	s_cselect_b32 s34, s52, s30
	s_cselect_b32 s31, s19, s55
	s_cselect_b32 s30, s53, s54
	s_add_i32 m0, s25, 0xc000
	ds_read_b128 v[194:197], v172
	ds_read_b128 v[198:201], v172 offset:1024
	ds_read_b128 v[210:213], v172 offset:2048
	ds_read_b128 v[214:217], v172 offset:3072
	ds_read_b128 v[218:221], v172 offset:4096
	ds_read_b128 v[222:225], v172 offset:5120
	ds_read_b128 v[226:229], v172 offset:6144
	ds_read_b128 v[230:233], v172 offset:7168
	global_load_lds_dwordx4 v142, s[28:29]
	s_add_i32 m0, s25, 0xe000
	s_nop 0
	global_load_lds_dwordx4 v140, s[28:29]
	s_waitcnt vmcnt(8)
	s_waitcnt lgkmcnt(0)
	s_barrier
	s_setprio 1
	s_waitcnt lgkmcnt(0)
	v_mfma_f32_16x16x32_bf16 v[124:127], v[128:131], v[194:197], v[124:127]
	v_mfma_f32_16x16x32_bf16 v[120:123], v[152:155], v[194:197], v[120:123]
	v_mfma_f32_16x16x32_bf16 v[116:119], v[128:131], v[210:213], v[116:119]
	v_mfma_f32_16x16x32_bf16 v[112:115], v[152:155], v[210:213], v[112:115]
	v_mfma_f32_16x16x32_bf16 v[92:95], v[128:131], v[218:221], v[92:95]
	v_mfma_f32_16x16x32_bf16 v[88:91], v[152:155], v[218:221], v[88:91]
	v_mfma_f32_16x16x32_bf16 v[84:87], v[128:131], v[226:229], v[84:87]
	v_mfma_f32_16x16x32_bf16 v[72:75], v[152:155], v[226:229], v[72:75]
	v_mfma_f32_16x16x32_bf16 v[124:127], v[148:151], v[198:201], v[124:127]
	v_mfma_f32_16x16x32_bf16 v[120:123], v[174:177], v[198:201], v[120:123]
	v_mfma_f32_16x16x32_bf16 v[116:119], v[148:151], v[214:217], v[116:119]
	v_mfma_f32_16x16x32_bf16 v[112:115], v[174:177], v[214:217], v[112:115]
	v_mfma_f32_16x16x32_bf16 v[92:95], v[148:151], v[222:225], v[92:95]
	v_mfma_f32_16x16x32_bf16 v[88:91], v[174:177], v[222:225], v[88:91]
	v_mfma_f32_16x16x32_bf16 v[84:87], v[148:151], v[230:233], v[84:87]
	v_mfma_f32_16x16x32_bf16 v[72:75], v[174:177], v[230:233], v[72:75]
	v_mfma_f32_16x16x32_bf16 v[108:111], v[178:181], v[194:197], v[108:111]
	v_mfma_f32_16x16x32_bf16 v[104:107], v[186:189], v[194:197], v[104:107]
	v_mfma_f32_16x16x32_bf16 v[100:103], v[178:181], v[210:213], v[100:103]
	v_mfma_f32_16x16x32_bf16 v[96:99], v[186:189], v[210:213], v[96:99]
	v_mfma_f32_16x16x32_bf16 v[80:83], v[178:181], v[218:221], v[80:83]
	v_mfma_f32_16x16x32_bf16 v[76:79], v[186:189], v[218:221], v[76:79]
	v_mfma_f32_16x16x32_bf16 v[68:71], v[178:181], v[226:229], v[68:71]
	v_mfma_f32_16x16x32_bf16 v[64:67], v[186:189], v[226:229], v[64:67]
	v_mfma_f32_16x16x32_bf16 v[108:111], v[182:185], v[198:201], v[108:111]
	v_mfma_f32_16x16x32_bf16 v[104:107], v[190:193], v[198:201], v[104:107]
	v_mfma_f32_16x16x32_bf16 v[100:103], v[182:185], v[214:217], v[100:103]
	v_mfma_f32_16x16x32_bf16 v[96:99], v[190:193], v[214:217], v[96:99]
	v_mfma_f32_16x16x32_bf16 v[80:83], v[182:185], v[222:225], v[80:83]
	v_mfma_f32_16x16x32_bf16 v[76:79], v[190:193], v[222:225], v[76:79]
	v_mfma_f32_16x16x32_bf16 v[68:71], v[182:185], v[230:233], v[68:71]
	v_mfma_f32_16x16x32_bf16 v[64:67], v[190:193], v[230:233], v[64:67]
	s_setprio 0
	s_barrier
	s_add_i32 s57, s49, s42
	s_mov_b32 m0, s57
	ds_read_b128 v[194:197], v172 offset:16384
	ds_read_b128 v[198:201], v172 offset:17408
	ds_read_b128 v[210:213], v172 offset:18432
	ds_read_b128 v[214:217], v172 offset:19456
	ds_read_b128 v[218:221], v172 offset:20480
	ds_read_b128 v[222:225], v172 offset:21504
	ds_read_b128 v[226:229], v172 offset:22528
	ds_read_b128 v[230:233], v172 offset:23552
	global_load_lds_dwordx4 v134, s[30:31]
	s_add_i32 m0, s57, 0x2000
	s_add_u32 s58, s30, 0x4000
	s_addc_u32 s59, s31, 0
	s_add_i32 s57, s50, s42
	global_load_lds_dwordx4 v138, s[30:31]
	s_mov_b32 m0, s57
	v_lshl_add_u64 v[206:207], s[34:35], 0, v[136:137]
	global_load_lds_dwordx4 v134, s[58:59]
	s_add_i32 m0, s57, 0x2000
	s_nop 0
	global_load_lds_dwordx4 v138, s[58:59]
	v_lshl_add_u64 v[204:205], s[34:35], 0, v[132:133]
	s_mov_b32 m0, s25
	s_nop 0
	global_load_lds_dwordx4 v[204:205], off
	s_mov_b32 m0, s27
	s_nop 0
	global_load_lds_dwordx4 v[206:207], off
	s_waitcnt vmcnt(8)
	s_waitcnt lgkmcnt(0)
	s_barrier
	s_setprio 1
	s_waitcnt lgkmcnt(0)
	v_mfma_f32_16x16x32_bf16 v[60:63], v[128:131], v[194:197], v[60:63]
	v_mfma_f32_16x16x32_bf16 v[56:59], v[152:155], v[194:197], v[56:59]
	v_mfma_f32_16x16x32_bf16 v[48:51], v[128:131], v[210:213], v[48:51]
	v_mfma_f32_16x16x32_bf16 v[40:43], v[152:155], v[210:213], v[40:43]
	v_mfma_f32_16x16x32_bf16 v[32:35], v[128:131], v[218:221], v[32:35]
	v_mfma_f32_16x16x32_bf16 v[24:27], v[152:155], v[218:221], v[24:27]
	v_mfma_f32_16x16x32_bf16 v[16:19], v[128:131], v[226:229], v[16:19]
	v_mfma_f32_16x16x32_bf16 v[8:11], v[152:155], v[226:229], v[8:11]
	v_mfma_f32_16x16x32_bf16 v[60:63], v[148:151], v[198:201], v[60:63]
	v_mfma_f32_16x16x32_bf16 v[56:59], v[174:177], v[198:201], v[56:59]
	v_mfma_f32_16x16x32_bf16 v[48:51], v[148:151], v[214:217], v[48:51]
	v_mfma_f32_16x16x32_bf16 v[40:43], v[174:177], v[214:217], v[40:43]
	v_mfma_f32_16x16x32_bf16 v[32:35], v[148:151], v[222:225], v[32:35]
	v_mfma_f32_16x16x32_bf16 v[24:27], v[174:177], v[222:225], v[24:27]
	v_mfma_f32_16x16x32_bf16 v[16:19], v[148:151], v[230:233], v[16:19]
	v_mfma_f32_16x16x32_bf16 v[8:11], v[174:177], v[230:233], v[8:11]
	v_mfma_f32_16x16x32_bf16 v[52:55], v[178:181], v[194:197], v[52:55]
	v_mfma_f32_16x16x32_bf16 v[44:47], v[186:189], v[194:197], v[44:47]
	v_mfma_f32_16x16x32_bf16 v[36:39], v[178:181], v[210:213], v[36:39]
	v_mfma_f32_16x16x32_bf16 v[28:31], v[186:189], v[210:213], v[28:31]
	v_mfma_f32_16x16x32_bf16 v[20:23], v[178:181], v[218:221], v[20:23]
	v_mfma_f32_16x16x32_bf16 v[12:15], v[186:189], v[218:221], v[12:15]
	v_mfma_f32_16x16x32_bf16 v[4:7], v[178:181], v[226:229], v[4:7]
	v_mfma_f32_16x16x32_bf16 v[0:3], v[186:189], v[226:229], v[0:3]
	v_mfma_f32_16x16x32_bf16 v[52:55], v[182:185], v[198:201], v[52:55]
	v_mfma_f32_16x16x32_bf16 v[44:47], v[190:193], v[198:201], v[44:47]
	v_mfma_f32_16x16x32_bf16 v[36:39], v[182:185], v[214:217], v[36:39]
	v_mfma_f32_16x16x32_bf16 v[28:31], v[190:193], v[214:217], v[28:31]
	v_mfma_f32_16x16x32_bf16 v[20:23], v[182:185], v[222:225], v[20:23]
	v_mfma_f32_16x16x32_bf16 v[12:15], v[190:193], v[222:225], v[12:15]
	v_mfma_f32_16x16x32_bf16 v[4:7], v[182:185], v[230:233], v[4:7]
	v_mfma_f32_16x16x32_bf16 v[0:3], v[190:193], v[230:233], v[0:3]
	s_setprio 0
	s_barrier
	s_add_i32 s57, 0, 0x18000
	v_add_u32_e32 v173, s57, v168
	s_add_i32 s58, 0, 0x1c000
	ds_read_b128 v[128:131], v173
	ds_read_b128 v[148:151], v173 offset:1024
	ds_read_b128 v[152:155], v173 offset:2048
	ds_read_b128 v[174:177], v173 offset:3072
	v_add_u32_e32 v173, s58, v168
	ds_read_b128 v[178:181], v173
	ds_read_b128 v[182:185], v173 offset:1024
	ds_read_b128 v[186:189], v173 offset:2048
	ds_read_b128 v[190:193], v173 offset:3072
	s_add_u32 s34, s34, 0x20000
	s_addc_u32 s35, s35, 0
	s_mov_b32 m0, s43
	ds_read_b128 v[194:197], v172 offset:32768
	ds_read_b128 v[198:201], v172 offset:33792
	ds_read_b128 v[210:213], v172 offset:34816
	ds_read_b128 v[214:217], v172 offset:35840
	ds_read_b128 v[218:221], v172 offset:36864
	ds_read_b128 v[222:225], v172 offset:37888
	ds_read_b128 v[226:229], v172 offset:38912
	ds_read_b128 v[230:233], v172 offset:39936
	global_load_lds_dwordx4 v132, s[34:35]
	s_mov_b32 m0, s44
	s_nop 0
	global_load_lds_dwordx4 v136, s[34:35]
	s_waitcnt vmcnt(8)
	s_waitcnt lgkmcnt(0)
	s_barrier
	s_setprio 1
	s_waitcnt lgkmcnt(0)
	v_mfma_f32_16x16x32_bf16 v[124:127], v[128:131], v[194:197], v[124:127]
	v_mfma_f32_16x16x32_bf16 v[120:123], v[152:155], v[194:197], v[120:123]
	v_mfma_f32_16x16x32_bf16 v[116:119], v[128:131], v[210:213], v[116:119]
	v_mfma_f32_16x16x32_bf16 v[112:115], v[152:155], v[210:213], v[112:115]
	v_mfma_f32_16x16x32_bf16 v[92:95], v[128:131], v[218:221], v[92:95]
	v_mfma_f32_16x16x32_bf16 v[88:91], v[152:155], v[218:221], v[88:91]
	v_mfma_f32_16x16x32_bf16 v[84:87], v[128:131], v[226:229], v[84:87]
	v_mfma_f32_16x16x32_bf16 v[72:75], v[152:155], v[226:229], v[72:75]
	v_mfma_f32_16x16x32_bf16 v[124:127], v[148:151], v[198:201], v[124:127]
	v_mfma_f32_16x16x32_bf16 v[120:123], v[174:177], v[198:201], v[120:123]
	v_mfma_f32_16x16x32_bf16 v[116:119], v[148:151], v[214:217], v[116:119]
	v_mfma_f32_16x16x32_bf16 v[112:115], v[174:177], v[214:217], v[112:115]
	v_mfma_f32_16x16x32_bf16 v[92:95], v[148:151], v[222:225], v[92:95]
	v_mfma_f32_16x16x32_bf16 v[88:91], v[174:177], v[222:225], v[88:91]
	v_mfma_f32_16x16x32_bf16 v[84:87], v[148:151], v[230:233], v[84:87]
	v_mfma_f32_16x16x32_bf16 v[72:75], v[174:177], v[230:233], v[72:75]
	v_mfma_f32_16x16x32_bf16 v[108:111], v[178:181], v[194:197], v[108:111]
	v_mfma_f32_16x16x32_bf16 v[104:107], v[186:189], v[194:197], v[104:107]
	v_mfma_f32_16x16x32_bf16 v[100:103], v[178:181], v[210:213], v[100:103]
	v_mfma_f32_16x16x32_bf16 v[96:99], v[186:189], v[210:213], v[96:99]
	v_mfma_f32_16x16x32_bf16 v[80:83], v[178:181], v[218:221], v[80:83]
	v_mfma_f32_16x16x32_bf16 v[76:79], v[186:189], v[218:221], v[76:79]
	v_mfma_f32_16x16x32_bf16 v[68:71], v[178:181], v[226:229], v[68:71]
	v_mfma_f32_16x16x32_bf16 v[64:67], v[186:189], v[226:229], v[64:67]
	v_mfma_f32_16x16x32_bf16 v[108:111], v[182:185], v[198:201], v[108:111]
	v_mfma_f32_16x16x32_bf16 v[104:107], v[190:193], v[198:201], v[104:107]
	v_mfma_f32_16x16x32_bf16 v[100:103], v[182:185], v[214:217], v[100:103]
	v_mfma_f32_16x16x32_bf16 v[96:99], v[190:193], v[214:217], v[96:99]
	v_mfma_f32_16x16x32_bf16 v[80:83], v[182:185], v[222:225], v[80:83]
	v_mfma_f32_16x16x32_bf16 v[76:79], v[190:193], v[222:225], v[76:79]
	v_mfma_f32_16x16x32_bf16 v[68:71], v[182:185], v[230:233], v[68:71]
	v_mfma_f32_16x16x32_bf16 v[64:67], v[190:193], v[230:233], v[64:67]
	s_setprio 0
	s_barrier
	s_add_u32 s34, s30, 0x8000
	s_addc_u32 s35, s31, 0
	s_add_i32 s57, s57, s42
	s_mov_b32 m0, s57
	ds_read_b128 v[194:197], v172 offset:49152
	ds_read_b128 v[198:201], v172 offset:50176
	ds_read_b128 v[210:213], v172 offset:51200
	ds_read_b128 v[214:217], v172 offset:52224
	ds_read_b128 v[218:221], v172 offset:53248
	ds_read_b128 v[222:225], v172 offset:54272
	ds_read_b128 v[226:229], v172 offset:55296
	ds_read_b128 v[230:233], v172 offset:56320
	global_load_lds_dwordx4 v134, s[34:35]
	s_add_i32 m0, s57, 0x2000
	s_add_u32 s30, s30, 0xc000
	v_lshl_add_u64 v[234:235], s[34:35], 0, v[138:139]
	s_addc_u32 s31, s31, 0
	s_add_i32 s34, s58, s42
	global_load_lds_dwordx4 v[234:235], off
	s_mov_b32 m0, s34
	v_lshl_add_u64 v[204:205], v[204:205], 0, s[12:13]
	global_load_lds_dwordx4 v134, s[30:31]
	s_add_i32 m0, s34, 0x2000
	s_nop 0
	global_load_lds_dwordx4 v138, s[30:31]
	s_mov_b32 m0, s46
	s_nop 0
	global_load_lds_dwordx4 v[204:205], off
	v_lshl_add_u64 v[204:205], v[206:207], 0, s[12:13]
	s_mov_b32 m0, s47
	s_nop 0
	global_load_lds_dwordx4 v[204:205], off
	s_waitcnt vmcnt(8)
	s_waitcnt lgkmcnt(0)
	s_barrier
	s_setprio 1
	s_waitcnt lgkmcnt(0)
	v_mfma_f32_16x16x32_bf16 v[60:63], v[128:131], v[194:197], v[60:63]
	v_mfma_f32_16x16x32_bf16 v[56:59], v[152:155], v[194:197], v[56:59]
	v_mfma_f32_16x16x32_bf16 v[48:51], v[128:131], v[210:213], v[48:51]
	v_mfma_f32_16x16x32_bf16 v[40:43], v[152:155], v[210:213], v[40:43]
	v_mfma_f32_16x16x32_bf16 v[32:35], v[128:131], v[218:221], v[32:35]
	v_mfma_f32_16x16x32_bf16 v[24:27], v[152:155], v[218:221], v[24:27]
	v_mfma_f32_16x16x32_bf16 v[16:19], v[128:131], v[226:229], v[16:19]
	v_mfma_f32_16x16x32_bf16 v[8:11], v[152:155], v[226:229], v[8:11]
	v_mfma_f32_16x16x32_bf16 v[60:63], v[148:151], v[198:201], v[60:63]
	v_mfma_f32_16x16x32_bf16 v[56:59], v[174:177], v[198:201], v[56:59]
	v_mfma_f32_16x16x32_bf16 v[48:51], v[148:151], v[214:217], v[48:51]
	v_mfma_f32_16x16x32_bf16 v[40:43], v[174:177], v[214:217], v[40:43]
	v_mfma_f32_16x16x32_bf16 v[32:35], v[148:151], v[222:225], v[32:35]
	v_mfma_f32_16x16x32_bf16 v[24:27], v[174:177], v[222:225], v[24:27]
	v_mfma_f32_16x16x32_bf16 v[16:19], v[148:151], v[230:233], v[16:19]
	v_mfma_f32_16x16x32_bf16 v[8:11], v[174:177], v[230:233], v[8:11]
	v_mfma_f32_16x16x32_bf16 v[52:55], v[178:181], v[194:197], v[52:55]
	v_mfma_f32_16x16x32_bf16 v[44:47], v[186:189], v[194:197], v[44:47]
	v_mfma_f32_16x16x32_bf16 v[36:39], v[178:181], v[210:213], v[36:39]
	v_mfma_f32_16x16x32_bf16 v[28:31], v[186:189], v[210:213], v[28:31]
	v_mfma_f32_16x16x32_bf16 v[20:23], v[178:181], v[218:221], v[20:23]
	v_mfma_f32_16x16x32_bf16 v[12:15], v[186:189], v[218:221], v[12:15]
	v_mfma_f32_16x16x32_bf16 v[4:7], v[178:181], v[226:229], v[4:7]
	v_mfma_f32_16x16x32_bf16 v[0:3], v[186:189], v[226:229], v[0:3]
	v_mfma_f32_16x16x32_bf16 v[52:55], v[182:185], v[198:201], v[52:55]
	v_mfma_f32_16x16x32_bf16 v[44:47], v[190:193], v[198:201], v[44:47]
	v_mfma_f32_16x16x32_bf16 v[36:39], v[182:185], v[214:217], v[36:39]
	v_mfma_f32_16x16x32_bf16 v[28:31], v[190:193], v[214:217], v[28:31]
	v_mfma_f32_16x16x32_bf16 v[20:23], v[182:185], v[222:225], v[20:23]
	v_mfma_f32_16x16x32_bf16 v[12:15], v[190:193], v[222:225], v[12:15]
	v_mfma_f32_16x16x32_bf16 v[4:7], v[182:185], v[230:233], v[4:7]
	v_mfma_f32_16x16x32_bf16 v[0:3], v[190:193], v[230:233], v[0:3]
	s_setprio 0
	s_barrier
	s_add_i32 s56, s56, 2
	s_add_u32 s54, s54, 0x10000
	s_addc_u32 s55, s55, 0
	s_add_u32 s28, s28, 0x100
	s_addc_u32 s29, s29, 0
	s_cmp_gt_u32 s56, 5
	s_cbranch_scc0 .LBB0_2258
	s_and_b64 vcc, exec, s[14:15]
	s_cbranch_vccz .LBB0_2261
	s_barrier

.LBB0_2282:
	ds_read_b128 v[144:147], v155
	ds_read_b128 v[148:151], v155 offset:1024
	ds_read_b128 v[158:161], v155 offset:2048
	ds_read_b128 v[162:165], v155 offset:3072
	ds_read_b128 v[166:169], v156
	ds_read_b128 v[170:173], v156 offset:1024
	ds_read_b128 v[174:177], v156 offset:2048
	ds_read_b128 v[178:181], v156 offset:3072
	s_add_u32 s28, s26, 0xfffe0080
	s_addc_u32 s29, s27, -1
	s_cmp_eq_u32 s54, 4
	s_cselect_b32 s31, s15, s29
	s_cselect_b32 s30, s50, s28
	s_cselect_b32 s29, s17, s53
	s_cselect_b32 s28, s51, s52
	s_add_i32 m0, s23, 0xc000
	ds_read_b128 v[182:185], v157
	ds_read_b128 v[186:189], v157 offset:1024
	ds_read_b128 v[190:193], v157 offset:2048
	ds_read_b128 v[194:197], v157 offset:3072
	ds_read_b128 v[198:201], v157 offset:4096
	ds_read_b128 v[210:213], v157 offset:5120
	ds_read_b128 v[214:217], v157 offset:6144
	ds_read_b128 v[218:221], v157 offset:7168
	global_load_lds_dwordx4 v130, s[26:27]
	s_add_i32 m0, s23, 0xe000
	s_nop 0
	global_load_lds_dwordx4 v128, s[26:27]
	s_waitcnt vmcnt(8)
	s_waitcnt lgkmcnt(0)
	s_barrier
	s_setprio 1
	s_waitcnt lgkmcnt(0)
	v_mfma_f32_16x16x32_bf16 v[124:127], v[144:147], v[182:185], v[124:127]
	v_mfma_f32_16x16x32_bf16 v[120:123], v[158:161], v[182:185], v[120:123]
	v_mfma_f32_16x16x32_bf16 v[112:115], v[144:147], v[190:193], v[112:115]
	v_mfma_f32_16x16x32_bf16 v[104:107], v[158:161], v[190:193], v[104:107]
	v_mfma_f32_16x16x32_bf16 v[92:95], v[144:147], v[198:201], v[92:95]
	v_mfma_f32_16x16x32_bf16 v[88:91], v[158:161], v[198:201], v[88:91]
	v_mfma_f32_16x16x32_bf16 v[80:83], v[144:147], v[214:217], v[80:83]
	v_mfma_f32_16x16x32_bf16 v[72:75], v[158:161], v[214:217], v[72:75]
	v_mfma_f32_16x16x32_bf16 v[124:127], v[148:151], v[186:189], v[124:127]
	v_mfma_f32_16x16x32_bf16 v[120:123], v[162:165], v[186:189], v[120:123]
	v_mfma_f32_16x16x32_bf16 v[112:115], v[148:151], v[194:197], v[112:115]
	v_mfma_f32_16x16x32_bf16 v[104:107], v[162:165], v[194:197], v[104:107]
	v_mfma_f32_16x16x32_bf16 v[92:95], v[148:151], v[210:213], v[92:95]
	v_mfma_f32_16x16x32_bf16 v[88:91], v[162:165], v[210:213], v[88:91]
	v_mfma_f32_16x16x32_bf16 v[80:83], v[148:151], v[218:221], v[80:83]
	v_mfma_f32_16x16x32_bf16 v[72:75], v[162:165], v[218:221], v[72:75]
	v_mfma_f32_16x16x32_bf16 v[116:119], v[166:169], v[182:185], v[116:119]
	v_mfma_f32_16x16x32_bf16 v[108:111], v[174:177], v[182:185], v[108:111]
	v_mfma_f32_16x16x32_bf16 v[100:103], v[166:169], v[190:193], v[100:103]
	v_mfma_f32_16x16x32_bf16 v[96:99], v[174:177], v[190:193], v[96:99]
	v_mfma_f32_16x16x32_bf16 v[84:87], v[166:169], v[198:201], v[84:87]
	v_mfma_f32_16x16x32_bf16 v[76:79], v[174:177], v[198:201], v[76:79]
	v_mfma_f32_16x16x32_bf16 v[68:71], v[166:169], v[214:217], v[68:71]
	v_mfma_f32_16x16x32_bf16 v[64:67], v[174:177], v[214:217], v[64:67]
	v_mfma_f32_16x16x32_bf16 v[116:119], v[170:173], v[186:189], v[116:119]
	v_mfma_f32_16x16x32_bf16 v[108:111], v[178:181], v[186:189], v[108:111]
	v_mfma_f32_16x16x32_bf16 v[100:103], v[170:173], v[194:197], v[100:103]
	v_mfma_f32_16x16x32_bf16 v[96:99], v[178:181], v[194:197], v[96:99]
	v_mfma_f32_16x16x32_bf16 v[84:87], v[170:173], v[210:213], v[84:87]
	v_mfma_f32_16x16x32_bf16 v[76:79], v[178:181], v[210:213], v[76:79]
	v_mfma_f32_16x16x32_bf16 v[68:71], v[170:173], v[218:221], v[68:71]
	v_mfma_f32_16x16x32_bf16 v[64:67], v[178:181], v[218:221], v[64:67]
	s_setprio 0
	s_barrier
	s_add_i32 s55, s47, s40
	s_mov_b32 m0, s55
	ds_read_b128 v[182:185], v157 offset:16384
	ds_read_b128 v[186:189], v157 offset:17408
	ds_read_b128 v[190:193], v157 offset:18432
	ds_read_b128 v[194:197], v157 offset:19456
	ds_read_b128 v[198:201], v157 offset:20480
	ds_read_b128 v[210:213], v157 offset:21504
	ds_read_b128 v[214:217], v157 offset:22528
	ds_read_b128 v[218:221], v157 offset:23552
	global_load_lds_dwordx4 v134, s[28:29]
	s_add_i32 m0, s55, 0x2000
	s_add_u32 s56, s28, 0x4000
	s_addc_u32 s57, s29, 0
	s_add_i32 s55, s48, s40
	global_load_lds_dwordx4 v138, s[28:29]
	s_mov_b32 m0, s55
	v_lshl_add_u64 v[206:207], s[30:31], 0, v[136:137]
	global_load_lds_dwordx4 v134, s[56:57]
	s_add_i32 m0, s55, 0x2000
	s_nop 0
	global_load_lds_dwordx4 v138, s[56:57]
	v_lshl_add_u64 v[204:205], s[30:31], 0, v[132:133]
	s_mov_b32 m0, s23
	s_nop 0
	global_load_lds_dwordx4 v[204:205], off
	s_mov_b32 m0, s25
	s_nop 0
	global_load_lds_dwordx4 v[206:207], off
	s_waitcnt vmcnt(8)
	s_waitcnt lgkmcnt(0)
	s_barrier
	s_setprio 1
	s_waitcnt lgkmcnt(0)
	v_mfma_f32_16x16x32_bf16 v[60:63], v[144:147], v[182:185], v[60:63]
	v_mfma_f32_16x16x32_bf16 v[56:59], v[158:161], v[182:185], v[56:59]
	v_mfma_f32_16x16x32_bf16 v[48:51], v[144:147], v[190:193], v[48:51]
	v_mfma_f32_16x16x32_bf16 v[40:43], v[158:161], v[190:193], v[40:43]
	v_mfma_f32_16x16x32_bf16 v[28:31], v[144:147], v[198:201], v[28:31]
	v_mfma_f32_16x16x32_bf16 v[24:27], v[158:161], v[198:201], v[24:27]
	v_mfma_f32_16x16x32_bf16 v[16:19], v[144:147], v[214:217], v[16:19]
	v_mfma_f32_16x16x32_bf16 v[8:11], v[158:161], v[214:217], v[8:11]
	v_mfma_f32_16x16x32_bf16 v[60:63], v[148:151], v[186:189], v[60:63]
	v_mfma_f32_16x16x32_bf16 v[56:59], v[162:165], v[186:189], v[56:59]
	v_mfma_f32_16x16x32_bf16 v[48:51], v[148:151], v[194:197], v[48:51]
	v_mfma_f32_16x16x32_bf16 v[40:43], v[162:165], v[194:197], v[40:43]
	v_mfma_f32_16x16x32_bf16 v[28:31], v[148:151], v[210:213], v[28:31]
	v_mfma_f32_16x16x32_bf16 v[24:27], v[162:165], v[210:213], v[24:27]
	v_mfma_f32_16x16x32_bf16 v[16:19], v[148:151], v[218:221], v[16:19]
	v_mfma_f32_16x16x32_bf16 v[8:11], v[162:165], v[218:221], v[8:11]
	v_mfma_f32_16x16x32_bf16 v[52:55], v[166:169], v[182:185], v[52:55]
	v_mfma_f32_16x16x32_bf16 v[44:47], v[174:177], v[182:185], v[44:47]
	v_mfma_f32_16x16x32_bf16 v[36:39], v[166:169], v[190:193], v[36:39]
	v_mfma_f32_16x16x32_bf16 v[32:35], v[174:177], v[190:193], v[32:35]
	v_mfma_f32_16x16x32_bf16 v[20:23], v[166:169], v[198:201], v[20:23]
	v_mfma_f32_16x16x32_bf16 v[12:15], v[174:177], v[198:201], v[12:15]
	v_mfma_f32_16x16x32_bf16 v[4:7], v[166:169], v[214:217], v[4:7]
	v_mfma_f32_16x16x32_bf16 v[0:3], v[174:177], v[214:217], v[0:3]
	v_mfma_f32_16x16x32_bf16 v[52:55], v[170:173], v[186:189], v[52:55]
	v_mfma_f32_16x16x32_bf16 v[44:47], v[178:181], v[186:189], v[44:47]
	v_mfma_f32_16x16x32_bf16 v[36:39], v[170:173], v[194:197], v[36:39]
	v_mfma_f32_16x16x32_bf16 v[32:35], v[178:181], v[194:197], v[32:35]
	v_mfma_f32_16x16x32_bf16 v[20:23], v[170:173], v[210:213], v[20:23]
	v_mfma_f32_16x16x32_bf16 v[12:15], v[178:181], v[210:213], v[12:15]
	v_mfma_f32_16x16x32_bf16 v[4:7], v[170:173], v[218:221], v[4:7]
	v_mfma_f32_16x16x32_bf16 v[0:3], v[178:181], v[218:221], v[0:3]
	s_setprio 0
	s_barrier
	s_add_i32 s55, 0, 0x18000
	s_add_i32 s56, 0, 0x1c000
	v_add_u32_e32 v162, s55, v153
	v_add_u32_e32 v178, s56, v153
	ds_read_b128 v[144:147], v162
	ds_read_b128 v[148:151], v162 offset:1024
	ds_read_b128 v[158:161], v162 offset:2048
	ds_read_b128 v[162:165], v162 offset:3072
	ds_read_b128 v[166:169], v178
	ds_read_b128 v[170:173], v178 offset:1024
	ds_read_b128 v[174:177], v178 offset:2048
	ds_read_b128 v[178:181], v178 offset:3072
	s_add_u32 s30, s30, 0x20000
	s_addc_u32 s31, s31, 0
	s_mov_b32 m0, s41
	ds_read_b128 v[182:185], v157 offset:32768
	ds_read_b128 v[186:189], v157 offset:33792
	ds_read_b128 v[190:193], v157 offset:34816
	ds_read_b128 v[194:197], v157 offset:35840
	ds_read_b128 v[198:201], v157 offset:36864
	ds_read_b128 v[210:213], v157 offset:37888
	ds_read_b128 v[214:217], v157 offset:38912
	ds_read_b128 v[218:221], v157 offset:39936
	global_load_lds_dwordx4 v132, s[30:31]
	s_mov_b32 m0, s42
	s_nop 0
	global_load_lds_dwordx4 v136, s[30:31]
	s_waitcnt vmcnt(8)
	s_waitcnt lgkmcnt(0)
	s_barrier
	s_setprio 1
	s_waitcnt lgkmcnt(0)
	v_mfma_f32_16x16x32_bf16 v[124:127], v[144:147], v[182:185], v[124:127]
	v_mfma_f32_16x16x32_bf16 v[120:123], v[158:161], v[182:185], v[120:123]
	v_mfma_f32_16x16x32_bf16 v[112:115], v[144:147], v[190:193], v[112:115]
	v_mfma_f32_16x16x32_bf16 v[104:107], v[158:161], v[190:193], v[104:107]
	v_mfma_f32_16x16x32_bf16 v[92:95], v[144:147], v[198:201], v[92:95]
	v_mfma_f32_16x16x32_bf16 v[88:91], v[158:161], v[198:201], v[88:91]
	v_mfma_f32_16x16x32_bf16 v[80:83], v[144:147], v[214:217], v[80:83]
	v_mfma_f32_16x16x32_bf16 v[72:75], v[158:161], v[214:217], v[72:75]
	v_mfma_f32_16x16x32_bf16 v[124:127], v[148:151], v[186:189], v[124:127]
	v_mfma_f32_16x16x32_bf16 v[120:123], v[162:165], v[186:189], v[120:123]
	v_mfma_f32_16x16x32_bf16 v[112:115], v[148:151], v[194:197], v[112:115]
	v_mfma_f32_16x16x32_bf16 v[104:107], v[162:165], v[194:197], v[104:107]
	v_mfma_f32_16x16x32_bf16 v[92:95], v[148:151], v[210:213], v[92:95]
	v_mfma_f32_16x16x32_bf16 v[88:91], v[162:165], v[210:213], v[88:91]
	v_mfma_f32_16x16x32_bf16 v[80:83], v[148:151], v[218:221], v[80:83]
	v_mfma_f32_16x16x32_bf16 v[72:75], v[162:165], v[218:221], v[72:75]
	v_mfma_f32_16x16x32_bf16 v[116:119], v[166:169], v[182:185], v[116:119]
	v_mfma_f32_16x16x32_bf16 v[108:111], v[174:177], v[182:185], v[108:111]
	v_mfma_f32_16x16x32_bf16 v[100:103], v[166:169], v[190:193], v[100:103]
	v_mfma_f32_16x16x32_bf16 v[96:99], v[174:177], v[190:193], v[96:99]
	v_mfma_f32_16x16x32_bf16 v[84:87], v[166:169], v[198:201], v[84:87]
	v_mfma_f32_16x16x32_bf16 v[76:79], v[174:177], v[198:201], v[76:79]
	v_mfma_f32_16x16x32_bf16 v[68:71], v[166:169], v[214:217], v[68:71]
	v_mfma_f32_16x16x32_bf16 v[64:67], v[174:177], v[214:217], v[64:67]
	v_mfma_f32_16x16x32_bf16 v[116:119], v[170:173], v[186:189], v[116:119]
	v_mfma_f32_16x16x32_bf16 v[108:111], v[178:181], v[186:189], v[108:111]
	v_mfma_f32_16x16x32_bf16 v[100:103], v[170:173], v[194:197], v[100:103]
	v_mfma_f32_16x16x32_bf16 v[96:99], v[178:181], v[194:197], v[96:99]
	v_mfma_f32_16x16x32_bf16 v[84:87], v[170:173], v[210:213], v[84:87]
	v_mfma_f32_16x16x32_bf16 v[76:79], v[178:181], v[210:213], v[76:79]
	v_mfma_f32_16x16x32_bf16 v[68:71], v[170:173], v[218:221], v[68:71]
	v_mfma_f32_16x16x32_bf16 v[64:67], v[178:181], v[218:221], v[64:67]
	s_setprio 0
	s_barrier
	s_add_u32 s30, s28, 0x8000
	s_addc_u32 s31, s29, 0
	s_add_i32 s55, s55, s40
	s_mov_b32 m0, s55
	ds_read_b128 v[182:185], v157 offset:49152
	ds_read_b128 v[186:189], v157 offset:50176
	ds_read_b128 v[190:193], v157 offset:51200
	ds_read_b128 v[194:197], v157 offset:52224
	ds_read_b128 v[198:201], v157 offset:53248
	ds_read_b128 v[210:213], v157 offset:54272
	ds_read_b128 v[214:217], v157 offset:55296
	ds_read_b128 v[218:221], v157 offset:56320
	global_load_lds_dwordx4 v134, s[30:31]
	s_add_i32 m0, s55, 0x2000
	s_add_u32 s28, s28, 0xc000
	v_lshl_add_u64 v[222:223], s[30:31], 0, v[138:139]
	s_addc_u32 s29, s29, 0
	s_add_i32 s30, s56, s40
	global_load_lds_dwordx4 v[222:223], off
	s_mov_b32 m0, s30
	v_lshl_add_u64 v[204:205], v[204:205], 0, s[8:9]
	global_load_lds_dwordx4 v134, s[28:29]
	s_add_i32 m0, s30, 0x2000
	s_nop 0
	global_load_lds_dwordx4 v138, s[28:29]
	s_mov_b32 m0, s44
	s_nop 0
	global_load_lds_dwordx4 v[204:205], off
	v_lshl_add_u64 v[204:205], v[206:207], 0, s[8:9]
	s_mov_b32 m0, s45
	s_nop 0
	global_load_lds_dwordx4 v[204:205], off
	s_waitcnt vmcnt(8)
	s_waitcnt lgkmcnt(0)
	s_barrier
	s_setprio 1
	s_waitcnt lgkmcnt(0)
	v_mfma_f32_16x16x32_bf16 v[60:63], v[144:147], v[182:185], v[60:63]
	v_mfma_f32_16x16x32_bf16 v[56:59], v[158:161], v[182:185], v[56:59]
	v_mfma_f32_16x16x32_bf16 v[48:51], v[144:147], v[190:193], v[48:51]
	v_mfma_f32_16x16x32_bf16 v[40:43], v[158:161], v[190:193], v[40:43]
	v_mfma_f32_16x16x32_bf16 v[28:31], v[144:147], v[198:201], v[28:31]
	v_mfma_f32_16x16x32_bf16 v[24:27], v[158:161], v[198:201], v[24:27]
	v_mfma_f32_16x16x32_bf16 v[16:19], v[144:147], v[214:217], v[16:19]
	v_mfma_f32_16x16x32_bf16 v[8:11], v[158:161], v[214:217], v[8:11]
	v_mfma_f32_16x16x32_bf16 v[60:63], v[148:151], v[186:189], v[60:63]
	v_mfma_f32_16x16x32_bf16 v[56:59], v[162:165], v[186:189], v[56:59]
	v_mfma_f32_16x16x32_bf16 v[48:51], v[148:151], v[194:197], v[48:51]
	v_mfma_f32_16x16x32_bf16 v[40:43], v[162:165], v[194:197], v[40:43]
	v_mfma_f32_16x16x32_bf16 v[28:31], v[148:151], v[210:213], v[28:31]
	v_mfma_f32_16x16x32_bf16 v[24:27], v[162:165], v[210:213], v[24:27]
	v_mfma_f32_16x16x32_bf16 v[16:19], v[148:151], v[218:221], v[16:19]
	v_mfma_f32_16x16x32_bf16 v[8:11], v[162:165], v[218:221], v[8:11]
	v_mfma_f32_16x16x32_bf16 v[52:55], v[166:169], v[182:185], v[52:55]
	v_mfma_f32_16x16x32_bf16 v[44:47], v[174:177], v[182:185], v[44:47]
	v_mfma_f32_16x16x32_bf16 v[36:39], v[166:169], v[190:193], v[36:39]
	v_mfma_f32_16x16x32_bf16 v[32:35], v[174:177], v[190:193], v[32:35]
	v_mfma_f32_16x16x32_bf16 v[20:23], v[166:169], v[198:201], v[20:23]
	v_mfma_f32_16x16x32_bf16 v[12:15], v[174:177], v[198:201], v[12:15]
	v_mfma_f32_16x16x32_bf16 v[4:7], v[166:169], v[214:217], v[4:7]
	v_mfma_f32_16x16x32_bf16 v[0:3], v[174:177], v[214:217], v[0:3]
	v_mfma_f32_16x16x32_bf16 v[52:55], v[170:173], v[186:189], v[52:55]
	v_mfma_f32_16x16x32_bf16 v[44:47], v[178:181], v[186:189], v[44:47]
	v_mfma_f32_16x16x32_bf16 v[36:39], v[170:173], v[194:197], v[36:39]
	v_mfma_f32_16x16x32_bf16 v[32:35], v[178:181], v[194:197], v[32:35]
	v_mfma_f32_16x16x32_bf16 v[20:23], v[170:173], v[210:213], v[20:23]
	v_mfma_f32_16x16x32_bf16 v[12:15], v[178:181], v[210:213], v[12:15]
	v_mfma_f32_16x16x32_bf16 v[4:7], v[170:173], v[218:221], v[4:7]
	v_mfma_f32_16x16x32_bf16 v[0:3], v[178:181], v[218:221], v[0:3]
	s_setprio 0
	s_barrier
	s_add_i32 s54, s54, 2
	s_add_u32 s52, s52, 0x10000
	s_addc_u32 s53, s53, 0
	s_add_u32 s26, s26, 0x100
	s_addc_u32 s27, s27, 0
	s_cmp_gt_u32 s54, 5
	s_cbranch_scc0 .LBB0_2282
	s_and_b64 vcc, exec, s[10:11]
	s_cbranch_vccz .LBB0_2285
	s_barrier

.LBB0_2358:
	v_add_u32_e32 v168, s77, v182
	v_add_u32_e32 v204, s78, v182
	ds_read_b128 v[156:159], v168
	ds_read_b128 v[160:163], v168 offset:1024
	ds_read_b128 v[164:167], v168 offset:2048
	ds_read_b128 v[168:171], v168 offset:3072
	ds_read_b128 v[172:175], v204
	ds_read_b128 v[176:179], v204 offset:1024
	ds_read_b128 v[212:215], v204 offset:2048
	ds_read_b128 v[216:219], v204 offset:3072
	s_add_u32 s48, s46, 0xfffc0080
	s_addc_u32 s49, s47, -1
	s_cmp_eq_u32 s54, 12
	s_cselect_b32 s51, s35, s49
	s_cselect_b32 s50, s43, s48
	s_cselect_b32 s49, s37, s53
	s_cselect_b32 s48, s45, s52
	s_add_i32 m0, s65, 0xc000
	ds_read_b128 v[220:223], v199
	ds_read_b128 v[224:227], v199 offset:1024
	ds_read_b128 v[228:231], v199 offset:2048
	ds_read_b128 v[232:235], v199 offset:3072
	ds_read_b128 v[236:239], v199 offset:4096
	ds_read_b128 v[240:243], v199 offset:5120
	ds_read_b128 v[244:247], v199 offset:6144
	ds_read_b128 v[248:251], v199 offset:7168
	global_load_lds_dwordx4 v154, s[46:47]
	s_add_i32 m0, s65, 0xe000
	s_nop 0
	global_load_lds_dwordx4 v152, s[46:47]
	s_waitcnt vmcnt(8)
	s_waitcnt lgkmcnt(0)
	s_barrier
	s_setprio 1
	s_waitcnt lgkmcnt(0)
	v_mfma_f32_16x16x32_bf16 v[124:127], v[156:159], v[220:223], v[124:127]
	v_mfma_f32_16x16x32_bf16 v[120:123], v[164:167], v[220:223], v[120:123]
	v_mfma_f32_16x16x32_bf16 v[116:119], v[156:159], v[228:231], v[116:119]
	v_mfma_f32_16x16x32_bf16 v[112:115], v[164:167], v[228:231], v[112:115]
	v_mfma_f32_16x16x32_bf16 v[92:95], v[156:159], v[236:239], v[92:95]
	v_mfma_f32_16x16x32_bf16 v[88:91], v[164:167], v[236:239], v[88:91]
	v_mfma_f32_16x16x32_bf16 v[84:87], v[156:159], v[244:247], v[84:87]
	v_mfma_f32_16x16x32_bf16 v[80:83], v[164:167], v[244:247], v[80:83]
	v_mfma_f32_16x16x32_bf16 v[124:127], v[160:163], v[224:227], v[124:127]
	v_mfma_f32_16x16x32_bf16 v[120:123], v[168:171], v[224:227], v[120:123]
	v_mfma_f32_16x16x32_bf16 v[116:119], v[160:163], v[232:235], v[116:119]
	v_mfma_f32_16x16x32_bf16 v[112:115], v[168:171], v[232:235], v[112:115]
	v_mfma_f32_16x16x32_bf16 v[92:95], v[160:163], v[240:243], v[92:95]
	v_mfma_f32_16x16x32_bf16 v[88:91], v[168:171], v[240:243], v[88:91]
	v_mfma_f32_16x16x32_bf16 v[84:87], v[160:163], v[248:251], v[84:87]
	v_mfma_f32_16x16x32_bf16 v[80:83], v[168:171], v[248:251], v[80:83]
	v_mfma_f32_16x16x32_bf16 v[108:111], v[172:175], v[220:223], v[108:111]
	v_mfma_f32_16x16x32_bf16 v[104:107], v[212:215], v[220:223], v[104:107]
	v_mfma_f32_16x16x32_bf16 v[100:103], v[172:175], v[228:231], v[100:103]
	v_mfma_f32_16x16x32_bf16 v[96:99], v[212:215], v[228:231], v[96:99]
	v_mfma_f32_16x16x32_bf16 v[76:79], v[172:175], v[236:239], v[76:79]
	v_mfma_f32_16x16x32_bf16 v[72:75], v[212:215], v[236:239], v[72:75]
	v_mfma_f32_16x16x32_bf16 v[68:71], v[172:175], v[244:247], v[68:71]
	v_mfma_f32_16x16x32_bf16 v[64:67], v[212:215], v[244:247], v[64:67]
	v_mfma_f32_16x16x32_bf16 v[108:111], v[176:179], v[224:227], v[108:111]
	v_mfma_f32_16x16x32_bf16 v[104:107], v[216:219], v[224:227], v[104:107]
	v_mfma_f32_16x16x32_bf16 v[100:103], v[176:179], v[232:235], v[100:103]
	v_mfma_f32_16x16x32_bf16 v[96:99], v[216:219], v[232:235], v[96:99]
	v_mfma_f32_16x16x32_bf16 v[76:79], v[176:179], v[240:243], v[76:79]
	v_mfma_f32_16x16x32_bf16 v[72:75], v[216:219], v[240:243], v[72:75]
	v_mfma_f32_16x16x32_bf16 v[68:71], v[176:179], v[248:251], v[68:71]
	v_mfma_f32_16x16x32_bf16 v[64:67], v[216:219], v[248:251], v[64:67]
	s_setprio 0
	s_barrier
	s_add_i32 s55, s77, s64
	s_mov_b32 m0, s55
	ds_read_b128 v[220:223], v199 offset:16384
	ds_read_b128 v[224:227], v199 offset:17408
	ds_read_b128 v[228:231], v199 offset:18432
	ds_read_b128 v[232:235], v199 offset:19456
	ds_read_b128 v[236:239], v199 offset:20480
	ds_read_b128 v[240:243], v199 offset:21504
	ds_read_b128 v[244:247], v199 offset:22528
	ds_read_b128 v[248:251], v199 offset:23552
	global_load_lds_dwordx4 v130, s[48:49]
	s_add_i32 m0, s55, 0x2000
	s_add_u32 s56, s48, 0x4000
	s_addc_u32 s57, s49, 0
	s_add_i32 s55, s78, s64
	global_load_lds_dwordx4 v134, s[48:49]
	s_mov_b32 m0, s55
	v_lshl_add_u64 v[206:207], s[50:51], 0, v[132:133]
	global_load_lds_dwordx4 v130, s[56:57]
	s_add_i32 m0, s55, 0x2000
	s_nop 0
	global_load_lds_dwordx4 v134, s[56:57]
	v_lshl_add_u64 v[204:205], s[50:51], 0, v[128:129]
	s_mov_b32 m0, s65
	s_nop 0
	global_load_lds_dwordx4 v[204:205], off
	s_mov_b32 m0, s66
	s_nop 0
	global_load_lds_dwordx4 v[206:207], off
	s_waitcnt vmcnt(8)
	s_waitcnt lgkmcnt(0)
	s_barrier
	s_setprio 1
	s_waitcnt lgkmcnt(0)
	v_mfma_f32_16x16x32_bf16 v[60:63], v[156:159], v[220:223], v[60:63]
	v_mfma_f32_16x16x32_bf16 v[56:59], v[164:167], v[220:223], v[56:59]
	v_mfma_f32_16x16x32_bf16 v[52:55], v[156:159], v[228:231], v[52:55]
	v_mfma_f32_16x16x32_bf16 v[48:51], v[164:167], v[228:231], v[48:51]
	v_mfma_f32_16x16x32_bf16 v[28:31], v[156:159], v[236:239], v[28:31]
	v_mfma_f32_16x16x32_bf16 v[24:27], v[164:167], v[236:239], v[24:27]
	v_mfma_f32_16x16x32_bf16 v[20:23], v[156:159], v[244:247], v[20:23]
	v_mfma_f32_16x16x32_bf16 v[12:15], v[164:167], v[244:247], v[12:15]
	v_mfma_f32_16x16x32_bf16 v[60:63], v[160:163], v[224:227], v[60:63]
	v_mfma_f32_16x16x32_bf16 v[56:59], v[168:171], v[224:227], v[56:59]
	v_mfma_f32_16x16x32_bf16 v[52:55], v[160:163], v[232:235], v[52:55]
	v_mfma_f32_16x16x32_bf16 v[48:51], v[168:171], v[232:235], v[48:51]
	v_mfma_f32_16x16x32_bf16 v[28:31], v[160:163], v[240:243], v[28:31]
	v_mfma_f32_16x16x32_bf16 v[24:27], v[168:171], v[240:243], v[24:27]
	v_mfma_f32_16x16x32_bf16 v[20:23], v[160:163], v[248:251], v[20:23]
	v_mfma_f32_16x16x32_bf16 v[12:15], v[168:171], v[248:251], v[12:15]
	v_mfma_f32_16x16x32_bf16 v[44:47], v[172:175], v[220:223], v[44:47]
	v_mfma_f32_16x16x32_bf16 v[40:43], v[212:215], v[220:223], v[40:43]
	v_mfma_f32_16x16x32_bf16 v[36:39], v[172:175], v[228:231], v[36:39]
	v_mfma_f32_16x16x32_bf16 v[32:35], v[212:215], v[228:231], v[32:35]
	v_mfma_f32_16x16x32_bf16 v[16:19], v[172:175], v[236:239], v[16:19]
	v_mfma_f32_16x16x32_bf16 v[8:11], v[212:215], v[236:239], v[8:11]
	v_mfma_f32_16x16x32_bf16 v[4:7], v[172:175], v[244:247], v[4:7]
	v_mfma_f32_16x16x32_bf16 v[0:3], v[212:215], v[244:247], v[0:3]
	v_mfma_f32_16x16x32_bf16 v[44:47], v[176:179], v[224:227], v[44:47]
	v_mfma_f32_16x16x32_bf16 v[40:43], v[216:219], v[224:227], v[40:43]
	v_mfma_f32_16x16x32_bf16 v[36:39], v[176:179], v[232:235], v[36:39]
	v_mfma_f32_16x16x32_bf16 v[32:35], v[216:219], v[232:235], v[32:35]
	v_mfma_f32_16x16x32_bf16 v[16:19], v[176:179], v[240:243], v[16:19]
	v_mfma_f32_16x16x32_bf16 v[8:11], v[216:219], v[240:243], v[8:11]
	v_mfma_f32_16x16x32_bf16 v[4:7], v[176:179], v[248:251], v[4:7]
	v_mfma_f32_16x16x32_bf16 v[0:3], v[216:219], v[248:251], v[0:3]
	s_setprio 0
	s_barrier
	s_add_i32 s55, 0, 0x18000
	s_add_i32 s56, 0, 0x1c000
	v_add_u32_e32 v168, s55, v182
	v_add_u32_e32 v216, s56, v182
	ds_read_b128 v[156:159], v168
	ds_read_b128 v[160:163], v168 offset:1024
	ds_read_b128 v[164:167], v168 offset:2048
	ds_read_b128 v[168:171], v168 offset:3072
	ds_read_b128 v[172:175], v216
	ds_read_b128 v[176:179], v216 offset:1024
	ds_read_b128 v[212:215], v216 offset:2048
	ds_read_b128 v[216:219], v216 offset:3072
	s_add_u32 s50, s50, 0x40000
	s_addc_u32 s51, s51, 0
	s_mov_b32 m0, s67
	ds_read_b128 v[220:223], v199 offset:32768
	ds_read_b128 v[224:227], v199 offset:33792
	ds_read_b128 v[228:231], v199 offset:34816
	ds_read_b128 v[232:235], v199 offset:35840
	ds_read_b128 v[236:239], v199 offset:36864
	ds_read_b128 v[240:243], v199 offset:37888
	ds_read_b128 v[244:247], v199 offset:38912
	ds_read_b128 v[248:251], v199 offset:39936
	global_load_lds_dwordx4 v128, s[50:51]
	s_mov_b32 m0, s68
	s_nop 0
	global_load_lds_dwordx4 v132, s[50:51]
	s_waitcnt vmcnt(8)
	s_waitcnt lgkmcnt(0)
	s_barrier
	s_setprio 1
	s_waitcnt lgkmcnt(0)
	v_mfma_f32_16x16x32_bf16 v[124:127], v[156:159], v[220:223], v[124:127]
	v_mfma_f32_16x16x32_bf16 v[120:123], v[164:167], v[220:223], v[120:123]
	v_mfma_f32_16x16x32_bf16 v[116:119], v[156:159], v[228:231], v[116:119]
	v_mfma_f32_16x16x32_bf16 v[112:115], v[164:167], v[228:231], v[112:115]
	v_mfma_f32_16x16x32_bf16 v[92:95], v[156:159], v[236:239], v[92:95]
	v_mfma_f32_16x16x32_bf16 v[88:91], v[164:167], v[236:239], v[88:91]
	v_mfma_f32_16x16x32_bf16 v[84:87], v[156:159], v[244:247], v[84:87]
	v_mfma_f32_16x16x32_bf16 v[80:83], v[164:167], v[244:247], v[80:83]
	v_mfma_f32_16x16x32_bf16 v[124:127], v[160:163], v[224:227], v[124:127]
	v_mfma_f32_16x16x32_bf16 v[120:123], v[168:171], v[224:227], v[120:123]
	v_mfma_f32_16x16x32_bf16 v[116:119], v[160:163], v[232:235], v[116:119]
	v_mfma_f32_16x16x32_bf16 v[112:115], v[168:171], v[232:235], v[112:115]
	v_mfma_f32_16x16x32_bf16 v[92:95], v[160:163], v[240:243], v[92:95]
	v_mfma_f32_16x16x32_bf16 v[88:91], v[168:171], v[240:243], v[88:91]
	v_mfma_f32_16x16x32_bf16 v[84:87], v[160:163], v[248:251], v[84:87]
	v_mfma_f32_16x16x32_bf16 v[80:83], v[168:171], v[248:251], v[80:83]
	v_mfma_f32_16x16x32_bf16 v[108:111], v[172:175], v[220:223], v[108:111]
	v_mfma_f32_16x16x32_bf16 v[104:107], v[212:215], v[220:223], v[104:107]
	v_mfma_f32_16x16x32_bf16 v[100:103], v[172:175], v[228:231], v[100:103]
	v_mfma_f32_16x16x32_bf16 v[96:99], v[212:215], v[228:231], v[96:99]
	v_mfma_f32_16x16x32_bf16 v[76:79], v[172:175], v[236:239], v[76:79]
	v_mfma_f32_16x16x32_bf16 v[72:75], v[212:215], v[236:239], v[72:75]
	v_mfma_f32_16x16x32_bf16 v[68:71], v[172:175], v[244:247], v[68:71]
	v_mfma_f32_16x16x32_bf16 v[64:67], v[212:215], v[244:247], v[64:67]
	v_mfma_f32_16x16x32_bf16 v[108:111], v[176:179], v[224:227], v[108:111]
	v_mfma_f32_16x16x32_bf16 v[104:107], v[216:219], v[224:227], v[104:107]
	v_mfma_f32_16x16x32_bf16 v[100:103], v[176:179], v[232:235], v[100:103]
	v_mfma_f32_16x16x32_bf16 v[96:99], v[216:219], v[232:235], v[96:99]
	v_mfma_f32_16x16x32_bf16 v[76:79], v[176:179], v[240:243], v[76:79]
	v_mfma_f32_16x16x32_bf16 v[72:75], v[216:219], v[240:243], v[72:75]
	v_mfma_f32_16x16x32_bf16 v[68:71], v[176:179], v[248:251], v[68:71]
	v_mfma_f32_16x16x32_bf16 v[64:67], v[216:219], v[248:251], v[64:67]
	s_setprio 0
	s_barrier
	s_add_u32 s50, s48, 0x8000
	s_addc_u32 s51, s49, 0
	s_add_i32 s55, s55, s64
	s_mov_b32 m0, s55
	ds_read_b128 v[220:223], v199 offset:49152
	ds_read_b128 v[224:227], v199 offset:50176
	ds_read_b128 v[228:231], v199 offset:51200
	ds_read_b128 v[232:235], v199 offset:52224
	ds_read_b128 v[236:239], v199 offset:53248
	ds_read_b128 v[240:243], v199 offset:54272
	ds_read_b128 v[244:247], v199 offset:55296
	ds_read_b128 v[248:251], v199 offset:56320
	global_load_lds_dwordx4 v130, s[50:51]
	s_add_i32 m0, s55, 0x2000
	s_add_u32 s48, s48, 0xc000
	v_lshl_add_u64 v[252:253], s[50:51], 0, v[134:135]
	s_addc_u32 s49, s49, 0
	s_add_i32 s50, s56, s64
	global_load_lds_dwordx4 v[252:253], off
	s_mov_b32 m0, s50
	v_lshl_add_u64 v[204:205], v[204:205], 0, s[14:15]
	global_load_lds_dwordx4 v130, s[48:49]
	s_add_i32 m0, s50, 0x2000
	s_nop 0
	global_load_lds_dwordx4 v134, s[48:49]
	s_mov_b32 m0, s74
	s_nop 0
	global_load_lds_dwordx4 v[204:205], off
	v_lshl_add_u64 v[204:205], v[206:207], 0, s[14:15]
	s_mov_b32 m0, s75
	s_nop 0
	global_load_lds_dwordx4 v[204:205], off
	s_waitcnt vmcnt(8)
	s_waitcnt lgkmcnt(0)
	s_barrier
	s_setprio 1
	s_waitcnt lgkmcnt(0)
	v_mfma_f32_16x16x32_bf16 v[60:63], v[156:159], v[220:223], v[60:63]
	v_mfma_f32_16x16x32_bf16 v[56:59], v[164:167], v[220:223], v[56:59]
	v_mfma_f32_16x16x32_bf16 v[52:55], v[156:159], v[228:231], v[52:55]
	v_mfma_f32_16x16x32_bf16 v[48:51], v[164:167], v[228:231], v[48:51]
	v_mfma_f32_16x16x32_bf16 v[28:31], v[156:159], v[236:239], v[28:31]
	v_mfma_f32_16x16x32_bf16 v[24:27], v[164:167], v[236:239], v[24:27]
	v_mfma_f32_16x16x32_bf16 v[20:23], v[156:159], v[244:247], v[20:23]
	v_mfma_f32_16x16x32_bf16 v[12:15], v[164:167], v[244:247], v[12:15]
	v_mfma_f32_16x16x32_bf16 v[60:63], v[160:163], v[224:227], v[60:63]
	v_mfma_f32_16x16x32_bf16 v[56:59], v[168:171], v[224:227], v[56:59]
	v_mfma_f32_16x16x32_bf16 v[52:55], v[160:163], v[232:235], v[52:55]
	v_mfma_f32_16x16x32_bf16 v[48:51], v[168:171], v[232:235], v[48:51]
	v_mfma_f32_16x16x32_bf16 v[28:31], v[160:163], v[240:243], v[28:31]
	v_mfma_f32_16x16x32_bf16 v[24:27], v[168:171], v[240:243], v[24:27]
	v_mfma_f32_16x16x32_bf16 v[20:23], v[160:163], v[248:251], v[20:23]
	v_mfma_f32_16x16x32_bf16 v[12:15], v[168:171], v[248:251], v[12:15]
	v_mfma_f32_16x16x32_bf16 v[44:47], v[172:175], v[220:223], v[44:47]
	v_mfma_f32_16x16x32_bf16 v[40:43], v[212:215], v[220:223], v[40:43]
	v_mfma_f32_16x16x32_bf16 v[36:39], v[172:175], v[228:231], v[36:39]
	v_mfma_f32_16x16x32_bf16 v[32:35], v[212:215], v[228:231], v[32:35]
	v_mfma_f32_16x16x32_bf16 v[16:19], v[172:175], v[236:239], v[16:19]
	v_mfma_f32_16x16x32_bf16 v[8:11], v[212:215], v[236:239], v[8:11]
	v_mfma_f32_16x16x32_bf16 v[4:7], v[172:175], v[244:247], v[4:7]
	v_mfma_f32_16x16x32_bf16 v[0:3], v[212:215], v[244:247], v[0:3]
	v_mfma_f32_16x16x32_bf16 v[44:47], v[176:179], v[224:227], v[44:47]
	v_mfma_f32_16x16x32_bf16 v[40:43], v[216:219], v[224:227], v[40:43]
	v_mfma_f32_16x16x32_bf16 v[36:39], v[176:179], v[232:235], v[36:39]
	v_mfma_f32_16x16x32_bf16 v[32:35], v[216:219], v[232:235], v[32:35]
	v_mfma_f32_16x16x32_bf16 v[16:19], v[176:179], v[240:243], v[16:19]
	v_mfma_f32_16x16x32_bf16 v[8:11], v[216:219], v[240:243], v[8:11]
	v_mfma_f32_16x16x32_bf16 v[4:7], v[176:179], v[248:251], v[4:7]
	v_mfma_f32_16x16x32_bf16 v[0:3], v[216:219], v[248:251], v[0:3]
	s_setprio 0
	s_barrier
	s_add_i32 s54, s54, 2
	s_add_u32 s52, s52, 0x10000
	s_addc_u32 s53, s53, 0
	s_add_u32 s46, s46, 0x100
	s_addc_u32 s47, s47, 0
	s_cmp_gt_u32 s54, 13
	s_cbranch_scc0 .LBB0_2358
	s_and_b64 vcc, exec, s[16:17]
	s_cbranch_vccz .LBB0_2361
	s_barrier

.LBB0_2519:
	ds_read_b128 v[144:147], v178
	ds_read_b128 v[148:151], v178 offset:1024
	ds_read_b128 v[152:155], v178 offset:2048
	ds_read_b128 v[156:159], v178 offset:3072
	ds_read_b128 v[160:163], v179
	ds_read_b128 v[164:167], v179 offset:1024
	ds_read_b128 v[182:185], v179 offset:2048
	ds_read_b128 v[186:189], v179 offset:3072
	s_add_u32 s34, s30, 0x4000
	s_addc_u32 s35, s31, 0
	s_cmp_eq_u32 s64, 40
	s_cselect_b32 s38, s4, s34
	s_cselect_b32 s39, s5, s35
	s_cselect_b32 s36, s28, s62
	s_cselect_b32 s37, s29, s63
	s_add_u32 s34, s38, 0x8000
	s_addc_u32 s35, s39, 0
	s_add_i32 m0, s42, 0xc000
	ds_read_b128 v[190:193], v180
	ds_read_b128 v[194:197], v180 offset:1024
	ds_read_b128 v[198:201], v180 offset:2048
	ds_read_b128 v[202:205], v180 offset:3072
	ds_read_b128 v[206:209], v180 offset:4096
	ds_read_b128 v[210:213], v180 offset:5120
	ds_read_b128 v[214:217], v180 offset:6144
	ds_read_b128 v[218:221], v180 offset:7168
	global_load_lds_dwordx4 v138, s[30:31]
	s_add_i32 m0, s42, 0xe000
	s_nop 0
	global_load_lds_dwordx4 v136, s[30:31]
	s_waitcnt vmcnt(8)
	s_waitcnt lgkmcnt(0)
	s_barrier
	s_setprio 1
	s_waitcnt lgkmcnt(0)
	v_mfma_f32_16x16x32_bf16 v[124:127], v[144:147], v[190:193], v[124:127]
	v_mfma_f32_16x16x32_bf16 v[120:123], v[152:155], v[190:193], v[120:123]
	v_mfma_f32_16x16x32_bf16 v[116:119], v[144:147], v[198:201], v[116:119]
	v_mfma_f32_16x16x32_bf16 v[112:115], v[152:155], v[198:201], v[112:115]
	v_mfma_f32_16x16x32_bf16 v[92:95], v[144:147], v[206:209], v[92:95]
	v_mfma_f32_16x16x32_bf16 v[88:91], v[152:155], v[206:209], v[88:91]
	v_mfma_f32_16x16x32_bf16 v[84:87], v[144:147], v[214:217], v[84:87]
	v_mfma_f32_16x16x32_bf16 v[80:83], v[152:155], v[214:217], v[80:83]
	v_mfma_f32_16x16x32_bf16 v[124:127], v[148:151], v[194:197], v[124:127]
	v_mfma_f32_16x16x32_bf16 v[120:123], v[156:159], v[194:197], v[120:123]
	v_mfma_f32_16x16x32_bf16 v[116:119], v[148:151], v[202:205], v[116:119]
	v_mfma_f32_16x16x32_bf16 v[112:115], v[156:159], v[202:205], v[112:115]
	v_mfma_f32_16x16x32_bf16 v[92:95], v[148:151], v[210:213], v[92:95]
	v_mfma_f32_16x16x32_bf16 v[88:91], v[156:159], v[210:213], v[88:91]
	v_mfma_f32_16x16x32_bf16 v[84:87], v[148:151], v[218:221], v[84:87]
	v_mfma_f32_16x16x32_bf16 v[80:83], v[156:159], v[218:221], v[80:83]
	v_mfma_f32_16x16x32_bf16 v[108:111], v[160:163], v[190:193], v[108:111]
	v_mfma_f32_16x16x32_bf16 v[104:107], v[182:185], v[190:193], v[104:107]
	v_mfma_f32_16x16x32_bf16 v[100:103], v[160:163], v[198:201], v[100:103]
	v_mfma_f32_16x16x32_bf16 v[96:99], v[182:185], v[198:201], v[96:99]
	v_mfma_f32_16x16x32_bf16 v[76:79], v[160:163], v[206:209], v[76:79]
	v_mfma_f32_16x16x32_bf16 v[72:75], v[182:185], v[206:209], v[72:75]
	v_mfma_f32_16x16x32_bf16 v[68:71], v[160:163], v[214:217], v[68:71]
	v_mfma_f32_16x16x32_bf16 v[64:67], v[182:185], v[214:217], v[64:67]
	v_mfma_f32_16x16x32_bf16 v[108:111], v[164:167], v[194:197], v[108:111]
	v_mfma_f32_16x16x32_bf16 v[104:107], v[186:189], v[194:197], v[104:107]
	v_mfma_f32_16x16x32_bf16 v[100:103], v[164:167], v[202:205], v[100:103]
	v_mfma_f32_16x16x32_bf16 v[96:99], v[186:189], v[202:205], v[96:99]
	v_mfma_f32_16x16x32_bf16 v[76:79], v[164:167], v[210:213], v[76:79]
	v_mfma_f32_16x16x32_bf16 v[72:75], v[186:189], v[210:213], v[72:75]
	v_mfma_f32_16x16x32_bf16 v[68:71], v[164:167], v[218:221], v[68:71]
	v_mfma_f32_16x16x32_bf16 v[64:67], v[186:189], v[218:221], v[64:67]
	s_setprio 0
	s_barrier
	s_add_i32 s65, s55, s41
	s_mov_b32 m0, s65
	ds_read_b128 v[190:193], v180 offset:16384
	ds_read_b128 v[194:197], v180 offset:17408
	ds_read_b128 v[198:201], v180 offset:18432
	ds_read_b128 v[202:205], v180 offset:19456
	ds_read_b128 v[206:209], v180 offset:20480
	ds_read_b128 v[210:213], v180 offset:21504
	ds_read_b128 v[214:217], v180 offset:22528
	ds_read_b128 v[218:221], v180 offset:23552
	global_load_lds_dwordx4 v128, s[36:37]
	s_add_i32 m0, s65, 0x2000
	s_add_u32 s66, s36, 0x4000
	s_addc_u32 s67, s37, 0
	s_add_i32 s65, s56, s41
	global_load_lds_dwordx4 v130, s[36:37]
	s_mov_b32 m0, s65
	s_nop 0
	global_load_lds_dwordx4 v128, s[66:67]
	s_add_i32 m0, s65, 0x2000
	s_nop 0
	global_load_lds_dwordx4 v130, s[66:67]
	s_mov_b32 m0, s42
	s_nop 0
	global_load_lds_dwordx4 v128, s[38:39]
	s_mov_b32 m0, s43
	s_nop 0
	global_load_lds_dwordx4 v130, s[38:39]
	s_waitcnt vmcnt(8)
	s_waitcnt lgkmcnt(0)
	s_barrier
	s_setprio 1
	s_waitcnt lgkmcnt(0)
	v_mfma_f32_16x16x32_bf16 v[60:63], v[144:147], v[190:193], v[60:63]
	v_mfma_f32_16x16x32_bf16 v[56:59], v[152:155], v[190:193], v[56:59]
	v_mfma_f32_16x16x32_bf16 v[52:55], v[144:147], v[198:201], v[52:55]
	v_mfma_f32_16x16x32_bf16 v[48:51], v[152:155], v[198:201], v[48:51]
	v_mfma_f32_16x16x32_bf16 v[28:31], v[144:147], v[206:209], v[28:31]
	v_mfma_f32_16x16x32_bf16 v[24:27], v[152:155], v[206:209], v[24:27]
	v_mfma_f32_16x16x32_bf16 v[20:23], v[144:147], v[214:217], v[20:23]
	v_mfma_f32_16x16x32_bf16 v[12:15], v[152:155], v[214:217], v[12:15]
	v_mfma_f32_16x16x32_bf16 v[60:63], v[148:151], v[194:197], v[60:63]
	v_mfma_f32_16x16x32_bf16 v[56:59], v[156:159], v[194:197], v[56:59]
	v_mfma_f32_16x16x32_bf16 v[52:55], v[148:151], v[202:205], v[52:55]
	v_mfma_f32_16x16x32_bf16 v[48:51], v[156:159], v[202:205], v[48:51]
	v_mfma_f32_16x16x32_bf16 v[28:31], v[148:151], v[210:213], v[28:31]
	v_mfma_f32_16x16x32_bf16 v[24:27], v[156:159], v[210:213], v[24:27]
	v_mfma_f32_16x16x32_bf16 v[20:23], v[148:151], v[218:221], v[20:23]
	v_mfma_f32_16x16x32_bf16 v[12:15], v[156:159], v[218:221], v[12:15]
	v_mfma_f32_16x16x32_bf16 v[44:47], v[160:163], v[190:193], v[44:47]
	v_mfma_f32_16x16x32_bf16 v[40:43], v[182:185], v[190:193], v[40:43]
	v_mfma_f32_16x16x32_bf16 v[36:39], v[160:163], v[198:201], v[36:39]
	v_mfma_f32_16x16x32_bf16 v[32:35], v[182:185], v[198:201], v[32:35]
	v_mfma_f32_16x16x32_bf16 v[16:19], v[160:163], v[206:209], v[16:19]
	v_mfma_f32_16x16x32_bf16 v[8:11], v[182:185], v[206:209], v[8:11]
	v_mfma_f32_16x16x32_bf16 v[4:7], v[160:163], v[214:217], v[4:7]
	v_mfma_f32_16x16x32_bf16 v[0:3], v[182:185], v[214:217], v[0:3]
	v_mfma_f32_16x16x32_bf16 v[44:47], v[164:167], v[194:197], v[44:47]
	v_mfma_f32_16x16x32_bf16 v[40:43], v[186:189], v[194:197], v[40:43]
	v_mfma_f32_16x16x32_bf16 v[36:39], v[164:167], v[202:205], v[36:39]
	v_mfma_f32_16x16x32_bf16 v[32:35], v[186:189], v[202:205], v[32:35]
	v_mfma_f32_16x16x32_bf16 v[16:19], v[164:167], v[210:213], v[16:19]
	v_mfma_f32_16x16x32_bf16 v[8:11], v[186:189], v[210:213], v[8:11]
	v_mfma_f32_16x16x32_bf16 v[4:7], v[164:167], v[218:221], v[4:7]
	v_mfma_f32_16x16x32_bf16 v[0:3], v[186:189], v[218:221], v[0:3]
	s_setprio 0
	s_barrier
	s_add_i32 s65, 0, 0x18000
	s_add_i32 s66, 0, 0x1c000
	v_add_u32_e32 v156, s65, v170
	v_add_u32_e32 v186, s66, v170
	ds_read_b128 v[144:147], v156
	ds_read_b128 v[148:151], v156 offset:1024
	ds_read_b128 v[152:155], v156 offset:2048
	ds_read_b128 v[156:159], v156 offset:3072
	ds_read_b128 v[160:163], v186
	ds_read_b128 v[164:167], v186 offset:1024
	ds_read_b128 v[182:185], v186 offset:2048
	ds_read_b128 v[186:189], v186 offset:3072
	s_add_u32 s38, s38, 0x4000
	s_addc_u32 s39, s39, 0
	s_mov_b32 m0, s44
	ds_read_b128 v[190:193], v180 offset:32768
	ds_read_b128 v[194:197], v180 offset:33792
	ds_read_b128 v[198:201], v180 offset:34816
	ds_read_b128 v[202:205], v180 offset:35840
	ds_read_b128 v[206:209], v180 offset:36864
	ds_read_b128 v[210:213], v180 offset:37888
	ds_read_b128 v[214:217], v180 offset:38912
	ds_read_b128 v[218:221], v180 offset:39936
	global_load_lds_dwordx4 v128, s[38:39]
	s_mov_b32 m0, s45
	s_nop 0
	global_load_lds_dwordx4 v130, s[38:39]
	s_waitcnt vmcnt(8)
	s_waitcnt lgkmcnt(0)
	s_barrier
	s_setprio 1
	s_waitcnt lgkmcnt(0)
	v_mfma_f32_16x16x32_bf16 v[124:127], v[144:147], v[190:193], v[124:127]
	v_mfma_f32_16x16x32_bf16 v[120:123], v[152:155], v[190:193], v[120:123]
	v_mfma_f32_16x16x32_bf16 v[116:119], v[144:147], v[198:201], v[116:119]
	v_mfma_f32_16x16x32_bf16 v[112:115], v[152:155], v[198:201], v[112:115]
	v_mfma_f32_16x16x32_bf16 v[92:95], v[144:147], v[206:209], v[92:95]
	v_mfma_f32_16x16x32_bf16 v[88:91], v[152:155], v[206:209], v[88:91]
	v_mfma_f32_16x16x32_bf16 v[84:87], v[144:147], v[214:217], v[84:87]
	v_mfma_f32_16x16x32_bf16 v[80:83], v[152:155], v[214:217], v[80:83]
	v_mfma_f32_16x16x32_bf16 v[124:127], v[148:151], v[194:197], v[124:127]
	v_mfma_f32_16x16x32_bf16 v[120:123], v[156:159], v[194:197], v[120:123]
	v_mfma_f32_16x16x32_bf16 v[116:119], v[148:151], v[202:205], v[116:119]
	v_mfma_f32_16x16x32_bf16 v[112:115], v[156:159], v[202:205], v[112:115]
	v_mfma_f32_16x16x32_bf16 v[92:95], v[148:151], v[210:213], v[92:95]
	v_mfma_f32_16x16x32_bf16 v[88:91], v[156:159], v[210:213], v[88:91]
	v_mfma_f32_16x16x32_bf16 v[84:87], v[148:151], v[218:221], v[84:87]
	v_mfma_f32_16x16x32_bf16 v[80:83], v[156:159], v[218:221], v[80:83]
	v_mfma_f32_16x16x32_bf16 v[108:111], v[160:163], v[190:193], v[108:111]
	v_mfma_f32_16x16x32_bf16 v[104:107], v[182:185], v[190:193], v[104:107]
	v_mfma_f32_16x16x32_bf16 v[100:103], v[160:163], v[198:201], v[100:103]
	v_mfma_f32_16x16x32_bf16 v[96:99], v[182:185], v[198:201], v[96:99]
	v_mfma_f32_16x16x32_bf16 v[76:79], v[160:163], v[206:209], v[76:79]
	v_mfma_f32_16x16x32_bf16 v[72:75], v[182:185], v[206:209], v[72:75]
	v_mfma_f32_16x16x32_bf16 v[68:71], v[160:163], v[214:217], v[68:71]
	v_mfma_f32_16x16x32_bf16 v[64:67], v[182:185], v[214:217], v[64:67]
	v_mfma_f32_16x16x32_bf16 v[108:111], v[164:167], v[194:197], v[108:111]
	v_mfma_f32_16x16x32_bf16 v[104:107], v[186:189], v[194:197], v[104:107]
	v_mfma_f32_16x16x32_bf16 v[100:103], v[164:167], v[202:205], v[100:103]
	v_mfma_f32_16x16x32_bf16 v[96:99], v[186:189], v[202:205], v[96:99]
	v_mfma_f32_16x16x32_bf16 v[76:79], v[164:167], v[210:213], v[76:79]
	v_mfma_f32_16x16x32_bf16 v[72:75], v[186:189], v[210:213], v[72:75]
	v_mfma_f32_16x16x32_bf16 v[68:71], v[164:167], v[218:221], v[68:71]
	v_mfma_f32_16x16x32_bf16 v[64:67], v[186:189], v[218:221], v[64:67]
	s_setprio 0
	s_barrier
	s_add_u32 s38, s36, 0x8000
	s_addc_u32 s39, s37, 0
	s_add_i32 s65, s65, s41
	s_mov_b32 m0, s65
	ds_read_b128 v[190:193], v180 offset:49152
	ds_read_b128 v[194:197], v180 offset:50176
	ds_read_b128 v[198:201], v180 offset:51200
	ds_read_b128 v[202:205], v180 offset:52224
	ds_read_b128 v[206:209], v180 offset:53248
	ds_read_b128 v[210:213], v180 offset:54272
	ds_read_b128 v[214:217], v180 offset:55296
	ds_read_b128 v[218:221], v180 offset:56320
	global_load_lds_dwordx4 v128, s[38:39]
	s_add_i32 m0, s65, 0x2000
	s_add_u32 s36, s36, 0xc000
	v_lshl_add_u64 v[222:223], s[38:39], 0, v[130:131]
	s_addc_u32 s37, s37, 0
	s_add_i32 s38, s66, s41
	global_load_lds_dwordx4 v[222:223], off
	s_mov_b32 m0, s38
	s_nop 0
	global_load_lds_dwordx4 v128, s[36:37]
	s_add_i32 m0, s38, 0x2000
	s_nop 0
	global_load_lds_dwordx4 v130, s[36:37]
	s_mov_b32 m0, s51
	s_nop 0
	global_load_lds_dwordx4 v128, s[34:35]
	s_mov_b32 m0, s52
	s_nop 0
	global_load_lds_dwordx4 v130, s[34:35]
	s_waitcnt vmcnt(8)
	s_waitcnt lgkmcnt(0)
	s_barrier
	s_setprio 1
	s_waitcnt lgkmcnt(0)
	v_mfma_f32_16x16x32_bf16 v[60:63], v[144:147], v[190:193], v[60:63]
	v_mfma_f32_16x16x32_bf16 v[56:59], v[152:155], v[190:193], v[56:59]
	v_mfma_f32_16x16x32_bf16 v[52:55], v[144:147], v[198:201], v[52:55]
	v_mfma_f32_16x16x32_bf16 v[48:51], v[152:155], v[198:201], v[48:51]
	v_mfma_f32_16x16x32_bf16 v[28:31], v[144:147], v[206:209], v[28:31]
	v_mfma_f32_16x16x32_bf16 v[24:27], v[152:155], v[206:209], v[24:27]
	v_mfma_f32_16x16x32_bf16 v[20:23], v[144:147], v[214:217], v[20:23]
	v_mfma_f32_16x16x32_bf16 v[12:15], v[152:155], v[214:217], v[12:15]
	v_mfma_f32_16x16x32_bf16 v[60:63], v[148:151], v[194:197], v[60:63]
	v_mfma_f32_16x16x32_bf16 v[56:59], v[156:159], v[194:197], v[56:59]
	v_mfma_f32_16x16x32_bf16 v[52:55], v[148:151], v[202:205], v[52:55]
	v_mfma_f32_16x16x32_bf16 v[48:51], v[156:159], v[202:205], v[48:51]
	v_mfma_f32_16x16x32_bf16 v[28:31], v[148:151], v[210:213], v[28:31]
	v_mfma_f32_16x16x32_bf16 v[24:27], v[156:159], v[210:213], v[24:27]
	v_mfma_f32_16x16x32_bf16 v[20:23], v[148:151], v[218:221], v[20:23]
	v_mfma_f32_16x16x32_bf16 v[12:15], v[156:159], v[218:221], v[12:15]
	v_mfma_f32_16x16x32_bf16 v[44:47], v[160:163], v[190:193], v[44:47]
	v_mfma_f32_16x16x32_bf16 v[40:43], v[182:185], v[190:193], v[40:43]
	v_mfma_f32_16x16x32_bf16 v[36:39], v[160:163], v[198:201], v[36:39]
	v_mfma_f32_16x16x32_bf16 v[32:35], v[182:185], v[198:201], v[32:35]
	v_mfma_f32_16x16x32_bf16 v[16:19], v[160:163], v[206:209], v[16:19]
	v_mfma_f32_16x16x32_bf16 v[8:11], v[182:185], v[206:209], v[8:11]
	v_mfma_f32_16x16x32_bf16 v[4:7], v[160:163], v[214:217], v[4:7]
	v_mfma_f32_16x16x32_bf16 v[0:3], v[182:185], v[214:217], v[0:3]
	v_mfma_f32_16x16x32_bf16 v[44:47], v[164:167], v[194:197], v[44:47]
	v_mfma_f32_16x16x32_bf16 v[40:43], v[186:189], v[194:197], v[40:43]
	v_mfma_f32_16x16x32_bf16 v[36:39], v[164:167], v[202:205], v[36:39]
	v_mfma_f32_16x16x32_bf16 v[32:35], v[186:189], v[202:205], v[32:35]
	v_mfma_f32_16x16x32_bf16 v[16:19], v[164:167], v[210:213], v[16:19]
	v_mfma_f32_16x16x32_bf16 v[8:11], v[186:189], v[210:213], v[8:11]
	v_mfma_f32_16x16x32_bf16 v[4:7], v[164:167], v[218:221], v[4:7]
	v_mfma_f32_16x16x32_bf16 v[0:3], v[186:189], v[218:221], v[0:3]
	s_setprio 0
	s_barrier
	s_add_i32 s64, s64, 2
	s_add_u32 s62, s62, 0x10000
	s_addc_u32 s63, s63, 0
	s_add_u32 s30, s30, 0x10000
	s_addc_u32 s31, s31, 0
	s_cmp_gt_u32 s64, 41
	s_cbranch_scc0 .LBB0_2519
	s_and_b64 vcc, exec, s[14:15]
	s_cbranch_vccz .LBB0_2522
	s_barrier
